# early GEMM barrier moved 2 MFMAs before block end (variant of 4); all other changes as previous
# speedup vs baseline: 1.0068x; 1.0068x over previous
; #define PG8_STAGE(bufoff, gbase, voff) do { _Pragma("unroll") for (int _i = 0; _i < 2; ++_i) \
;         __builtin_amdgcn_global_load_lds((const unsigned*)((const char*)(gbase) + (voff)[_i]), (PG8_LAS unsigned*)(lds + (bufoff) + ldsw + _i * 8192), 16, 0, 0); } while (0)
; #define PG8_LDA(dst, b, h) do { _Pragma("unroll") for (int m = 0; m < 4; ++m) _Pragma("unroll") for (int k = 0; k < 2; ++k) dst[m][k] = *(const PG8_LAS bf16x8*)(lds + PG8_SA(b, h) + aoff + m * 2048 + k * 1024); } while (0)
; #define PG8_LDB(dst, b, h) do { _Pragma("unroll") for (int n = 0; n < 2; ++n) _Pragma("unroll") for (int k = 0; k < 2; ++k) dst[n][k] = *(const PG8_LAS bf16x8*)(lds + PG8_SB(b, h) + boff + n * 2048 + k * 1024); } while (0)
; #define PG8_BAR __builtin_amdgcn_s_barrier()
; template <class Epi, class Sched, bool ALIGN_EPI = false, bool SP2 = false>
; __device__ __forceinline__ void gemm_phase(PG8_LAS unsigned char* lds, const Gemm g, const Sched& S, const Epi& E) {
;     ...
;             const bool last = (t == nt - 2);
;             const char* a1 = cA + (size_t)(t + 1) * kstep;
;             const char* a2 = last ? nA : cA + (size_t)(t + 2) * kstep; const char* b2 = last ? nB : cB + (size_t)(t + 2) * kstep;
;             const char* a3 = a2 + kstep; const char* b3 = b2 + kstep;
;             if (last && has_next) S.a_ready(nxt);
;             if constexpr (SP2) {
;             PG8_LDB(B0, 0, 0); PG8_LDB(B1, 0, 1); PG8_SCHED; PG8_LDA(At, 0, 0); PG8_STAGE(PG8_SA(1, 1), a1 + hstep, voffA);
;             PG8_WAIT_V(8); PG8_WAIT_L(0); PG8_BAR; PG8_MMA(0, 0, At, B0); PG8_MMA(0, 1, At, B1); PG8_BAR; PG8_SCHED;
;             PG8_LDA(At, 0, 1); PG8_STAGE(PG8_SB(0, 0), b2, voffB); PG8_STAGE(PG8_SB(0, 1), b2 + hstep, voffB); PG8_STAGE(PG8_SA(0, 0), a2, voffA);
;             PG8_WAIT_V(8); PG8_WAIT_L(0); PG8_BAR; PG8_MMA(1, 0, At, B0); PG8_MMA(1, 1, At, B1); PG8_BAR; PG8_SCHED;
;             PG8_LDB(B0, 1, 0); PG8_LDB(B1, 1, 1); PG8_SCHED; PG8_LDA(At, 1, 0); PG8_STAGE(PG8_SA(0, 1), a2 + hstep, voffA);
;             PG8_WAIT_V(8); PG8_WAIT_L(0); PG8_BAR; PG8_MMA(0, 0, At, B0); PG8_MMA(0, 1, At, B1); PG8_BAR; PG8_SCHED;
;             PG8_LDA(At, 1, 1); PG8_STAGE(PG8_SB(1, 0), b3, voffB); PG8_STAGE(PG8_SB(1, 1), b3 + hstep, voffB); PG8_STAGE(PG8_SA(1, 0), a3, voffA);
;             PG8_WAIT_V(8); PG8_WAIT_L(0); PG8_BAR; PG8_MMA(1, 0, At, B0); PG8_MMA(1, 1, At, B1); PG8_BAR; PG8_SCHED;
.LBB0_48:
	ds_read_b128 v[146:149], v153
	ds_read_b128 v[156:159], v153 offset:1024
	ds_read_b128 v[160:163], v153 offset:2048
	ds_read_b128 v[164:167], v153 offset:3072
	ds_read_b128 v[168:171], v154
	ds_read_b128 v[172:175], v154 offset:1024
	ds_read_b128 v[176:179], v154 offset:2048
	ds_read_b128 v[180:183], v154 offset:3072
	s_add_u32 s22, s20, 0xfff80080
	s_addc_u32 s23, s21, -1
	s_cmp_eq_u32 s53, 28
	s_cselect_b32 s25, s13, s23
	s_cselect_b32 s24, s45, s22
	s_cselect_b32 s23, s11, s52
	s_cselect_b32 s22, s50, s51
	v_lshl_add_u64 v[216:217], s[20:21], 0, v[138:139]
	s_add_i32 m0, s19, 0xc000
	ds_read_b128 v[184:187], v155
	ds_read_b128 v[188:191], v155 offset:1024
	ds_read_b128 v[192:195], v155 offset:2048
	ds_read_b128 v[196:199], v155 offset:3072
	ds_read_b128 v[200:203], v155 offset:4096
	ds_read_b128 v[204:207], v155 offset:5120
	ds_read_b128 v[208:211], v155 offset:6144
	ds_read_b128 v[212:215], v155 offset:7168
	global_load_lds_dwordx4 v[216:217], off
	v_lshl_add_u64 v[216:217], s[20:21], 0, v[140:141]
	s_add_i32 m0, s19, 0xe000
	s_nop 0
	global_load_lds_dwordx4 v[216:217], off
	s_waitcnt vmcnt(8)
	s_waitcnt lgkmcnt(0)
	s_barrier
	s_setprio 1
	s_waitcnt lgkmcnt(0)
	v_mfma_f32_16x16x32_bf16 v[124:127], v[146:149], v[184:187], v[124:127]
	v_mfma_f32_16x16x32_bf16 v[116:119], v[160:163], v[184:187], v[116:119]
	v_mfma_f32_16x16x32_bf16 v[108:111], v[146:149], v[192:195], v[108:111]
	v_mfma_f32_16x16x32_bf16 v[100:103], v[160:163], v[192:195], v[100:103]
	v_mfma_f32_16x16x32_bf16 v[92:95], v[146:149], v[200:203], v[92:95]
	v_mfma_f32_16x16x32_bf16 v[84:87], v[160:163], v[200:203], v[84:87]
	v_mfma_f32_16x16x32_bf16 v[76:79], v[146:149], v[208:211], v[76:79]
	v_mfma_f32_16x16x32_bf16 v[68:71], v[160:163], v[208:211], v[68:71]
	v_mfma_f32_16x16x32_bf16 v[124:127], v[156:159], v[188:191], v[124:127]
	v_mfma_f32_16x16x32_bf16 v[116:119], v[164:167], v[188:191], v[116:119]
	v_mfma_f32_16x16x32_bf16 v[108:111], v[156:159], v[196:199], v[108:111]
	v_mfma_f32_16x16x32_bf16 v[100:103], v[164:167], v[196:199], v[100:103]
	v_mfma_f32_16x16x32_bf16 v[92:95], v[156:159], v[204:207], v[92:95]
	v_mfma_f32_16x16x32_bf16 v[84:87], v[164:167], v[204:207], v[84:87]
	v_mfma_f32_16x16x32_bf16 v[76:79], v[156:159], v[212:215], v[76:79]
	v_mfma_f32_16x16x32_bf16 v[68:71], v[164:167], v[212:215], v[68:71]
	s_setprio 0
	s_setprio 1
	v_mfma_f32_16x16x32_bf16 v[120:123], v[168:171], v[184:187], v[120:123]
	v_mfma_f32_16x16x32_bf16 v[112:115], v[176:179], v[184:187], v[112:115]
	v_mfma_f32_16x16x32_bf16 v[104:107], v[168:171], v[192:195], v[104:107]
	v_mfma_f32_16x16x32_bf16 v[96:99], v[176:179], v[192:195], v[96:99]
	v_mfma_f32_16x16x32_bf16 v[88:91], v[168:171], v[200:203], v[88:91]
	v_mfma_f32_16x16x32_bf16 v[80:83], v[176:179], v[200:203], v[80:83]
	v_mfma_f32_16x16x32_bf16 v[72:75], v[168:171], v[208:211], v[72:75]
	v_mfma_f32_16x16x32_bf16 v[64:67], v[176:179], v[208:211], v[64:67]
	v_mfma_f32_16x16x32_bf16 v[120:123], v[172:175], v[188:191], v[120:123]
	v_mfma_f32_16x16x32_bf16 v[112:115], v[180:183], v[188:191], v[112:115]
	v_mfma_f32_16x16x32_bf16 v[104:107], v[172:175], v[196:199], v[104:107]
	v_mfma_f32_16x16x32_bf16 v[96:99], v[180:183], v[196:199], v[96:99]
	v_mfma_f32_16x16x32_bf16 v[88:91], v[172:175], v[204:207], v[88:91]
	v_mfma_f32_16x16x32_bf16 v[80:83], v[180:183], v[204:207], v[80:83]
	s_setprio 2
	s_barrier
	v_mfma_f32_16x16x32_bf16 v[72:75], v[172:175], v[212:215], v[72:75]
	v_mfma_f32_16x16x32_bf16 v[64:67], v[180:183], v[212:215], v[64:67]
	s_setprio 0
	s_add_i32 s54, s41, s28
	v_lshl_add_u64 v[216:217], s[22:23], 0, v[134:135]
	s_mov_b32 m0, s54
	ds_read_b128 v[184:187], v155 offset:16384
	ds_read_b128 v[188:191], v155 offset:17408
	ds_read_b128 v[192:195], v155 offset:18432
	ds_read_b128 v[196:199], v155 offset:19456
	ds_read_b128 v[200:203], v155 offset:20480
	ds_read_b128 v[204:207], v155 offset:21504
	ds_read_b128 v[208:211], v155 offset:22528
	ds_read_b128 v[212:215], v155 offset:23552
	global_load_lds_dwordx4 v[216:217], off
	s_add_i32 m0, s54, 0x2000
	s_add_u32 s54, s22, 0x80000
	v_lshl_add_u64 v[218:219], s[22:23], 0, v[130:131]
	s_addc_u32 s55, s23, 0
	s_add_i32 s56, s42, s28
	global_load_lds_dwordx4 v[218:219], off
	v_lshl_add_u64 v[220:221], s[54:55], 0, v[134:135]
	s_mov_b32 m0, s56
	v_lshl_add_u64 v[222:223], s[24:25], 0, v[132:133]
	global_load_lds_dwordx4 v[220:221], off
	v_lshl_add_u64 v[220:221], s[54:55], 0, v[130:131]
	s_add_i32 m0, s56, 0x2000
	s_nop 0
	global_load_lds_dwordx4 v[220:221], off
	v_lshl_add_u64 v[220:221], s[24:25], 0, v[136:137]
	s_mov_b32 m0, s19
	s_nop 0
	global_load_lds_dwordx4 v[220:221], off
	s_mov_b32 m0, s31
	s_nop 0
	global_load_lds_dwordx4 v[222:223], off
	s_waitcnt vmcnt(8)
	s_waitcnt lgkmcnt(0)
	s_barrier
; #define PG8_STAGE(bufoff, gbase, voff) do { _Pragma("unroll") for (int _i = 0; _i < 2; ++_i) \
;         __builtin_amdgcn_global_load_lds((const unsigned*)((const char*)(gbase) + (voff)[_i]), (PG8_LAS unsigned*)(lds + (bufoff) + ldsw + _i * 8192), 16, 0, 0); } while (0)
; #define PG8_LDA(dst, b, h) do { _Pragma("unroll") for (int m = 0; m < 4; ++m) _Pragma("unroll") for (int k = 0; k < 2; ++k) dst[m][k] = *(const PG8_LAS bf16x8*)(lds + PG8_SA(b, h) + aoff + m * 2048 + k * 1024); } while (0)
; #define PG8_LDB(dst, b, h) do { _Pragma("unroll") for (int n = 0; n < 2; ++n) _Pragma("unroll") for (int k = 0; k < 2; ++k) dst[n][k] = *(const PG8_LAS bf16x8*)(lds + PG8_SB(b, h) + boff + n * 2048 + k * 1024); } while (0)
; #define PG8_MMA(ai, bj, At, Bt) do { __builtin_amdgcn_s_setprio(1); _Pragma("unroll") for (int m = 0; m < 4; ++m) _Pragma("unroll") for (int n = 0; n < 2; ++n) _Pragma("unroll") for (int k = 0; k < 2; ++k) \
;         acc[ai][bj][m][n] = __builtin_amdgcn_mfma_f32_16x16x32_bf16(Bt[n][k], At[m][k], acc[ai][bj][m][n], 0, 0, 0); __builtin_amdgcn_s_setprio(0); } while (0)
; #define PG8_WAIT_V(n) asm volatile("s_waitcnt vmcnt(" #n ")" ::: "memory")
; #define PG8_WAIT_L(n) asm volatile("s_waitcnt lgkmcnt(" #n ")" ::: "memory")
; #define PG8_BAR __builtin_amdgcn_s_barrier()
; #define PG8_SCHED __builtin_amdgcn_sched_barrier(0)
; template <class Epi, class Sched, bool ALIGN_EPI = false, bool SP2 = false>
; __device__ __forceinline__ void gemm_phase(PG8_LAS unsigned char* lds, const Gemm g, const Sched& S, const Epi& E) {
;     ...
;             PG8_WAIT_V(8); PG8_WAIT_L(0); PG8_BAR; PG8_MMA(0, 0, At, B0); PG8_MMA(0, 1, At, B1); PG8_BAR; PG8_SCHED;
;             PG8_LDA(At, 0, 1); PG8_STAGE(PG8_SB(0, 0), b2, voffB); PG8_STAGE(PG8_SB(0, 1), b2 + hstep, voffB); PG8_STAGE(PG8_SA(0, 0), a2, voffA);
;             PG8_WAIT_V(8); PG8_WAIT_L(0); PG8_BAR; PG8_MMA(1, 0, At, B0); PG8_MMA(1, 1, At, B1); PG8_BAR; PG8_SCHED;
;             PG8_LDB(B0, 1, 0); PG8_LDB(B1, 1, 1); PG8_SCHED; PG8_LDA(At, 1, 0); PG8_STAGE(PG8_SA(0, 1), a2 + hstep, voffA);
;             PG8_WAIT_V(8); PG8_WAIT_L(0); PG8_BAR; PG8_MMA(0, 0, At, B0); PG8_MMA(0, 1, At, B1); PG8_BAR; PG8_SCHED;
	s_setprio 1
	s_waitcnt lgkmcnt(0)
	v_mfma_f32_16x16x32_bf16 v[60:63], v[146:149], v[184:187], v[60:63]
	v_mfma_f32_16x16x32_bf16 v[52:55], v[160:163], v[184:187], v[52:55]
	v_mfma_f32_16x16x32_bf16 v[44:47], v[146:149], v[192:195], v[44:47]
	v_mfma_f32_16x16x32_bf16 v[36:39], v[160:163], v[192:195], v[36:39]
	v_mfma_f32_16x16x32_bf16 v[28:31], v[146:149], v[200:203], v[28:31]
	v_mfma_f32_16x16x32_bf16 v[20:23], v[160:163], v[200:203], v[20:23]
	v_mfma_f32_16x16x32_bf16 v[12:15], v[146:149], v[208:211], v[12:15]
	v_mfma_f32_16x16x32_bf16 v[4:7], v[160:163], v[208:211], v[4:7]
	v_mfma_f32_16x16x32_bf16 v[60:63], v[156:159], v[188:191], v[60:63]
	v_mfma_f32_16x16x32_bf16 v[52:55], v[164:167], v[188:191], v[52:55]
	v_mfma_f32_16x16x32_bf16 v[44:47], v[156:159], v[196:199], v[44:47]
	v_mfma_f32_16x16x32_bf16 v[36:39], v[164:167], v[196:199], v[36:39]
	v_mfma_f32_16x16x32_bf16 v[28:31], v[156:159], v[204:207], v[28:31]
	v_mfma_f32_16x16x32_bf16 v[20:23], v[164:167], v[204:207], v[20:23]
	v_mfma_f32_16x16x32_bf16 v[12:15], v[156:159], v[212:215], v[12:15]
	v_mfma_f32_16x16x32_bf16 v[4:7], v[164:167], v[212:215], v[4:7]
	s_setprio 0
	s_setprio 1
	v_mfma_f32_16x16x32_bf16 v[56:59], v[168:171], v[184:187], v[56:59]
	v_mfma_f32_16x16x32_bf16 v[48:51], v[176:179], v[184:187], v[48:51]
	v_mfma_f32_16x16x32_bf16 v[40:43], v[168:171], v[192:195], v[40:43]
	v_mfma_f32_16x16x32_bf16 v[32:35], v[176:179], v[192:195], v[32:35]
	v_mfma_f32_16x16x32_bf16 v[24:27], v[168:171], v[200:203], v[24:27]
	v_mfma_f32_16x16x32_bf16 v[16:19], v[176:179], v[200:203], v[16:19]
	v_mfma_f32_16x16x32_bf16 v[8:11], v[168:171], v[208:211], v[8:11]
	v_mfma_f32_16x16x32_bf16 v[0:3], v[176:179], v[208:211], v[0:3]
	v_mfma_f32_16x16x32_bf16 v[56:59], v[172:175], v[188:191], v[56:59]
	v_mfma_f32_16x16x32_bf16 v[48:51], v[180:183], v[188:191], v[48:51]
	v_mfma_f32_16x16x32_bf16 v[40:43], v[172:175], v[196:199], v[40:43]
	v_mfma_f32_16x16x32_bf16 v[32:35], v[180:183], v[196:199], v[32:35]
	v_mfma_f32_16x16x32_bf16 v[24:27], v[172:175], v[204:207], v[24:27]
	v_mfma_f32_16x16x32_bf16 v[16:19], v[180:183], v[204:207], v[16:19]
	s_setprio 2
	s_barrier
	v_mfma_f32_16x16x32_bf16 v[8:11], v[172:175], v[212:215], v[8:11]
	v_mfma_f32_16x16x32_bf16 v[0:3], v[180:183], v[212:215], v[0:3]
	s_setprio 0
	s_add_i32 s54, 0, 0x18000
	s_add_i32 s55, 0, 0x1c000
	v_add_u32_e32 v164, s54, v151
	v_add_u32_e32 v180, s55, v151
	ds_read_b128 v[146:149], v164
	ds_read_b128 v[156:159], v164 offset:1024
	ds_read_b128 v[160:163], v164 offset:2048
	ds_read_b128 v[164:167], v164 offset:3072
	ds_read_b128 v[168:171], v180
	ds_read_b128 v[172:175], v180 offset:1024
	ds_read_b128 v[176:179], v180 offset:2048
	ds_read_b128 v[180:183], v180 offset:3072
	s_add_u32 s24, s24, 0x80000
	s_addc_u32 s25, s25, 0
	s_mov_b32 m0, s34
	v_lshl_add_u64 v[224:225], s[24:25], 0, v[136:137]
	ds_read_b128 v[184:187], v155 offset:32768
	ds_read_b128 v[188:191], v155 offset:33792
	ds_read_b128 v[192:195], v155 offset:34816
	ds_read_b128 v[196:199], v155 offset:35840
	ds_read_b128 v[200:203], v155 offset:36864
	ds_read_b128 v[204:207], v155 offset:37888
	ds_read_b128 v[208:211], v155 offset:38912
	ds_read_b128 v[212:215], v155 offset:39936
	global_load_lds_dwordx4 v[224:225], off
	v_lshl_add_u64 v[224:225], s[24:25], 0, v[132:133]
	s_mov_b32 m0, s35
	s_nop 0
	global_load_lds_dwordx4 v[224:225], off
	s_waitcnt vmcnt(8)
	s_waitcnt lgkmcnt(0)
	s_barrier
	s_setprio 1
	s_waitcnt lgkmcnt(0)
	v_mfma_f32_16x16x32_bf16 v[124:127], v[146:149], v[184:187], v[124:127]
	v_mfma_f32_16x16x32_bf16 v[116:119], v[160:163], v[184:187], v[116:119]
	v_mfma_f32_16x16x32_bf16 v[108:111], v[146:149], v[192:195], v[108:111]
	v_mfma_f32_16x16x32_bf16 v[100:103], v[160:163], v[192:195], v[100:103]
	v_mfma_f32_16x16x32_bf16 v[92:95], v[146:149], v[200:203], v[92:95]
	v_mfma_f32_16x16x32_bf16 v[84:87], v[160:163], v[200:203], v[84:87]
	v_mfma_f32_16x16x32_bf16 v[76:79], v[146:149], v[208:211], v[76:79]
	v_mfma_f32_16x16x32_bf16 v[68:71], v[160:163], v[208:211], v[68:71]
	v_mfma_f32_16x16x32_bf16 v[124:127], v[156:159], v[188:191], v[124:127]
	v_mfma_f32_16x16x32_bf16 v[116:119], v[164:167], v[188:191], v[116:119]
	v_mfma_f32_16x16x32_bf16 v[108:111], v[156:159], v[196:199], v[108:111]
	v_mfma_f32_16x16x32_bf16 v[100:103], v[164:167], v[196:199], v[100:103]
	v_mfma_f32_16x16x32_bf16 v[92:95], v[156:159], v[204:207], v[92:95]
	v_mfma_f32_16x16x32_bf16 v[84:87], v[164:167], v[204:207], v[84:87]
	v_mfma_f32_16x16x32_bf16 v[76:79], v[156:159], v[212:215], v[76:79]
	v_mfma_f32_16x16x32_bf16 v[68:71], v[164:167], v[212:215], v[68:71]
	s_setprio 0
	s_setprio 1
	v_mfma_f32_16x16x32_bf16 v[120:123], v[168:171], v[184:187], v[120:123]
	v_mfma_f32_16x16x32_bf16 v[112:115], v[176:179], v[184:187], v[112:115]
	v_mfma_f32_16x16x32_bf16 v[104:107], v[168:171], v[192:195], v[104:107]
	v_mfma_f32_16x16x32_bf16 v[96:99], v[176:179], v[192:195], v[96:99]
	v_mfma_f32_16x16x32_bf16 v[88:91], v[168:171], v[200:203], v[88:91]
	v_mfma_f32_16x16x32_bf16 v[80:83], v[176:179], v[200:203], v[80:83]
	v_mfma_f32_16x16x32_bf16 v[72:75], v[168:171], v[208:211], v[72:75]
	v_mfma_f32_16x16x32_bf16 v[64:67], v[176:179], v[208:211], v[64:67]
	v_mfma_f32_16x16x32_bf16 v[120:123], v[172:175], v[188:191], v[120:123]
	v_mfma_f32_16x16x32_bf16 v[112:115], v[180:183], v[188:191], v[112:115]
	v_mfma_f32_16x16x32_bf16 v[104:107], v[172:175], v[196:199], v[104:107]
	v_mfma_f32_16x16x32_bf16 v[96:99], v[180:183], v[196:199], v[96:99]
	v_mfma_f32_16x16x32_bf16 v[88:91], v[172:175], v[204:207], v[88:91]
	v_mfma_f32_16x16x32_bf16 v[80:83], v[180:183], v[204:207], v[80:83]
	s_setprio 2
	s_barrier
; #define PG8_STAGE(bufoff, gbase, voff) do { _Pragma("unroll") for (int _i = 0; _i < 2; ++_i) \
;         __builtin_amdgcn_global_load_lds((const unsigned*)((const char*)(gbase) + (voff)[_i]), (PG8_LAS unsigned*)(lds + (bufoff) + ldsw + _i * 8192), 16, 0, 0); } while (0)
; #define PG8_LDA(dst, b, h) do { _Pragma("unroll") for (int m = 0; m < 4; ++m) _Pragma("unroll") for (int k = 0; k < 2; ++k) dst[m][k] = *(const PG8_LAS bf16x8*)(lds + PG8_SA(b, h) + aoff + m * 2048 + k * 1024); } while (0)
; #define PG8_MMA(ai, bj, At, Bt) do { __builtin_amdgcn_s_setprio(1); _Pragma("unroll") for (int m = 0; m < 4; ++m) _Pragma("unroll") for (int n = 0; n < 2; ++n) _Pragma("unroll") for (int k = 0; k < 2; ++k) \
;         acc[ai][bj][m][n] = __builtin_amdgcn_mfma_f32_16x16x32_bf16(Bt[n][k], At[m][k], acc[ai][bj][m][n], 0, 0, 0); __builtin_amdgcn_s_setprio(0); } while (0)
; #define PG8_WAIT_V(n) asm volatile("s_waitcnt vmcnt(" #n ")" ::: "memory")
; #define PG8_WAIT_L(n) asm volatile("s_waitcnt lgkmcnt(" #n ")" ::: "memory")
; #define PG8_BAR __builtin_amdgcn_s_barrier()
; #define PG8_SCHED __builtin_amdgcn_sched_barrier(0)
; template <class Epi, class Sched, bool ALIGN_EPI = false, bool SP2 = false>
; __device__ __forceinline__ void gemm_phase(PG8_LAS unsigned char* lds, const Gemm g, const Sched& S, const Epi& E) {
;     ...
;             PG8_WAIT_V(8); PG8_WAIT_L(0); PG8_BAR; PG8_MMA(0, 0, At, B0); PG8_MMA(0, 1, At, B1); PG8_BAR; PG8_SCHED;
;             PG8_LDA(At, 1, 1); PG8_STAGE(PG8_SB(1, 0), b3, voffB); PG8_STAGE(PG8_SB(1, 1), b3 + hstep, voffB); PG8_STAGE(PG8_SA(1, 0), a3, voffA);
;             PG8_WAIT_V(8); PG8_WAIT_L(0); PG8_BAR; PG8_MMA(1, 0, At, B0); PG8_MMA(1, 1, At, B1); PG8_BAR; PG8_SCHED;
;     ...
;         if constexpr (ALIGN_EPI) { if (wr == 0) PG8_BAR; }
	v_mfma_f32_16x16x32_bf16 v[72:75], v[172:175], v[212:215], v[72:75]
	v_mfma_f32_16x16x32_bf16 v[64:67], v[180:183], v[212:215], v[64:67]
	s_setprio 0
	s_add_i32 s24, s54, s28
	v_lshl_add_u64 v[216:217], v[216:217], 0, s[4:5]
	s_mov_b32 m0, s24
	ds_read_b128 v[184:187], v155 offset:49152
	ds_read_b128 v[188:191], v155 offset:50176
	ds_read_b128 v[192:195], v155 offset:51200
	ds_read_b128 v[196:199], v155 offset:52224
	ds_read_b128 v[200:203], v155 offset:53248
	ds_read_b128 v[204:207], v155 offset:54272
	ds_read_b128 v[208:211], v155 offset:55296
	ds_read_b128 v[212:215], v155 offset:56320
	global_load_lds_dwordx4 v[216:217], off
	s_add_i32 m0, s24, 0x2000
	s_add_u32 s22, s22, 0x80080
	v_lshl_add_u64 v[216:217], v[218:219], 0, s[4:5]
	s_addc_u32 s23, s23, 0
	s_add_i32 s24, s55, s28
	global_load_lds_dwordx4 v[216:217], off
	v_lshl_add_u64 v[216:217], s[22:23], 0, v[134:135]
	s_mov_b32 m0, s24
	s_nop 0
	global_load_lds_dwordx4 v[216:217], off
	v_lshl_add_u64 v[216:217], s[22:23], 0, v[130:131]
	s_add_i32 m0, s24, 0x2000
	s_nop 0
	global_load_lds_dwordx4 v[216:217], off
	v_lshl_add_u64 v[216:217], v[220:221], 0, s[4:5]
	s_mov_b32 m0, s37
	s_nop 0
	global_load_lds_dwordx4 v[216:217], off
	v_lshl_add_u64 v[216:217], v[222:223], 0, s[4:5]
	s_mov_b32 m0, s38
	s_nop 0
	global_load_lds_dwordx4 v[216:217], off
	s_waitcnt vmcnt(8)
	s_waitcnt lgkmcnt(0)
	s_barrier
	s_setprio 1
	s_waitcnt lgkmcnt(0)
	v_mfma_f32_16x16x32_bf16 v[60:63], v[146:149], v[184:187], v[60:63]
	v_mfma_f32_16x16x32_bf16 v[52:55], v[160:163], v[184:187], v[52:55]
	v_mfma_f32_16x16x32_bf16 v[44:47], v[146:149], v[192:195], v[44:47]
	v_mfma_f32_16x16x32_bf16 v[36:39], v[160:163], v[192:195], v[36:39]
	v_mfma_f32_16x16x32_bf16 v[28:31], v[146:149], v[200:203], v[28:31]
	v_mfma_f32_16x16x32_bf16 v[20:23], v[160:163], v[200:203], v[20:23]
	v_mfma_f32_16x16x32_bf16 v[12:15], v[146:149], v[208:211], v[12:15]
	v_mfma_f32_16x16x32_bf16 v[4:7], v[160:163], v[208:211], v[4:7]
	v_mfma_f32_16x16x32_bf16 v[60:63], v[156:159], v[188:191], v[60:63]
	v_mfma_f32_16x16x32_bf16 v[52:55], v[164:167], v[188:191], v[52:55]
	v_mfma_f32_16x16x32_bf16 v[44:47], v[156:159], v[196:199], v[44:47]
	v_mfma_f32_16x16x32_bf16 v[36:39], v[164:167], v[196:199], v[36:39]
	v_mfma_f32_16x16x32_bf16 v[28:31], v[156:159], v[204:207], v[28:31]
	v_mfma_f32_16x16x32_bf16 v[20:23], v[164:167], v[204:207], v[20:23]
	v_mfma_f32_16x16x32_bf16 v[12:15], v[156:159], v[212:215], v[12:15]
	v_mfma_f32_16x16x32_bf16 v[4:7], v[164:167], v[212:215], v[4:7]
	s_setprio 0
	s_setprio 1
	v_mfma_f32_16x16x32_bf16 v[56:59], v[168:171], v[184:187], v[56:59]
	v_mfma_f32_16x16x32_bf16 v[48:51], v[176:179], v[184:187], v[48:51]
	v_mfma_f32_16x16x32_bf16 v[40:43], v[168:171], v[192:195], v[40:43]
	v_mfma_f32_16x16x32_bf16 v[32:35], v[176:179], v[192:195], v[32:35]
	v_mfma_f32_16x16x32_bf16 v[24:27], v[168:171], v[200:203], v[24:27]
	v_mfma_f32_16x16x32_bf16 v[16:19], v[176:179], v[200:203], v[16:19]
	v_mfma_f32_16x16x32_bf16 v[8:11], v[168:171], v[208:211], v[8:11]
	v_mfma_f32_16x16x32_bf16 v[0:3], v[176:179], v[208:211], v[0:3]
	v_mfma_f32_16x16x32_bf16 v[56:59], v[172:175], v[188:191], v[56:59]
	v_mfma_f32_16x16x32_bf16 v[48:51], v[180:183], v[188:191], v[48:51]
	v_mfma_f32_16x16x32_bf16 v[40:43], v[172:175], v[196:199], v[40:43]
	v_mfma_f32_16x16x32_bf16 v[32:35], v[180:183], v[196:199], v[32:35]
	v_mfma_f32_16x16x32_bf16 v[24:27], v[172:175], v[204:207], v[24:27]
	v_mfma_f32_16x16x32_bf16 v[16:19], v[180:183], v[204:207], v[16:19]
	s_setprio 2
	s_barrier
	v_mfma_f32_16x16x32_bf16 v[8:11], v[172:175], v[212:215], v[8:11]
	v_mfma_f32_16x16x32_bf16 v[0:3], v[180:183], v[212:215], v[0:3]
	s_setprio 0
	s_add_i32 s53, s53, 2
	s_add_u32 s20, s20, 0x100
	s_addc_u32 s21, s21, 0
	s_add_u32 s51, s51, 0x100
	s_addc_u32 s52, s52, 0
	s_cmp_gt_u32 s53, 29
	s_cbranch_scc0 .LBB0_48
	s_and_b64 vcc, exec, s[8:9]
	s_cbranch_vccz .LBB0_51
	s_barrier

; #define PG8_STAGE(bufoff, gbase, voff) do { _Pragma("unroll") for (int _i = 0; _i < 2; ++_i) \
;         __builtin_amdgcn_global_load_lds((const unsigned*)((const char*)(gbase) + (voff)[_i]), (PG8_LAS unsigned*)(lds + (bufoff) + ldsw + _i * 8192), 16, 0, 0); } while (0)
; #define PG8_LDA(dst, b, h) do { _Pragma("unroll") for (int m = 0; m < 4; ++m) _Pragma("unroll") for (int k = 0; k < 2; ++k) dst[m][k] = *(const PG8_LAS bf16x8*)(lds + PG8_SA(b, h) + aoff + m * 2048 + k * 1024); } while (0)
; #define PG8_LDB(dst, b, h) do { _Pragma("unroll") for (int n = 0; n < 2; ++n) _Pragma("unroll") for (int k = 0; k < 2; ++k) dst[n][k] = *(const PG8_LAS bf16x8*)(lds + PG8_SB(b, h) + boff + n * 2048 + k * 1024); } while (0)
; #define PG8_MMA(ai, bj, At, Bt) do { __builtin_amdgcn_s_setprio(1); _Pragma("unroll") for (int m = 0; m < 4; ++m) _Pragma("unroll") for (int n = 0; n < 2; ++n) _Pragma("unroll") for (int k = 0; k < 2; ++k) \
;         acc[ai][bj][m][n] = __builtin_amdgcn_mfma_f32_16x16x32_bf16(Bt[n][k], At[m][k], acc[ai][bj][m][n], 0, 0, 0); __builtin_amdgcn_s_setprio(0); } while (0)
; #define PG8_WAIT_V(n) asm volatile("s_waitcnt vmcnt(" #n ")" ::: "memory")
; #define PG8_BAR __builtin_amdgcn_s_barrier()
; template <class Epi, class Sched, bool ALIGN_EPI = false, bool SP2 = false>
; __device__ __forceinline__ void gemm_phase(PG8_LAS unsigned char* lds, const Gemm g, const Sched& S, const Epi& E) {
;     ...
;         for (int t = 0; t < nt; t += 2) {
;             const bool last = (t == nt - 2);
;             const char* a1 = cA + (size_t)(t + 1) * kstep;
;             const char* a2 = last ? nA : cA + (size_t)(t + 2) * kstep; const char* b2 = last ? nB : cB + (size_t)(t + 2) * kstep;
;             const char* a3 = a2 + kstep; const char* b3 = b2 + kstep;
;             if (last && has_next) S.a_ready(nxt);
;             if constexpr (SP2) {
;             PG8_LDB(B0, 0, 0); PG8_LDB(B1, 0, 1); PG8_SCHED; PG8_LDA(At, 0, 0); PG8_STAGE(PG8_SA(1, 1), a1 + hstep, voffA);
;             PG8_WAIT_V(8); PG8_WAIT_L(0); PG8_BAR; PG8_MMA(0, 0, At, B0); PG8_MMA(0, 1, At, B1); PG8_BAR; PG8_SCHED;
;             PG8_LDA(At, 0, 1); PG8_STAGE(PG8_SB(0, 0), b2, voffB); PG8_STAGE(PG8_SB(0, 1), b2 + hstep, voffB); PG8_STAGE(PG8_SA(0, 0), a2, voffA);
;             PG8_WAIT_V(8); PG8_WAIT_L(0); PG8_BAR; PG8_MMA(1, 0, At, B0); PG8_MMA(1, 1, At, B1); PG8_BAR; PG8_SCHED;
.LBB0_140:
	ds_read_b128 v[158:161], v155
	ds_read_b128 v[162:165], v155 offset:1024
	ds_read_b128 v[166:169], v155 offset:2048
	ds_read_b128 v[170:173], v155 offset:3072
	ds_read_b128 v[174:177], v156
	ds_read_b128 v[178:181], v156 offset:1024
	ds_read_b128 v[182:185], v156 offset:2048
	ds_read_b128 v[186:189], v156 offset:3072
	s_add_u32 s24, s22, 0xffea0080
	s_addc_u32 s25, s23, -1
	s_cmpk_eq_i32 s58, 0x54
	s_cselect_b32 s27, s19, s25
	s_cselect_b32 s26, s18, s24
	s_cselect_b32 s25, s21, s57
	s_cselect_b32 s24, s20, s56
	v_lshl_add_u64 v[222:223], s[22:23], 0, v[138:139]
	s_add_i32 m0, s31, 0xc000
	ds_read_b128 v[190:193], v157
	ds_read_b128 v[194:197], v157 offset:1024
	ds_read_b128 v[198:201], v157 offset:2048
	ds_read_b128 v[202:205], v157 offset:3072
	ds_read_b128 v[206:209], v157 offset:4096
	ds_read_b128 v[210:213], v157 offset:5120
	ds_read_b128 v[214:217], v157 offset:6144
	ds_read_b128 v[218:221], v157 offset:7168
	global_load_lds_dwordx4 v[222:223], off
	v_lshl_add_u64 v[222:223], s[22:23], 0, v[140:141]
	s_add_i32 m0, s31, 0xe000
	s_nop 0
	global_load_lds_dwordx4 v[222:223], off
	s_waitcnt vmcnt(8)
	s_waitcnt lgkmcnt(0)
	s_barrier
	s_setprio 1
	s_waitcnt lgkmcnt(0)
	v_mfma_f32_16x16x32_bf16 v[124:127], v[158:161], v[190:193], v[124:127]
	v_mfma_f32_16x16x32_bf16 v[120:123], v[166:169], v[190:193], v[120:123]
	v_mfma_f32_16x16x32_bf16 v[116:119], v[158:161], v[198:201], v[116:119]
	v_mfma_f32_16x16x32_bf16 v[112:115], v[166:169], v[198:201], v[112:115]
	v_mfma_f32_16x16x32_bf16 v[100:103], v[158:161], v[206:209], v[100:103]
	v_mfma_f32_16x16x32_bf16 v[96:99], v[166:169], v[206:209], v[96:99]
	v_mfma_f32_16x16x32_bf16 v[84:87], v[158:161], v[214:217], v[84:87]
	v_mfma_f32_16x16x32_bf16 v[80:83], v[166:169], v[214:217], v[80:83]
	v_mfma_f32_16x16x32_bf16 v[124:127], v[162:165], v[194:197], v[124:127]
	v_mfma_f32_16x16x32_bf16 v[120:123], v[170:173], v[194:197], v[120:123]
	v_mfma_f32_16x16x32_bf16 v[116:119], v[162:165], v[202:205], v[116:119]
	v_mfma_f32_16x16x32_bf16 v[112:115], v[170:173], v[202:205], v[112:115]
	v_mfma_f32_16x16x32_bf16 v[100:103], v[162:165], v[210:213], v[100:103]
	v_mfma_f32_16x16x32_bf16 v[96:99], v[170:173], v[210:213], v[96:99]
	v_mfma_f32_16x16x32_bf16 v[84:87], v[162:165], v[218:221], v[84:87]
	v_mfma_f32_16x16x32_bf16 v[80:83], v[170:173], v[218:221], v[80:83]
	s_setprio 0
	s_setprio 1
	v_mfma_f32_16x16x32_bf16 v[108:111], v[174:177], v[190:193], v[108:111]
	v_mfma_f32_16x16x32_bf16 v[104:107], v[182:185], v[190:193], v[104:107]
	v_mfma_f32_16x16x32_bf16 v[92:95], v[174:177], v[198:201], v[92:95]
	v_mfma_f32_16x16x32_bf16 v[88:91], v[182:185], v[198:201], v[88:91]
	v_mfma_f32_16x16x32_bf16 v[76:79], v[174:177], v[206:209], v[76:79]
	v_mfma_f32_16x16x32_bf16 v[72:75], v[182:185], v[206:209], v[72:75]
	v_mfma_f32_16x16x32_bf16 v[68:71], v[174:177], v[214:217], v[68:71]
	v_mfma_f32_16x16x32_bf16 v[64:67], v[182:185], v[214:217], v[64:67]
	v_mfma_f32_16x16x32_bf16 v[108:111], v[178:181], v[194:197], v[108:111]
	v_mfma_f32_16x16x32_bf16 v[104:107], v[186:189], v[194:197], v[104:107]
	v_mfma_f32_16x16x32_bf16 v[92:95], v[178:181], v[202:205], v[92:95]
	v_mfma_f32_16x16x32_bf16 v[88:91], v[186:189], v[202:205], v[88:91]
	v_mfma_f32_16x16x32_bf16 v[76:79], v[178:181], v[210:213], v[76:79]
	v_mfma_f32_16x16x32_bf16 v[72:75], v[186:189], v[210:213], v[72:75]
	s_setprio 2
	s_barrier
	v_mfma_f32_16x16x32_bf16 v[68:71], v[178:181], v[218:221], v[68:71]
	v_mfma_f32_16x16x32_bf16 v[64:67], v[186:189], v[218:221], v[64:67]
	s_setprio 0
	s_add_i32 s59, s42, s28
	v_lshl_add_u64 v[222:223], s[24:25], 0, v[132:133]
	s_mov_b32 m0, s59
	ds_read_b128 v[190:193], v157 offset:16384
	ds_read_b128 v[194:197], v157 offset:17408
	ds_read_b128 v[198:201], v157 offset:18432
	ds_read_b128 v[202:205], v157 offset:19456
	ds_read_b128 v[206:209], v157 offset:20480
	ds_read_b128 v[210:213], v157 offset:21504
	ds_read_b128 v[214:217], v157 offset:22528
	ds_read_b128 v[218:221], v157 offset:23552
	global_load_lds_dwordx4 v[222:223], off
	s_add_i32 m0, s59, 0x2000
	s_add_u32 s60, s24, 0x160000
	v_lshl_add_u64 v[224:225], s[24:25], 0, v[136:137]
	s_addc_u32 s61, s25, 0
	s_add_i32 s59, s43, s28
	global_load_lds_dwordx4 v[224:225], off
	v_lshl_add_u64 v[226:227], s[60:61], 0, v[132:133]
	s_mov_b32 m0, s59
	v_lshl_add_u64 v[228:229], s[26:27], 0, v[134:135]
	global_load_lds_dwordx4 v[226:227], off
	v_lshl_add_u64 v[226:227], s[60:61], 0, v[136:137]
	s_add_i32 m0, s59, 0x2000
	s_nop 0
	global_load_lds_dwordx4 v[226:227], off
	v_lshl_add_u64 v[226:227], s[26:27], 0, v[130:131]
	s_mov_b32 m0, s31
	s_nop 0
	global_load_lds_dwordx4 v[226:227], off
	s_mov_b32 m0, s34
	s_nop 0
	global_load_lds_dwordx4 v[228:229], off
	s_waitcnt vmcnt(8)
	s_waitcnt lgkmcnt(0)
	s_barrier
; #define PG8_STAGE(bufoff, gbase, voff) do { _Pragma("unroll") for (int _i = 0; _i < 2; ++_i) \
;         __builtin_amdgcn_global_load_lds((const unsigned*)((const char*)(gbase) + (voff)[_i]), (PG8_LAS unsigned*)(lds + (bufoff) + ldsw + _i * 8192), 16, 0, 0); } while (0)
; #define PG8_LDA(dst, b, h) do { _Pragma("unroll") for (int m = 0; m < 4; ++m) _Pragma("unroll") for (int k = 0; k < 2; ++k) dst[m][k] = *(const PG8_LAS bf16x8*)(lds + PG8_SA(b, h) + aoff + m * 2048 + k * 1024); } while (0)
; #define PG8_LDB(dst, b, h) do { _Pragma("unroll") for (int n = 0; n < 2; ++n) _Pragma("unroll") for (int k = 0; k < 2; ++k) dst[n][k] = *(const PG8_LAS bf16x8*)(lds + PG8_SB(b, h) + boff + n * 2048 + k * 1024); } while (0)
; #define PG8_MMA(ai, bj, At, Bt) do { __builtin_amdgcn_s_setprio(1); _Pragma("unroll") for (int m = 0; m < 4; ++m) _Pragma("unroll") for (int n = 0; n < 2; ++n) _Pragma("unroll") for (int k = 0; k < 2; ++k) \
;         acc[ai][bj][m][n] = __builtin_amdgcn_mfma_f32_16x16x32_bf16(Bt[n][k], At[m][k], acc[ai][bj][m][n], 0, 0, 0); __builtin_amdgcn_s_setprio(0); } while (0)
; #define PG8_WAIT_V(n) asm volatile("s_waitcnt vmcnt(" #n ")" ::: "memory")
; #define PG8_WAIT_L(n) asm volatile("s_waitcnt lgkmcnt(" #n ")" ::: "memory")
; #define PG8_BAR __builtin_amdgcn_s_barrier()
; #define PG8_SCHED __builtin_amdgcn_sched_barrier(0)
; template <class Epi, class Sched, bool ALIGN_EPI = false, bool SP2 = false>
; __device__ __forceinline__ void gemm_phase(PG8_LAS unsigned char* lds, const Gemm g, const Sched& S, const Epi& E) {
;     ...
;             PG8_WAIT_V(8); PG8_WAIT_L(0); PG8_BAR; PG8_MMA(1, 0, At, B0); PG8_MMA(1, 1, At, B1); PG8_BAR; PG8_SCHED;
;             PG8_LDB(B0, 1, 0); PG8_LDB(B1, 1, 1); PG8_SCHED; PG8_LDA(At, 1, 0); PG8_STAGE(PG8_SA(0, 1), a2 + hstep, voffA);
;             PG8_WAIT_V(8); PG8_WAIT_L(0); PG8_BAR; PG8_MMA(0, 0, At, B0); PG8_MMA(0, 1, At, B1); PG8_BAR; PG8_SCHED;
	s_setprio 1
	s_waitcnt lgkmcnt(0)
	v_mfma_f32_16x16x32_bf16 v[60:63], v[158:161], v[190:193], v[60:63]
	v_mfma_f32_16x16x32_bf16 v[56:59], v[166:169], v[190:193], v[56:59]
	v_mfma_f32_16x16x32_bf16 v[52:55], v[158:161], v[198:201], v[52:55]
	v_mfma_f32_16x16x32_bf16 v[48:51], v[166:169], v[198:201], v[48:51]
	v_mfma_f32_16x16x32_bf16 v[36:39], v[158:161], v[206:209], v[36:39]
	v_mfma_f32_16x16x32_bf16 v[32:35], v[166:169], v[206:209], v[32:35]
	v_mfma_f32_16x16x32_bf16 v[20:23], v[158:161], v[214:217], v[20:23]
	v_mfma_f32_16x16x32_bf16 v[16:19], v[166:169], v[214:217], v[16:19]
	v_mfma_f32_16x16x32_bf16 v[60:63], v[162:165], v[194:197], v[60:63]
	v_mfma_f32_16x16x32_bf16 v[56:59], v[170:173], v[194:197], v[56:59]
	v_mfma_f32_16x16x32_bf16 v[52:55], v[162:165], v[202:205], v[52:55]
	v_mfma_f32_16x16x32_bf16 v[48:51], v[170:173], v[202:205], v[48:51]
	v_mfma_f32_16x16x32_bf16 v[36:39], v[162:165], v[210:213], v[36:39]
	v_mfma_f32_16x16x32_bf16 v[32:35], v[170:173], v[210:213], v[32:35]
	v_mfma_f32_16x16x32_bf16 v[20:23], v[162:165], v[218:221], v[20:23]
	v_mfma_f32_16x16x32_bf16 v[16:19], v[170:173], v[218:221], v[16:19]
	s_setprio 0
	s_setprio 1
	v_mfma_f32_16x16x32_bf16 v[44:47], v[174:177], v[190:193], v[44:47]
	v_mfma_f32_16x16x32_bf16 v[40:43], v[182:185], v[190:193], v[40:43]
	v_mfma_f32_16x16x32_bf16 v[28:31], v[174:177], v[198:201], v[28:31]
	v_mfma_f32_16x16x32_bf16 v[24:27], v[182:185], v[198:201], v[24:27]
	v_mfma_f32_16x16x32_bf16 v[12:15], v[174:177], v[206:209], v[12:15]
	v_mfma_f32_16x16x32_bf16 v[8:11], v[182:185], v[206:209], v[8:11]
	v_mfma_f32_16x16x32_bf16 v[4:7], v[174:177], v[214:217], v[4:7]
	v_mfma_f32_16x16x32_bf16 v[0:3], v[182:185], v[214:217], v[0:3]
	v_mfma_f32_16x16x32_bf16 v[44:47], v[178:181], v[194:197], v[44:47]
	v_mfma_f32_16x16x32_bf16 v[40:43], v[186:189], v[194:197], v[40:43]
	v_mfma_f32_16x16x32_bf16 v[28:31], v[178:181], v[202:205], v[28:31]
	v_mfma_f32_16x16x32_bf16 v[24:27], v[186:189], v[202:205], v[24:27]
	v_mfma_f32_16x16x32_bf16 v[12:15], v[178:181], v[210:213], v[12:15]
	v_mfma_f32_16x16x32_bf16 v[8:11], v[186:189], v[210:213], v[8:11]
	s_setprio 2
	s_barrier
	v_mfma_f32_16x16x32_bf16 v[4:7], v[178:181], v[218:221], v[4:7]
	v_mfma_f32_16x16x32_bf16 v[0:3], v[186:189], v[218:221], v[0:3]
	s_setprio 0
	s_add_i32 s59, 0, 0x18000
	s_add_i32 s60, 0, 0x1c000
	v_add_u32_e32 v170, s59, v153
	v_add_u32_e32 v186, s60, v153
	ds_read_b128 v[158:161], v170
	ds_read_b128 v[162:165], v170 offset:1024
	ds_read_b128 v[166:169], v170 offset:2048
	ds_read_b128 v[170:173], v170 offset:3072
	ds_read_b128 v[174:177], v186
	ds_read_b128 v[178:181], v186 offset:1024
	ds_read_b128 v[182:185], v186 offset:2048
	ds_read_b128 v[186:189], v186 offset:3072
	s_add_u32 s26, s26, 0x160000
	s_addc_u32 s27, s27, 0
	s_mov_b32 m0, s35
	v_lshl_add_u64 v[230:231], s[26:27], 0, v[130:131]
	ds_read_b128 v[190:193], v157 offset:32768
	ds_read_b128 v[194:197], v157 offset:33792
	ds_read_b128 v[198:201], v157 offset:34816
	ds_read_b128 v[202:205], v157 offset:35840
	ds_read_b128 v[206:209], v157 offset:36864
	ds_read_b128 v[210:213], v157 offset:37888
	ds_read_b128 v[214:217], v157 offset:38912
	ds_read_b128 v[218:221], v157 offset:39936
	global_load_lds_dwordx4 v[230:231], off
	v_lshl_add_u64 v[230:231], s[26:27], 0, v[134:135]
	s_mov_b32 m0, s36
	s_nop 0
	global_load_lds_dwordx4 v[230:231], off
	s_waitcnt vmcnt(8)
	s_waitcnt lgkmcnt(0)
	s_barrier
	s_setprio 1
	s_waitcnt lgkmcnt(0)
	v_mfma_f32_16x16x32_bf16 v[124:127], v[158:161], v[190:193], v[124:127]
	v_mfma_f32_16x16x32_bf16 v[120:123], v[166:169], v[190:193], v[120:123]
	v_mfma_f32_16x16x32_bf16 v[116:119], v[158:161], v[198:201], v[116:119]
	v_mfma_f32_16x16x32_bf16 v[112:115], v[166:169], v[198:201], v[112:115]
	v_mfma_f32_16x16x32_bf16 v[100:103], v[158:161], v[206:209], v[100:103]
	v_mfma_f32_16x16x32_bf16 v[96:99], v[166:169], v[206:209], v[96:99]
	v_mfma_f32_16x16x32_bf16 v[84:87], v[158:161], v[214:217], v[84:87]
	v_mfma_f32_16x16x32_bf16 v[80:83], v[166:169], v[214:217], v[80:83]
	v_mfma_f32_16x16x32_bf16 v[124:127], v[162:165], v[194:197], v[124:127]
	v_mfma_f32_16x16x32_bf16 v[120:123], v[170:173], v[194:197], v[120:123]
	v_mfma_f32_16x16x32_bf16 v[116:119], v[162:165], v[202:205], v[116:119]
	v_mfma_f32_16x16x32_bf16 v[112:115], v[170:173], v[202:205], v[112:115]
	v_mfma_f32_16x16x32_bf16 v[100:103], v[162:165], v[210:213], v[100:103]
	v_mfma_f32_16x16x32_bf16 v[96:99], v[170:173], v[210:213], v[96:99]
	v_mfma_f32_16x16x32_bf16 v[84:87], v[162:165], v[218:221], v[84:87]
	v_mfma_f32_16x16x32_bf16 v[80:83], v[170:173], v[218:221], v[80:83]
	s_setprio 0
	s_setprio 1
	v_mfma_f32_16x16x32_bf16 v[108:111], v[174:177], v[190:193], v[108:111]
	v_mfma_f32_16x16x32_bf16 v[104:107], v[182:185], v[190:193], v[104:107]
	v_mfma_f32_16x16x32_bf16 v[92:95], v[174:177], v[198:201], v[92:95]
	v_mfma_f32_16x16x32_bf16 v[88:91], v[182:185], v[198:201], v[88:91]
	v_mfma_f32_16x16x32_bf16 v[76:79], v[174:177], v[206:209], v[76:79]
	v_mfma_f32_16x16x32_bf16 v[72:75], v[182:185], v[206:209], v[72:75]
	v_mfma_f32_16x16x32_bf16 v[68:71], v[174:177], v[214:217], v[68:71]
	v_mfma_f32_16x16x32_bf16 v[64:67], v[182:185], v[214:217], v[64:67]
	v_mfma_f32_16x16x32_bf16 v[108:111], v[178:181], v[194:197], v[108:111]
	v_mfma_f32_16x16x32_bf16 v[104:107], v[186:189], v[194:197], v[104:107]
	v_mfma_f32_16x16x32_bf16 v[92:95], v[178:181], v[202:205], v[92:95]
	v_mfma_f32_16x16x32_bf16 v[88:91], v[186:189], v[202:205], v[88:91]
	v_mfma_f32_16x16x32_bf16 v[76:79], v[178:181], v[210:213], v[76:79]
	v_mfma_f32_16x16x32_bf16 v[72:75], v[186:189], v[210:213], v[72:75]
	s_setprio 2
	s_barrier
; #define PG8_STAGE(bufoff, gbase, voff) do { _Pragma("unroll") for (int _i = 0; _i < 2; ++_i) \
;         __builtin_amdgcn_global_load_lds((const unsigned*)((const char*)(gbase) + (voff)[_i]), (PG8_LAS unsigned*)(lds + (bufoff) + ldsw + _i * 8192), 16, 0, 0); } while (0)
; #define PG8_LDA(dst, b, h) do { _Pragma("unroll") for (int m = 0; m < 4; ++m) _Pragma("unroll") for (int k = 0; k < 2; ++k) dst[m][k] = *(const PG8_LAS bf16x8*)(lds + PG8_SA(b, h) + aoff + m * 2048 + k * 1024); } while (0)
; #define PG8_MMA(ai, bj, At, Bt) do { __builtin_amdgcn_s_setprio(1); _Pragma("unroll") for (int m = 0; m < 4; ++m) _Pragma("unroll") for (int n = 0; n < 2; ++n) _Pragma("unroll") for (int k = 0; k < 2; ++k) \
;         acc[ai][bj][m][n] = __builtin_amdgcn_mfma_f32_16x16x32_bf16(Bt[n][k], At[m][k], acc[ai][bj][m][n], 0, 0, 0); __builtin_amdgcn_s_setprio(0); } while (0)
; #define PG8_WAIT_V(n) asm volatile("s_waitcnt vmcnt(" #n ")" ::: "memory")
; #define PG8_WAIT_L(n) asm volatile("s_waitcnt lgkmcnt(" #n ")" ::: "memory")
; #define PG8_BAR __builtin_amdgcn_s_barrier()
; #define PG8_SCHED __builtin_amdgcn_sched_barrier(0)
; template <class Epi, class Sched, bool ALIGN_EPI = false, bool SP2 = false>
; __device__ __forceinline__ void gemm_phase(PG8_LAS unsigned char* lds, const Gemm g, const Sched& S, const Epi& E) {
;     ...
;             PG8_WAIT_V(8); PG8_WAIT_L(0); PG8_BAR; PG8_MMA(0, 0, At, B0); PG8_MMA(0, 1, At, B1); PG8_BAR; PG8_SCHED;
;             PG8_LDA(At, 1, 1); PG8_STAGE(PG8_SB(1, 0), b3, voffB); PG8_STAGE(PG8_SB(1, 1), b3 + hstep, voffB); PG8_STAGE(PG8_SA(1, 0), a3, voffA);
;             PG8_WAIT_V(8); PG8_WAIT_L(0); PG8_BAR; PG8_MMA(1, 0, At, B0); PG8_MMA(1, 1, At, B1); PG8_BAR; PG8_SCHED;
;     ...
;         if constexpr (ALIGN_EPI) { if (wr == 0) PG8_BAR; }
	v_mfma_f32_16x16x32_bf16 v[68:71], v[178:181], v[218:221], v[68:71]
	v_mfma_f32_16x16x32_bf16 v[64:67], v[186:189], v[218:221], v[64:67]
	s_setprio 0
	s_add_i32 s26, s59, s28
	v_lshl_add_u64 v[222:223], v[222:223], 0, s[4:5]
	s_mov_b32 m0, s26
	ds_read_b128 v[190:193], v157 offset:49152
	ds_read_b128 v[194:197], v157 offset:50176
	ds_read_b128 v[198:201], v157 offset:51200
	ds_read_b128 v[202:205], v157 offset:52224
	ds_read_b128 v[206:209], v157 offset:53248
	ds_read_b128 v[210:213], v157 offset:54272
	ds_read_b128 v[214:217], v157 offset:55296
	ds_read_b128 v[218:221], v157 offset:56320
	global_load_lds_dwordx4 v[222:223], off
	s_add_i32 m0, s26, 0x2000
	s_add_u32 s24, s24, 0x160080
	v_lshl_add_u64 v[222:223], v[224:225], 0, s[4:5]
	s_addc_u32 s25, s25, 0
	s_add_i32 s26, s60, s28
	global_load_lds_dwordx4 v[222:223], off
	v_lshl_add_u64 v[222:223], s[24:25], 0, v[132:133]
	s_mov_b32 m0, s26
	s_nop 0
	global_load_lds_dwordx4 v[222:223], off
	v_lshl_add_u64 v[222:223], s[24:25], 0, v[136:137]
	s_add_i32 m0, s26, 0x2000
	s_nop 0
	global_load_lds_dwordx4 v[222:223], off
	v_lshl_add_u64 v[222:223], v[226:227], 0, s[4:5]
	s_mov_b32 m0, s38
	s_nop 0
	global_load_lds_dwordx4 v[222:223], off
	v_lshl_add_u64 v[222:223], v[228:229], 0, s[4:5]
	s_mov_b32 m0, s39
	s_nop 0
	global_load_lds_dwordx4 v[222:223], off
	s_waitcnt vmcnt(8)
	s_waitcnt lgkmcnt(0)
	s_barrier
	s_setprio 1
	s_waitcnt lgkmcnt(0)
	v_mfma_f32_16x16x32_bf16 v[60:63], v[158:161], v[190:193], v[60:63]
	v_mfma_f32_16x16x32_bf16 v[56:59], v[166:169], v[190:193], v[56:59]
	v_mfma_f32_16x16x32_bf16 v[52:55], v[158:161], v[198:201], v[52:55]
	v_mfma_f32_16x16x32_bf16 v[48:51], v[166:169], v[198:201], v[48:51]
	v_mfma_f32_16x16x32_bf16 v[36:39], v[158:161], v[206:209], v[36:39]
	v_mfma_f32_16x16x32_bf16 v[32:35], v[166:169], v[206:209], v[32:35]
	v_mfma_f32_16x16x32_bf16 v[20:23], v[158:161], v[214:217], v[20:23]
	v_mfma_f32_16x16x32_bf16 v[16:19], v[166:169], v[214:217], v[16:19]
	v_mfma_f32_16x16x32_bf16 v[60:63], v[162:165], v[194:197], v[60:63]
	v_mfma_f32_16x16x32_bf16 v[56:59], v[170:173], v[194:197], v[56:59]
	v_mfma_f32_16x16x32_bf16 v[52:55], v[162:165], v[202:205], v[52:55]
	v_mfma_f32_16x16x32_bf16 v[48:51], v[170:173], v[202:205], v[48:51]
	v_mfma_f32_16x16x32_bf16 v[36:39], v[162:165], v[210:213], v[36:39]
	v_mfma_f32_16x16x32_bf16 v[32:35], v[170:173], v[210:213], v[32:35]
	v_mfma_f32_16x16x32_bf16 v[20:23], v[162:165], v[218:221], v[20:23]
	v_mfma_f32_16x16x32_bf16 v[16:19], v[170:173], v[218:221], v[16:19]
	s_setprio 0
	s_setprio 1
	v_mfma_f32_16x16x32_bf16 v[44:47], v[174:177], v[190:193], v[44:47]
	v_mfma_f32_16x16x32_bf16 v[40:43], v[182:185], v[190:193], v[40:43]
	v_mfma_f32_16x16x32_bf16 v[28:31], v[174:177], v[198:201], v[28:31]
	v_mfma_f32_16x16x32_bf16 v[24:27], v[182:185], v[198:201], v[24:27]
	v_mfma_f32_16x16x32_bf16 v[12:15], v[174:177], v[206:209], v[12:15]
	v_mfma_f32_16x16x32_bf16 v[8:11], v[182:185], v[206:209], v[8:11]
	v_mfma_f32_16x16x32_bf16 v[4:7], v[174:177], v[214:217], v[4:7]
	v_mfma_f32_16x16x32_bf16 v[0:3], v[182:185], v[214:217], v[0:3]
	v_mfma_f32_16x16x32_bf16 v[44:47], v[178:181], v[194:197], v[44:47]
	v_mfma_f32_16x16x32_bf16 v[40:43], v[186:189], v[194:197], v[40:43]
	v_mfma_f32_16x16x32_bf16 v[28:31], v[178:181], v[202:205], v[28:31]
	v_mfma_f32_16x16x32_bf16 v[24:27], v[186:189], v[202:205], v[24:27]
	v_mfma_f32_16x16x32_bf16 v[12:15], v[178:181], v[210:213], v[12:15]
	v_mfma_f32_16x16x32_bf16 v[8:11], v[186:189], v[210:213], v[8:11]
	s_setprio 2
	s_barrier
	v_mfma_f32_16x16x32_bf16 v[4:7], v[178:181], v[218:221], v[4:7]
	v_mfma_f32_16x16x32_bf16 v[0:3], v[186:189], v[218:221], v[0:3]
	s_setprio 0
	s_add_i32 s58, s58, 2
	s_add_u32 s22, s22, 0x100
	s_addc_u32 s23, s23, 0
	s_add_u32 s56, s56, 0x100
	s_addc_u32 s57, s57, 0
	s_cmpk_gt_u32 s58, 0x55
	s_cbranch_scc0 .LBB0_140
	s_and_b64 vcc, exec, s[8:9]
	s_cbranch_vccz .LBB0_143
	s_barrier

; #define PG8_STAGE(bufoff, gbase, voff) do { _Pragma("unroll") for (int _i = 0; _i < 2; ++_i) \
;         __builtin_amdgcn_global_load_lds((const unsigned*)((const char*)(gbase) + (voff)[_i]), (PG8_LAS unsigned*)(lds + (bufoff) + ldsw + _i * 8192), 16, 0, 0); } while (0)
; #define PG8_LDA(dst, b, h) do { _Pragma("unroll") for (int m = 0; m < 4; ++m) _Pragma("unroll") for (int k = 0; k < 2; ++k) dst[m][k] = *(const PG8_LAS bf16x8*)(lds + PG8_SA(b, h) + aoff + m * 2048 + k * 1024); } while (0)
; #define PG8_LDB(dst, b, h) do { _Pragma("unroll") for (int n = 0; n < 2; ++n) _Pragma("unroll") for (int k = 0; k < 2; ++k) dst[n][k] = *(const PG8_LAS bf16x8*)(lds + PG8_SB(b, h) + boff + n * 2048 + k * 1024); } while (0)
; #define PG8_MMA(ai, bj, At, Bt) do { __builtin_amdgcn_s_setprio(1); _Pragma("unroll") for (int m = 0; m < 4; ++m) _Pragma("unroll") for (int n = 0; n < 2; ++n) _Pragma("unroll") for (int k = 0; k < 2; ++k) \
;         acc[ai][bj][m][n] = __builtin_amdgcn_mfma_f32_16x16x32_bf16(Bt[n][k], At[m][k], acc[ai][bj][m][n], 0, 0, 0); __builtin_amdgcn_s_setprio(0); } while (0)
; #define PG8_WAIT_V(n) asm volatile("s_waitcnt vmcnt(" #n ")" ::: "memory")
; #define PG8_BAR __builtin_amdgcn_s_barrier()
; template <class Epi, class Sched, bool ALIGN_EPI = false, bool SP2 = false>
; __device__ __forceinline__ void gemm_phase(PG8_LAS unsigned char* lds, const Gemm g, const Sched& S, const Epi& E) {
;     ...
;         for (int t = 0; t < nt; t += 2) {
;             const bool last = (t == nt - 2);
;             const char* a1 = cA + (size_t)(t + 1) * kstep;
;             const char* a2 = last ? nA : cA + (size_t)(t + 2) * kstep; const char* b2 = last ? nB : cB + (size_t)(t + 2) * kstep;
;             const char* a3 = a2 + kstep; const char* b3 = b2 + kstep;
;             if (last && has_next) S.a_ready(nxt);
;             if constexpr (SP2) {
;             PG8_LDB(B0, 0, 0); PG8_LDB(B1, 0, 1); PG8_SCHED; PG8_LDA(At, 0, 0); PG8_STAGE(PG8_SA(1, 1), a1 + hstep, voffA);
;             PG8_WAIT_V(8); PG8_WAIT_L(0); PG8_BAR; PG8_MMA(0, 0, At, B0); PG8_MMA(0, 1, At, B1); PG8_BAR; PG8_SCHED;
;             PG8_LDA(At, 0, 1); PG8_STAGE(PG8_SB(0, 0), b2, voffB); PG8_STAGE(PG8_SB(0, 1), b2 + hstep, voffB); PG8_STAGE(PG8_SA(0, 0), a2, voffA);
;             PG8_WAIT_V(8); PG8_WAIT_L(0); PG8_BAR; PG8_MMA(1, 0, At, B0); PG8_MMA(1, 1, At, B1); PG8_BAR; PG8_SCHED;
.LBB0_165:
	ds_read_b128 v[150:153], v139
	ds_read_b128 v[154:157], v139 offset:1024
	ds_read_b128 v[158:161], v139 offset:2048
	ds_read_b128 v[162:165], v139 offset:3072
	ds_read_b128 v[166:169], v145
	ds_read_b128 v[170:173], v145 offset:1024
	ds_read_b128 v[174:177], v145 offset:2048
	ds_read_b128 v[178:181], v145 offset:3072
	s_add_u32 s12, s8, s10
	s_addc_u32 s13, s9, s11
	s_add_u32 s12, s12, 0x13500100
	s_addc_u32 s13, s13, 0
	s_add_u32 s39, s24, s10
	s_addc_u32 s40, s25, s11
	s_cmpk_eq_i32 s10, 0x1500
	s_cselect_b32 s15, s5, s13
	s_cselect_b32 s14, s4, s12
	s_cselect_b32 s13, s3, s40
	s_cselect_b32 s12, s2, s39
	s_mov_b32 m0, s27
	v_lshl_add_u64 v[214:215], v[140:141], 0, s[10:11]
	ds_read_b128 v[182:185], v146
	ds_read_b128 v[186:189], v146 offset:1024
	ds_read_b128 v[190:193], v146 offset:2048
	ds_read_b128 v[194:197], v146 offset:3072
	ds_read_b128 v[198:201], v146 offset:4096
	ds_read_b128 v[202:205], v146 offset:5120
	ds_read_b128 v[206:209], v146 offset:6144
	ds_read_b128 v[210:213], v146 offset:7168
	global_load_lds_dwordx4 v[214:215], off
	v_lshl_add_u64 v[214:215], v[142:143], 0, s[10:11]
	s_mov_b32 m0, s28
	s_nop 0
	global_load_lds_dwordx4 v[214:215], off
	s_waitcnt vmcnt(8)
	s_waitcnt lgkmcnt(0)
	s_barrier
	s_setprio 1
	s_waitcnt lgkmcnt(0)
	v_mfma_f32_16x16x32_bf16 v[124:127], v[150:153], v[182:185], v[124:127]
	v_mfma_f32_16x16x32_bf16 v[120:123], v[158:161], v[182:185], v[120:123]
	v_mfma_f32_16x16x32_bf16 v[116:119], v[150:153], v[190:193], v[116:119]
	v_mfma_f32_16x16x32_bf16 v[112:115], v[158:161], v[190:193], v[112:115]
	v_mfma_f32_16x16x32_bf16 v[108:111], v[150:153], v[198:201], v[108:111]
	v_mfma_f32_16x16x32_bf16 v[104:107], v[158:161], v[198:201], v[104:107]
	v_mfma_f32_16x16x32_bf16 v[96:99], v[150:153], v[206:209], v[96:99]
	v_mfma_f32_16x16x32_bf16 v[88:91], v[158:161], v[206:209], v[88:91]
	v_mfma_f32_16x16x32_bf16 v[124:127], v[154:157], v[186:189], v[124:127]
	v_mfma_f32_16x16x32_bf16 v[120:123], v[162:165], v[186:189], v[120:123]
	v_mfma_f32_16x16x32_bf16 v[116:119], v[154:157], v[194:197], v[116:119]
	v_mfma_f32_16x16x32_bf16 v[112:115], v[162:165], v[194:197], v[112:115]
	v_mfma_f32_16x16x32_bf16 v[108:111], v[154:157], v[202:205], v[108:111]
	v_mfma_f32_16x16x32_bf16 v[104:107], v[162:165], v[202:205], v[104:107]
	v_mfma_f32_16x16x32_bf16 v[96:99], v[154:157], v[210:213], v[96:99]
	v_mfma_f32_16x16x32_bf16 v[88:91], v[162:165], v[210:213], v[88:91]
	s_setprio 0
	s_setprio 1
	v_mfma_f32_16x16x32_bf16 v[100:103], v[166:169], v[182:185], v[100:103]
	v_mfma_f32_16x16x32_bf16 v[92:95], v[174:177], v[182:185], v[92:95]
	v_mfma_f32_16x16x32_bf16 v[84:87], v[166:169], v[190:193], v[84:87]
	v_mfma_f32_16x16x32_bf16 v[80:83], v[174:177], v[190:193], v[80:83]
	v_mfma_f32_16x16x32_bf16 v[76:79], v[166:169], v[198:201], v[76:79]
	v_mfma_f32_16x16x32_bf16 v[72:75], v[174:177], v[198:201], v[72:75]
	v_mfma_f32_16x16x32_bf16 v[68:71], v[166:169], v[206:209], v[68:71]
	v_mfma_f32_16x16x32_bf16 v[64:67], v[174:177], v[206:209], v[64:67]
	v_mfma_f32_16x16x32_bf16 v[100:103], v[170:173], v[186:189], v[100:103]
	v_mfma_f32_16x16x32_bf16 v[92:95], v[178:181], v[186:189], v[92:95]
	v_mfma_f32_16x16x32_bf16 v[84:87], v[170:173], v[194:197], v[84:87]
	v_mfma_f32_16x16x32_bf16 v[80:83], v[178:181], v[194:197], v[80:83]
	v_mfma_f32_16x16x32_bf16 v[76:79], v[170:173], v[202:205], v[76:79]
	v_mfma_f32_16x16x32_bf16 v[72:75], v[178:181], v[202:205], v[72:75]
	s_setprio 2
	s_barrier
	v_mfma_f32_16x16x32_bf16 v[68:71], v[170:173], v[210:213], v[68:71]
	v_mfma_f32_16x16x32_bf16 v[64:67], v[178:181], v[210:213], v[64:67]
	s_setprio 0
	s_mov_b32 m0, s29
	v_lshl_add_u64 v[214:215], s[12:13], 0, v[132:133]
	s_add_u32 s40, s12, 0x160000
	ds_read_b128 v[182:185], v146 offset:16384
	ds_read_b128 v[186:189], v146 offset:17408
	ds_read_b128 v[190:193], v146 offset:18432
	ds_read_b128 v[194:197], v146 offset:19456
	ds_read_b128 v[198:201], v146 offset:20480
	ds_read_b128 v[202:205], v146 offset:21504
	ds_read_b128 v[206:209], v146 offset:22528
	ds_read_b128 v[210:213], v146 offset:23552
	global_load_lds_dwordx4 v[214:215], off
	v_lshl_add_u64 v[216:217], s[12:13], 0, v[136:137]
	s_mov_b32 m0, s30
	s_addc_u32 s41, s13, 0
	global_load_lds_dwordx4 v[216:217], off
	v_lshl_add_u64 v[218:219], s[40:41], 0, v[132:133]
	s_mov_b32 m0, s31
	v_lshl_add_u64 v[220:221], s[14:15], 0, v[134:135]
	global_load_lds_dwordx4 v[218:219], off
	v_lshl_add_u64 v[218:219], s[40:41], 0, v[136:137]
	s_mov_b32 m0, s34
	s_nop 0
	global_load_lds_dwordx4 v[218:219], off
	v_lshl_add_u64 v[218:219], s[14:15], 0, v[130:131]
	s_mov_b32 m0, s17
	s_nop 0
	global_load_lds_dwordx4 v[218:219], off
	s_mov_b32 m0, s18
	s_nop 0
	global_load_lds_dwordx4 v[220:221], off
	s_waitcnt vmcnt(8)
	s_waitcnt lgkmcnt(0)
	s_barrier
; #define PG8_STAGE(bufoff, gbase, voff) do { _Pragma("unroll") for (int _i = 0; _i < 2; ++_i) \
;         __builtin_amdgcn_global_load_lds((const unsigned*)((const char*)(gbase) + (voff)[_i]), (PG8_LAS unsigned*)(lds + (bufoff) + ldsw + _i * 8192), 16, 0, 0); } while (0)
; #define PG8_LDA(dst, b, h) do { _Pragma("unroll") for (int m = 0; m < 4; ++m) _Pragma("unroll") for (int k = 0; k < 2; ++k) dst[m][k] = *(const PG8_LAS bf16x8*)(lds + PG8_SA(b, h) + aoff + m * 2048 + k * 1024); } while (0)
; #define PG8_LDB(dst, b, h) do { _Pragma("unroll") for (int n = 0; n < 2; ++n) _Pragma("unroll") for (int k = 0; k < 2; ++k) dst[n][k] = *(const PG8_LAS bf16x8*)(lds + PG8_SB(b, h) + boff + n * 2048 + k * 1024); } while (0)
; #define PG8_MMA(ai, bj, At, Bt) do { __builtin_amdgcn_s_setprio(1); _Pragma("unroll") for (int m = 0; m < 4; ++m) _Pragma("unroll") for (int n = 0; n < 2; ++n) _Pragma("unroll") for (int k = 0; k < 2; ++k) \
;         acc[ai][bj][m][n] = __builtin_amdgcn_mfma_f32_16x16x32_bf16(Bt[n][k], At[m][k], acc[ai][bj][m][n], 0, 0, 0); __builtin_amdgcn_s_setprio(0); } while (0)
; #define PG8_WAIT_V(n) asm volatile("s_waitcnt vmcnt(" #n ")" ::: "memory")
; #define PG8_WAIT_L(n) asm volatile("s_waitcnt lgkmcnt(" #n ")" ::: "memory")
; #define PG8_BAR __builtin_amdgcn_s_barrier()
; #define PG8_SCHED __builtin_amdgcn_sched_barrier(0)
; template <class Epi, class Sched, bool ALIGN_EPI = false, bool SP2 = false>
; __device__ __forceinline__ void gemm_phase(PG8_LAS unsigned char* lds, const Gemm g, const Sched& S, const Epi& E) {
;     ...
;             PG8_WAIT_V(8); PG8_WAIT_L(0); PG8_BAR; PG8_MMA(1, 0, At, B0); PG8_MMA(1, 1, At, B1); PG8_BAR; PG8_SCHED;
;             PG8_LDB(B0, 1, 0); PG8_LDB(B1, 1, 1); PG8_SCHED; PG8_LDA(At, 1, 0); PG8_STAGE(PG8_SA(0, 1), a2 + hstep, voffA);
;             PG8_WAIT_V(8); PG8_WAIT_L(0); PG8_BAR; PG8_MMA(0, 0, At, B0); PG8_MMA(0, 1, At, B1); PG8_BAR; PG8_SCHED;
	s_setprio 1
	s_waitcnt lgkmcnt(0)
	v_mfma_f32_16x16x32_bf16 v[60:63], v[150:153], v[182:185], v[60:63]
	v_mfma_f32_16x16x32_bf16 v[56:59], v[158:161], v[182:185], v[56:59]
	v_mfma_f32_16x16x32_bf16 v[52:55], v[150:153], v[190:193], v[52:55]
	v_mfma_f32_16x16x32_bf16 v[48:51], v[158:161], v[190:193], v[48:51]
	v_mfma_f32_16x16x32_bf16 v[44:47], v[150:153], v[198:201], v[44:47]
	v_mfma_f32_16x16x32_bf16 v[40:43], v[158:161], v[198:201], v[40:43]
	v_mfma_f32_16x16x32_bf16 v[32:35], v[150:153], v[206:209], v[32:35]
	v_mfma_f32_16x16x32_bf16 v[24:27], v[158:161], v[206:209], v[24:27]
	v_mfma_f32_16x16x32_bf16 v[60:63], v[154:157], v[186:189], v[60:63]
	v_mfma_f32_16x16x32_bf16 v[56:59], v[162:165], v[186:189], v[56:59]
	v_mfma_f32_16x16x32_bf16 v[52:55], v[154:157], v[194:197], v[52:55]
	v_mfma_f32_16x16x32_bf16 v[48:51], v[162:165], v[194:197], v[48:51]
	v_mfma_f32_16x16x32_bf16 v[44:47], v[154:157], v[202:205], v[44:47]
	v_mfma_f32_16x16x32_bf16 v[40:43], v[162:165], v[202:205], v[40:43]
	v_mfma_f32_16x16x32_bf16 v[32:35], v[154:157], v[210:213], v[32:35]
	v_mfma_f32_16x16x32_bf16 v[24:27], v[162:165], v[210:213], v[24:27]
	s_setprio 0
	s_setprio 1
	v_mfma_f32_16x16x32_bf16 v[36:39], v[166:169], v[182:185], v[36:39]
	v_mfma_f32_16x16x32_bf16 v[28:31], v[174:177], v[182:185], v[28:31]
	v_mfma_f32_16x16x32_bf16 v[20:23], v[166:169], v[190:193], v[20:23]
	v_mfma_f32_16x16x32_bf16 v[16:19], v[174:177], v[190:193], v[16:19]
	v_mfma_f32_16x16x32_bf16 v[12:15], v[166:169], v[198:201], v[12:15]
	v_mfma_f32_16x16x32_bf16 v[8:11], v[174:177], v[198:201], v[8:11]
	v_mfma_f32_16x16x32_bf16 v[4:7], v[166:169], v[206:209], v[4:7]
	v_mfma_f32_16x16x32_bf16 v[0:3], v[174:177], v[206:209], v[0:3]
	v_mfma_f32_16x16x32_bf16 v[36:39], v[170:173], v[186:189], v[36:39]
	v_mfma_f32_16x16x32_bf16 v[28:31], v[178:181], v[186:189], v[28:31]
	v_mfma_f32_16x16x32_bf16 v[20:23], v[170:173], v[194:197], v[20:23]
	v_mfma_f32_16x16x32_bf16 v[16:19], v[178:181], v[194:197], v[16:19]
	v_mfma_f32_16x16x32_bf16 v[12:15], v[170:173], v[202:205], v[12:15]
	v_mfma_f32_16x16x32_bf16 v[8:11], v[178:181], v[202:205], v[8:11]
	s_setprio 2
	s_barrier
	v_mfma_f32_16x16x32_bf16 v[4:7], v[170:173], v[210:213], v[4:7]
	v_mfma_f32_16x16x32_bf16 v[0:3], v[178:181], v[210:213], v[0:3]
	s_setprio 0
	ds_read_b128 v[150:153], v147
	ds_read_b128 v[154:157], v147 offset:1024
	ds_read_b128 v[158:161], v147 offset:2048
	ds_read_b128 v[162:165], v147 offset:3072
	ds_read_b128 v[166:169], v148
	ds_read_b128 v[170:173], v148 offset:1024
	ds_read_b128 v[174:177], v148 offset:2048
	ds_read_b128 v[178:181], v148 offset:3072
	s_add_u32 s14, s14, 0x160000
	s_addc_u32 s15, s15, 0
	s_mov_b32 m0, s19
	v_lshl_add_u64 v[222:223], s[14:15], 0, v[130:131]
	ds_read_b128 v[182:185], v146 offset:32768
	ds_read_b128 v[186:189], v146 offset:33792
	ds_read_b128 v[190:193], v146 offset:34816
	ds_read_b128 v[194:197], v146 offset:35840
	ds_read_b128 v[198:201], v146 offset:36864
	ds_read_b128 v[202:205], v146 offset:37888
	ds_read_b128 v[206:209], v146 offset:38912
	ds_read_b128 v[210:213], v146 offset:39936
	global_load_lds_dwordx4 v[222:223], off
	v_lshl_add_u64 v[222:223], s[14:15], 0, v[134:135]
	s_mov_b32 m0, s20
	s_nop 0
	global_load_lds_dwordx4 v[222:223], off
	s_waitcnt vmcnt(8)
	s_waitcnt lgkmcnt(0)
	s_barrier
	s_setprio 1
	s_waitcnt lgkmcnt(0)
	v_mfma_f32_16x16x32_bf16 v[124:127], v[150:153], v[182:185], v[124:127]
	v_mfma_f32_16x16x32_bf16 v[120:123], v[158:161], v[182:185], v[120:123]
	v_mfma_f32_16x16x32_bf16 v[116:119], v[150:153], v[190:193], v[116:119]
	v_mfma_f32_16x16x32_bf16 v[112:115], v[158:161], v[190:193], v[112:115]
	v_mfma_f32_16x16x32_bf16 v[108:111], v[150:153], v[198:201], v[108:111]
	v_mfma_f32_16x16x32_bf16 v[104:107], v[158:161], v[198:201], v[104:107]
	v_mfma_f32_16x16x32_bf16 v[96:99], v[150:153], v[206:209], v[96:99]
	v_mfma_f32_16x16x32_bf16 v[88:91], v[158:161], v[206:209], v[88:91]
	v_mfma_f32_16x16x32_bf16 v[124:127], v[154:157], v[186:189], v[124:127]
	v_mfma_f32_16x16x32_bf16 v[120:123], v[162:165], v[186:189], v[120:123]
	v_mfma_f32_16x16x32_bf16 v[116:119], v[154:157], v[194:197], v[116:119]
	v_mfma_f32_16x16x32_bf16 v[112:115], v[162:165], v[194:197], v[112:115]
	v_mfma_f32_16x16x32_bf16 v[108:111], v[154:157], v[202:205], v[108:111]
	v_mfma_f32_16x16x32_bf16 v[104:107], v[162:165], v[202:205], v[104:107]
	v_mfma_f32_16x16x32_bf16 v[96:99], v[154:157], v[210:213], v[96:99]
	v_mfma_f32_16x16x32_bf16 v[88:91], v[162:165], v[210:213], v[88:91]
	s_setprio 0
	s_setprio 1
	v_mfma_f32_16x16x32_bf16 v[100:103], v[166:169], v[182:185], v[100:103]
	v_mfma_f32_16x16x32_bf16 v[92:95], v[174:177], v[182:185], v[92:95]
	v_mfma_f32_16x16x32_bf16 v[84:87], v[166:169], v[190:193], v[84:87]
	v_mfma_f32_16x16x32_bf16 v[80:83], v[174:177], v[190:193], v[80:83]
	v_mfma_f32_16x16x32_bf16 v[76:79], v[166:169], v[198:201], v[76:79]
	v_mfma_f32_16x16x32_bf16 v[72:75], v[174:177], v[198:201], v[72:75]
	v_mfma_f32_16x16x32_bf16 v[68:71], v[166:169], v[206:209], v[68:71]
	v_mfma_f32_16x16x32_bf16 v[64:67], v[174:177], v[206:209], v[64:67]
	v_mfma_f32_16x16x32_bf16 v[100:103], v[170:173], v[186:189], v[100:103]
	v_mfma_f32_16x16x32_bf16 v[92:95], v[178:181], v[186:189], v[92:95]
	v_mfma_f32_16x16x32_bf16 v[84:87], v[170:173], v[194:197], v[84:87]
	v_mfma_f32_16x16x32_bf16 v[80:83], v[178:181], v[194:197], v[80:83]
	v_mfma_f32_16x16x32_bf16 v[76:79], v[170:173], v[202:205], v[76:79]
	v_mfma_f32_16x16x32_bf16 v[72:75], v[178:181], v[202:205], v[72:75]
	s_setprio 2
	s_barrier
; #define PG8_STAGE(bufoff, gbase, voff) do { _Pragma("unroll") for (int _i = 0; _i < 2; ++_i) \
;         __builtin_amdgcn_global_load_lds((const unsigned*)((const char*)(gbase) + (voff)[_i]), (PG8_LAS unsigned*)(lds + (bufoff) + ldsw + _i * 8192), 16, 0, 0); } while (0)
; #define PG8_LDA(dst, b, h) do { _Pragma("unroll") for (int m = 0; m < 4; ++m) _Pragma("unroll") for (int k = 0; k < 2; ++k) dst[m][k] = *(const PG8_LAS bf16x8*)(lds + PG8_SA(b, h) + aoff + m * 2048 + k * 1024); } while (0)
; #define PG8_MMA(ai, bj, At, Bt) do { __builtin_amdgcn_s_setprio(1); _Pragma("unroll") for (int m = 0; m < 4; ++m) _Pragma("unroll") for (int n = 0; n < 2; ++n) _Pragma("unroll") for (int k = 0; k < 2; ++k) \
;         acc[ai][bj][m][n] = __builtin_amdgcn_mfma_f32_16x16x32_bf16(Bt[n][k], At[m][k], acc[ai][bj][m][n], 0, 0, 0); __builtin_amdgcn_s_setprio(0); } while (0)
; #define PG8_WAIT_V(n) asm volatile("s_waitcnt vmcnt(" #n ")" ::: "memory")
; #define PG8_WAIT_L(n) asm volatile("s_waitcnt lgkmcnt(" #n ")" ::: "memory")
; #define PG8_BAR __builtin_amdgcn_s_barrier()
; #define PG8_SCHED __builtin_amdgcn_sched_barrier(0)
; template <class Epi, class Sched, bool ALIGN_EPI = false, bool SP2 = false>
; __device__ __forceinline__ void gemm_phase(PG8_LAS unsigned char* lds, const Gemm g, const Sched& S, const Epi& E) {
;     ...
;             PG8_WAIT_V(8); PG8_WAIT_L(0); PG8_BAR; PG8_MMA(0, 0, At, B0); PG8_MMA(0, 1, At, B1); PG8_BAR; PG8_SCHED;
;             PG8_LDA(At, 1, 1); PG8_STAGE(PG8_SB(1, 0), b3, voffB); PG8_STAGE(PG8_SB(1, 1), b3 + hstep, voffB); PG8_STAGE(PG8_SA(1, 0), a3, voffA);
;             PG8_WAIT_V(8); PG8_WAIT_L(0); PG8_BAR; PG8_MMA(1, 0, At, B0); PG8_MMA(1, 1, At, B1); PG8_BAR; PG8_SCHED;
;     ...
;         if constexpr (ALIGN_EPI) { if (wr == 0) PG8_BAR; }
	v_mfma_f32_16x16x32_bf16 v[68:71], v[170:173], v[210:213], v[68:71]
	v_mfma_f32_16x16x32_bf16 v[64:67], v[178:181], v[210:213], v[64:67]
	s_setprio 0
	s_mov_b32 m0, s35
	v_lshl_add_u64 v[214:215], v[214:215], 0, s[6:7]
	s_add_u32 s12, s12, 0x160080
	ds_read_b128 v[182:185], v146 offset:49152
	ds_read_b128 v[186:189], v146 offset:50176
	ds_read_b128 v[190:193], v146 offset:51200
	ds_read_b128 v[194:197], v146 offset:52224
	ds_read_b128 v[198:201], v146 offset:53248
	ds_read_b128 v[202:205], v146 offset:54272
	ds_read_b128 v[206:209], v146 offset:55296
	ds_read_b128 v[210:213], v146 offset:56320
	global_load_lds_dwordx4 v[214:215], off
	v_lshl_add_u64 v[214:215], v[216:217], 0, s[6:7]
	s_mov_b32 m0, s36
	s_addc_u32 s13, s13, 0
	global_load_lds_dwordx4 v[214:215], off
	v_lshl_add_u64 v[214:215], s[12:13], 0, v[132:133]
	s_mov_b32 m0, s37
	s_nop 0
	global_load_lds_dwordx4 v[214:215], off
	v_lshl_add_u64 v[214:215], s[12:13], 0, v[136:137]
	s_mov_b32 m0, s38
	s_nop 0
	global_load_lds_dwordx4 v[214:215], off
	v_lshl_add_u64 v[214:215], v[218:219], 0, s[6:7]
	s_mov_b32 m0, s22
	s_nop 0
	global_load_lds_dwordx4 v[214:215], off
	v_lshl_add_u64 v[214:215], v[220:221], 0, s[6:7]
	s_mov_b32 m0, s23
	s_nop 0
	global_load_lds_dwordx4 v[214:215], off
	s_waitcnt vmcnt(8)
	s_waitcnt lgkmcnt(0)
	s_barrier
	s_setprio 1
	s_waitcnt lgkmcnt(0)
	v_mfma_f32_16x16x32_bf16 v[60:63], v[150:153], v[182:185], v[60:63]
	v_mfma_f32_16x16x32_bf16 v[56:59], v[158:161], v[182:185], v[56:59]
	v_mfma_f32_16x16x32_bf16 v[52:55], v[150:153], v[190:193], v[52:55]
	v_mfma_f32_16x16x32_bf16 v[48:51], v[158:161], v[190:193], v[48:51]
	v_mfma_f32_16x16x32_bf16 v[44:47], v[150:153], v[198:201], v[44:47]
	v_mfma_f32_16x16x32_bf16 v[40:43], v[158:161], v[198:201], v[40:43]
	v_mfma_f32_16x16x32_bf16 v[32:35], v[150:153], v[206:209], v[32:35]
	v_mfma_f32_16x16x32_bf16 v[24:27], v[158:161], v[206:209], v[24:27]
	v_mfma_f32_16x16x32_bf16 v[60:63], v[154:157], v[186:189], v[60:63]
	v_mfma_f32_16x16x32_bf16 v[56:59], v[162:165], v[186:189], v[56:59]
	v_mfma_f32_16x16x32_bf16 v[52:55], v[154:157], v[194:197], v[52:55]
	v_mfma_f32_16x16x32_bf16 v[48:51], v[162:165], v[194:197], v[48:51]
	v_mfma_f32_16x16x32_bf16 v[44:47], v[154:157], v[202:205], v[44:47]
	v_mfma_f32_16x16x32_bf16 v[40:43], v[162:165], v[202:205], v[40:43]
	v_mfma_f32_16x16x32_bf16 v[32:35], v[154:157], v[210:213], v[32:35]
	v_mfma_f32_16x16x32_bf16 v[24:27], v[162:165], v[210:213], v[24:27]
	s_setprio 0
	s_setprio 1
	v_mfma_f32_16x16x32_bf16 v[36:39], v[166:169], v[182:185], v[36:39]
	v_mfma_f32_16x16x32_bf16 v[28:31], v[174:177], v[182:185], v[28:31]
	v_mfma_f32_16x16x32_bf16 v[20:23], v[166:169], v[190:193], v[20:23]
	v_mfma_f32_16x16x32_bf16 v[16:19], v[174:177], v[190:193], v[16:19]
	v_mfma_f32_16x16x32_bf16 v[12:15], v[166:169], v[198:201], v[12:15]
	v_mfma_f32_16x16x32_bf16 v[8:11], v[174:177], v[198:201], v[8:11]
	v_mfma_f32_16x16x32_bf16 v[4:7], v[166:169], v[206:209], v[4:7]
	v_mfma_f32_16x16x32_bf16 v[0:3], v[174:177], v[206:209], v[0:3]
	v_mfma_f32_16x16x32_bf16 v[36:39], v[170:173], v[186:189], v[36:39]
	v_mfma_f32_16x16x32_bf16 v[28:31], v[178:181], v[186:189], v[28:31]
	v_mfma_f32_16x16x32_bf16 v[20:23], v[170:173], v[194:197], v[20:23]
	v_mfma_f32_16x16x32_bf16 v[16:19], v[178:181], v[194:197], v[16:19]
	v_mfma_f32_16x16x32_bf16 v[12:15], v[170:173], v[202:205], v[12:15]
	v_mfma_f32_16x16x32_bf16 v[8:11], v[178:181], v[202:205], v[8:11]
	s_setprio 2
	s_barrier
	v_mfma_f32_16x16x32_bf16 v[4:7], v[170:173], v[210:213], v[4:7]
	v_mfma_f32_16x16x32_bf16 v[0:3], v[178:181], v[210:213], v[0:3]
	s_setprio 0
	s_add_i32 s26, s26, 2
	s_add_u32 s10, s10, 0x100
	s_addc_u32 s11, s11, 0
	s_cmp_gt_u32 s26, 41
	s_cbranch_scc0 .LBB0_165
	s_cmpk_lt_u32 s16, 0x100
	s_cbranch_scc0 .LBB0_168
	s_barrier

; #define PG8_STAGE(bufoff, gbase, voff) do { _Pragma("unroll") for (int _i = 0; _i < 2; ++_i) \
;         __builtin_amdgcn_global_load_lds((const unsigned*)((const char*)(gbase) + (voff)[_i]), (PG8_LAS unsigned*)(lds + (bufoff) + ldsw + _i * 8192), 16, 0, 0); } while (0)
; #define PG8_LDA(dst, b, h) do { _Pragma("unroll") for (int m = 0; m < 4; ++m) _Pragma("unroll") for (int k = 0; k < 2; ++k) dst[m][k] = *(const PG8_LAS bf16x8*)(lds + PG8_SA(b, h) + aoff + m * 2048 + k * 1024); } while (0)
; #define PG8_LDB(dst, b, h) do { _Pragma("unroll") for (int n = 0; n < 2; ++n) _Pragma("unroll") for (int k = 0; k < 2; ++k) dst[n][k] = *(const PG8_LAS bf16x8*)(lds + PG8_SB(b, h) + boff + n * 2048 + k * 1024); } while (0)
; #define PG8_MMA(ai, bj, At, Bt) do { __builtin_amdgcn_s_setprio(1); _Pragma("unroll") for (int m = 0; m < 4; ++m) _Pragma("unroll") for (int n = 0; n < 2; ++n) _Pragma("unroll") for (int k = 0; k < 2; ++k) \
;         acc[ai][bj][m][n] = __builtin_amdgcn_mfma_f32_16x16x32_bf16(Bt[n][k], At[m][k], acc[ai][bj][m][n], 0, 0, 0); __builtin_amdgcn_s_setprio(0); } while (0)
; #define PG8_WAIT_V(n) asm volatile("s_waitcnt vmcnt(" #n ")" ::: "memory")
; #define PG8_BAR __builtin_amdgcn_s_barrier()
; template <class Epi, class Sched, bool ALIGN_EPI = false, bool SP2 = false>
; __device__ __forceinline__ void gemm_phase(PG8_LAS unsigned char* lds, const Gemm g, const Sched& S, const Epi& E) {
;     ...
;         for (int t = 0; t < nt; t += 2) {
;             const bool last = (t == nt - 2);
;             const char* a1 = cA + (size_t)(t + 1) * kstep;
;             const char* a2 = last ? nA : cA + (size_t)(t + 2) * kstep; const char* b2 = last ? nB : cB + (size_t)(t + 2) * kstep;
;             const char* a3 = a2 + kstep; const char* b3 = b2 + kstep;
;             if (last && has_next) S.a_ready(nxt);
;             if constexpr (SP2) {
;             PG8_LDB(B0, 0, 0); PG8_LDB(B1, 0, 1); PG8_SCHED; PG8_LDA(At, 0, 0); PG8_STAGE(PG8_SA(1, 1), a1 + hstep, voffA);
;             PG8_WAIT_V(8); PG8_WAIT_L(0); PG8_BAR; PG8_MMA(0, 0, At, B0); PG8_MMA(0, 1, At, B1); PG8_BAR; PG8_SCHED;
;             PG8_LDA(At, 0, 1); PG8_STAGE(PG8_SB(0, 0), b2, voffB); PG8_STAGE(PG8_SB(0, 1), b2 + hstep, voffB); PG8_STAGE(PG8_SA(0, 0), a2, voffA);
;             PG8_WAIT_V(8); PG8_WAIT_L(0); PG8_BAR; PG8_MMA(1, 0, At, B0); PG8_MMA(1, 1, At, B1); PG8_BAR; PG8_SCHED;
.LBB0_356:
	ds_read_b128 v[152:155], v149
	ds_read_b128 v[156:159], v149 offset:1024
	ds_read_b128 v[160:163], v149 offset:2048
	ds_read_b128 v[164:167], v149 offset:3072
	ds_read_b128 v[168:171], v150
	ds_read_b128 v[172:175], v150 offset:1024
	ds_read_b128 v[176:179], v150 offset:2048
	ds_read_b128 v[180:183], v150 offset:3072
	s_add_u32 s22, s20, 0xfff80080
	s_addc_u32 s23, s21, -1
	s_cmp_eq_u32 s49, 28
	s_cselect_b32 s25, s15, s23
	s_cselect_b32 s24, s43, s22
	s_cselect_b32 s23, s13, s48
	s_cselect_b32 s22, s44, s45
	v_lshl_add_u64 v[216:217], s[20:21], 0, v[138:139]
	s_add_i32 m0, s11, 0xc000
	ds_read_b128 v[184:187], v151
	ds_read_b128 v[188:191], v151 offset:1024
	ds_read_b128 v[192:195], v151 offset:2048
	ds_read_b128 v[196:199], v151 offset:3072
	ds_read_b128 v[200:203], v151 offset:4096
	ds_read_b128 v[204:207], v151 offset:5120
	ds_read_b128 v[208:211], v151 offset:6144
	ds_read_b128 v[212:215], v151 offset:7168
	global_load_lds_dwordx4 v[216:217], off
	v_lshl_add_u64 v[216:217], s[20:21], 0, v[140:141]
	s_add_i32 m0, s11, 0xe000
	s_nop 0
	global_load_lds_dwordx4 v[216:217], off
	s_waitcnt vmcnt(8)
	s_waitcnt lgkmcnt(0)
	s_barrier
	s_setprio 1
	s_waitcnt lgkmcnt(0)
	v_mfma_f32_16x16x32_bf16 v[124:127], v[152:155], v[184:187], v[124:127]
	v_mfma_f32_16x16x32_bf16 v[120:123], v[160:163], v[184:187], v[120:123]
	v_mfma_f32_16x16x32_bf16 v[116:119], v[152:155], v[192:195], v[116:119]
	v_mfma_f32_16x16x32_bf16 v[112:115], v[160:163], v[192:195], v[112:115]
	v_mfma_f32_16x16x32_bf16 v[100:103], v[152:155], v[200:203], v[100:103]
	v_mfma_f32_16x16x32_bf16 v[96:99], v[160:163], v[200:203], v[96:99]
	v_mfma_f32_16x16x32_bf16 v[84:87], v[152:155], v[208:211], v[84:87]
	v_mfma_f32_16x16x32_bf16 v[80:83], v[160:163], v[208:211], v[80:83]
	v_mfma_f32_16x16x32_bf16 v[124:127], v[156:159], v[188:191], v[124:127]
	v_mfma_f32_16x16x32_bf16 v[120:123], v[164:167], v[188:191], v[120:123]
	v_mfma_f32_16x16x32_bf16 v[116:119], v[156:159], v[196:199], v[116:119]
	v_mfma_f32_16x16x32_bf16 v[112:115], v[164:167], v[196:199], v[112:115]
	v_mfma_f32_16x16x32_bf16 v[100:103], v[156:159], v[204:207], v[100:103]
	v_mfma_f32_16x16x32_bf16 v[96:99], v[164:167], v[204:207], v[96:99]
	v_mfma_f32_16x16x32_bf16 v[84:87], v[156:159], v[212:215], v[84:87]
	v_mfma_f32_16x16x32_bf16 v[80:83], v[164:167], v[212:215], v[80:83]
	s_setprio 0
	s_setprio 1
	v_mfma_f32_16x16x32_bf16 v[108:111], v[168:171], v[184:187], v[108:111]
	v_mfma_f32_16x16x32_bf16 v[104:107], v[176:179], v[184:187], v[104:107]
	v_mfma_f32_16x16x32_bf16 v[92:95], v[168:171], v[192:195], v[92:95]
	v_mfma_f32_16x16x32_bf16 v[88:91], v[176:179], v[192:195], v[88:91]
	v_mfma_f32_16x16x32_bf16 v[76:79], v[168:171], v[200:203], v[76:79]
	v_mfma_f32_16x16x32_bf16 v[72:75], v[176:179], v[200:203], v[72:75]
	v_mfma_f32_16x16x32_bf16 v[68:71], v[168:171], v[208:211], v[68:71]
	v_mfma_f32_16x16x32_bf16 v[64:67], v[176:179], v[208:211], v[64:67]
	v_mfma_f32_16x16x32_bf16 v[108:111], v[172:175], v[188:191], v[108:111]
	v_mfma_f32_16x16x32_bf16 v[104:107], v[180:183], v[188:191], v[104:107]
	v_mfma_f32_16x16x32_bf16 v[92:95], v[172:175], v[196:199], v[92:95]
	v_mfma_f32_16x16x32_bf16 v[88:91], v[180:183], v[196:199], v[88:91]
	v_mfma_f32_16x16x32_bf16 v[76:79], v[172:175], v[204:207], v[76:79]
	v_mfma_f32_16x16x32_bf16 v[72:75], v[180:183], v[204:207], v[72:75]
	s_setprio 2
	s_barrier
	v_mfma_f32_16x16x32_bf16 v[68:71], v[172:175], v[212:215], v[68:71]
	v_mfma_f32_16x16x32_bf16 v[64:67], v[180:183], v[212:215], v[64:67]
	s_setprio 0
	s_add_i32 s50, s39, s26
	v_lshl_add_u64 v[216:217], s[22:23], 0, v[134:135]
	s_mov_b32 m0, s50
	ds_read_b128 v[184:187], v151 offset:16384
	ds_read_b128 v[188:191], v151 offset:17408
	ds_read_b128 v[192:195], v151 offset:18432
	ds_read_b128 v[196:199], v151 offset:19456
	ds_read_b128 v[200:203], v151 offset:20480
	ds_read_b128 v[204:207], v151 offset:21504
	ds_read_b128 v[208:211], v151 offset:22528
	ds_read_b128 v[212:215], v151 offset:23552
	global_load_lds_dwordx4 v[216:217], off
	s_add_i32 m0, s50, 0x2000
	s_add_u32 s50, s22, 0x80000
	v_lshl_add_u64 v[218:219], s[22:23], 0, v[130:131]
	s_addc_u32 s51, s23, 0
	s_add_i32 s52, s40, s26
	global_load_lds_dwordx4 v[218:219], off
	v_lshl_add_u64 v[220:221], s[50:51], 0, v[134:135]
	s_mov_b32 m0, s52
	v_lshl_add_u64 v[222:223], s[24:25], 0, v[132:133]
	global_load_lds_dwordx4 v[220:221], off
	v_lshl_add_u64 v[220:221], s[50:51], 0, v[130:131]
	s_add_i32 m0, s52, 0x2000
	s_nop 0
	global_load_lds_dwordx4 v[220:221], off
	v_lshl_add_u64 v[220:221], s[24:25], 0, v[136:137]
	s_mov_b32 m0, s11
	s_nop 0
	global_load_lds_dwordx4 v[220:221], off
	s_mov_b32 m0, s29
	s_nop 0
	global_load_lds_dwordx4 v[222:223], off
	s_waitcnt vmcnt(8)
	s_waitcnt lgkmcnt(0)
	s_barrier
; #define PG8_STAGE(bufoff, gbase, voff) do { _Pragma("unroll") for (int _i = 0; _i < 2; ++_i) \
;         __builtin_amdgcn_global_load_lds((const unsigned*)((const char*)(gbase) + (voff)[_i]), (PG8_LAS unsigned*)(lds + (bufoff) + ldsw + _i * 8192), 16, 0, 0); } while (0)
; #define PG8_LDA(dst, b, h) do { _Pragma("unroll") for (int m = 0; m < 4; ++m) _Pragma("unroll") for (int k = 0; k < 2; ++k) dst[m][k] = *(const PG8_LAS bf16x8*)(lds + PG8_SA(b, h) + aoff + m * 2048 + k * 1024); } while (0)
; #define PG8_LDB(dst, b, h) do { _Pragma("unroll") for (int n = 0; n < 2; ++n) _Pragma("unroll") for (int k = 0; k < 2; ++k) dst[n][k] = *(const PG8_LAS bf16x8*)(lds + PG8_SB(b, h) + boff + n * 2048 + k * 1024); } while (0)
; #define PG8_MMA(ai, bj, At, Bt) do { __builtin_amdgcn_s_setprio(1); _Pragma("unroll") for (int m = 0; m < 4; ++m) _Pragma("unroll") for (int n = 0; n < 2; ++n) _Pragma("unroll") for (int k = 0; k < 2; ++k) \
;         acc[ai][bj][m][n] = __builtin_amdgcn_mfma_f32_16x16x32_bf16(Bt[n][k], At[m][k], acc[ai][bj][m][n], 0, 0, 0); __builtin_amdgcn_s_setprio(0); } while (0)
; #define PG8_WAIT_V(n) asm volatile("s_waitcnt vmcnt(" #n ")" ::: "memory")
; #define PG8_WAIT_L(n) asm volatile("s_waitcnt lgkmcnt(" #n ")" ::: "memory")
; #define PG8_BAR __builtin_amdgcn_s_barrier()
; #define PG8_SCHED __builtin_amdgcn_sched_barrier(0)
; template <class Epi, class Sched, bool ALIGN_EPI = false, bool SP2 = false>
; __device__ __forceinline__ void gemm_phase(PG8_LAS unsigned char* lds, const Gemm g, const Sched& S, const Epi& E) {
;     ...
;             PG8_WAIT_V(8); PG8_WAIT_L(0); PG8_BAR; PG8_MMA(1, 0, At, B0); PG8_MMA(1, 1, At, B1); PG8_BAR; PG8_SCHED;
;             PG8_LDB(B0, 1, 0); PG8_LDB(B1, 1, 1); PG8_SCHED; PG8_LDA(At, 1, 0); PG8_STAGE(PG8_SA(0, 1), a2 + hstep, voffA);
;             PG8_WAIT_V(8); PG8_WAIT_L(0); PG8_BAR; PG8_MMA(0, 0, At, B0); PG8_MMA(0, 1, At, B1); PG8_BAR; PG8_SCHED;
	s_setprio 1
	s_waitcnt lgkmcnt(0)
	v_mfma_f32_16x16x32_bf16 v[60:63], v[152:155], v[184:187], v[60:63]
	v_mfma_f32_16x16x32_bf16 v[56:59], v[160:163], v[184:187], v[56:59]
	v_mfma_f32_16x16x32_bf16 v[52:55], v[152:155], v[192:195], v[52:55]
	v_mfma_f32_16x16x32_bf16 v[48:51], v[160:163], v[192:195], v[48:51]
	v_mfma_f32_16x16x32_bf16 v[36:39], v[152:155], v[200:203], v[36:39]
	v_mfma_f32_16x16x32_bf16 v[32:35], v[160:163], v[200:203], v[32:35]
	v_mfma_f32_16x16x32_bf16 v[20:23], v[152:155], v[208:211], v[20:23]
	v_mfma_f32_16x16x32_bf16 v[16:19], v[160:163], v[208:211], v[16:19]
	v_mfma_f32_16x16x32_bf16 v[60:63], v[156:159], v[188:191], v[60:63]
	v_mfma_f32_16x16x32_bf16 v[56:59], v[164:167], v[188:191], v[56:59]
	v_mfma_f32_16x16x32_bf16 v[52:55], v[156:159], v[196:199], v[52:55]
	v_mfma_f32_16x16x32_bf16 v[48:51], v[164:167], v[196:199], v[48:51]
	v_mfma_f32_16x16x32_bf16 v[36:39], v[156:159], v[204:207], v[36:39]
	v_mfma_f32_16x16x32_bf16 v[32:35], v[164:167], v[204:207], v[32:35]
	v_mfma_f32_16x16x32_bf16 v[20:23], v[156:159], v[212:215], v[20:23]
	v_mfma_f32_16x16x32_bf16 v[16:19], v[164:167], v[212:215], v[16:19]
	s_setprio 0
	s_setprio 1
	v_mfma_f32_16x16x32_bf16 v[44:47], v[168:171], v[184:187], v[44:47]
	v_mfma_f32_16x16x32_bf16 v[40:43], v[176:179], v[184:187], v[40:43]
	v_mfma_f32_16x16x32_bf16 v[28:31], v[168:171], v[192:195], v[28:31]
	v_mfma_f32_16x16x32_bf16 v[24:27], v[176:179], v[192:195], v[24:27]
	v_mfma_f32_16x16x32_bf16 v[12:15], v[168:171], v[200:203], v[12:15]
	v_mfma_f32_16x16x32_bf16 v[8:11], v[176:179], v[200:203], v[8:11]
	v_mfma_f32_16x16x32_bf16 v[4:7], v[168:171], v[208:211], v[4:7]
	v_mfma_f32_16x16x32_bf16 v[0:3], v[176:179], v[208:211], v[0:3]
	v_mfma_f32_16x16x32_bf16 v[44:47], v[172:175], v[188:191], v[44:47]
	v_mfma_f32_16x16x32_bf16 v[40:43], v[180:183], v[188:191], v[40:43]
	v_mfma_f32_16x16x32_bf16 v[28:31], v[172:175], v[196:199], v[28:31]
	v_mfma_f32_16x16x32_bf16 v[24:27], v[180:183], v[196:199], v[24:27]
	v_mfma_f32_16x16x32_bf16 v[12:15], v[172:175], v[204:207], v[12:15]
	v_mfma_f32_16x16x32_bf16 v[8:11], v[180:183], v[204:207], v[8:11]
	s_setprio 2
	s_barrier
	v_mfma_f32_16x16x32_bf16 v[4:7], v[172:175], v[212:215], v[4:7]
	v_mfma_f32_16x16x32_bf16 v[0:3], v[180:183], v[212:215], v[0:3]
	s_setprio 0
	s_add_i32 s50, 0, 0x18000
	s_add_i32 s51, 0, 0x1c000
	v_add_u32_e32 v164, s50, v147
	v_add_u32_e32 v180, s51, v147
	ds_read_b128 v[152:155], v164
	ds_read_b128 v[156:159], v164 offset:1024
	ds_read_b128 v[160:163], v164 offset:2048
	ds_read_b128 v[164:167], v164 offset:3072
	ds_read_b128 v[168:171], v180
	ds_read_b128 v[172:175], v180 offset:1024
	ds_read_b128 v[176:179], v180 offset:2048
	ds_read_b128 v[180:183], v180 offset:3072
	s_add_u32 s24, s24, 0x80000
	s_addc_u32 s25, s25, 0
	s_mov_b32 m0, s30
	v_lshl_add_u64 v[224:225], s[24:25], 0, v[136:137]
	ds_read_b128 v[184:187], v151 offset:32768
	ds_read_b128 v[188:191], v151 offset:33792
	ds_read_b128 v[192:195], v151 offset:34816
	ds_read_b128 v[196:199], v151 offset:35840
	ds_read_b128 v[200:203], v151 offset:36864
	ds_read_b128 v[204:207], v151 offset:37888
	ds_read_b128 v[208:211], v151 offset:38912
	ds_read_b128 v[212:215], v151 offset:39936
	global_load_lds_dwordx4 v[224:225], off
	v_lshl_add_u64 v[224:225], s[24:25], 0, v[132:133]
	s_mov_b32 m0, s31
	s_nop 0
	global_load_lds_dwordx4 v[224:225], off
	s_waitcnt vmcnt(8)
	s_waitcnt lgkmcnt(0)
	s_barrier
	s_setprio 1
	s_waitcnt lgkmcnt(0)
	v_mfma_f32_16x16x32_bf16 v[124:127], v[152:155], v[184:187], v[124:127]
	v_mfma_f32_16x16x32_bf16 v[120:123], v[160:163], v[184:187], v[120:123]
	v_mfma_f32_16x16x32_bf16 v[116:119], v[152:155], v[192:195], v[116:119]
	v_mfma_f32_16x16x32_bf16 v[112:115], v[160:163], v[192:195], v[112:115]
	v_mfma_f32_16x16x32_bf16 v[100:103], v[152:155], v[200:203], v[100:103]
	v_mfma_f32_16x16x32_bf16 v[96:99], v[160:163], v[200:203], v[96:99]
	v_mfma_f32_16x16x32_bf16 v[84:87], v[152:155], v[208:211], v[84:87]
	v_mfma_f32_16x16x32_bf16 v[80:83], v[160:163], v[208:211], v[80:83]
	v_mfma_f32_16x16x32_bf16 v[124:127], v[156:159], v[188:191], v[124:127]
	v_mfma_f32_16x16x32_bf16 v[120:123], v[164:167], v[188:191], v[120:123]
	v_mfma_f32_16x16x32_bf16 v[116:119], v[156:159], v[196:199], v[116:119]
	v_mfma_f32_16x16x32_bf16 v[112:115], v[164:167], v[196:199], v[112:115]
	v_mfma_f32_16x16x32_bf16 v[100:103], v[156:159], v[204:207], v[100:103]
	v_mfma_f32_16x16x32_bf16 v[96:99], v[164:167], v[204:207], v[96:99]
	v_mfma_f32_16x16x32_bf16 v[84:87], v[156:159], v[212:215], v[84:87]
	v_mfma_f32_16x16x32_bf16 v[80:83], v[164:167], v[212:215], v[80:83]
	s_setprio 0
	s_setprio 1
	v_mfma_f32_16x16x32_bf16 v[108:111], v[168:171], v[184:187], v[108:111]
	v_mfma_f32_16x16x32_bf16 v[104:107], v[176:179], v[184:187], v[104:107]
	v_mfma_f32_16x16x32_bf16 v[92:95], v[168:171], v[192:195], v[92:95]
	v_mfma_f32_16x16x32_bf16 v[88:91], v[176:179], v[192:195], v[88:91]
	v_mfma_f32_16x16x32_bf16 v[76:79], v[168:171], v[200:203], v[76:79]
	v_mfma_f32_16x16x32_bf16 v[72:75], v[176:179], v[200:203], v[72:75]
	v_mfma_f32_16x16x32_bf16 v[68:71], v[168:171], v[208:211], v[68:71]
	v_mfma_f32_16x16x32_bf16 v[64:67], v[176:179], v[208:211], v[64:67]
	v_mfma_f32_16x16x32_bf16 v[108:111], v[172:175], v[188:191], v[108:111]
	v_mfma_f32_16x16x32_bf16 v[104:107], v[180:183], v[188:191], v[104:107]
	v_mfma_f32_16x16x32_bf16 v[92:95], v[172:175], v[196:199], v[92:95]
	v_mfma_f32_16x16x32_bf16 v[88:91], v[180:183], v[196:199], v[88:91]
	v_mfma_f32_16x16x32_bf16 v[76:79], v[172:175], v[204:207], v[76:79]
	v_mfma_f32_16x16x32_bf16 v[72:75], v[180:183], v[204:207], v[72:75]
	s_setprio 2
	s_barrier
; #define PG8_STAGE(bufoff, gbase, voff) do { _Pragma("unroll") for (int _i = 0; _i < 2; ++_i) \
;         __builtin_amdgcn_global_load_lds((const unsigned*)((const char*)(gbase) + (voff)[_i]), (PG8_LAS unsigned*)(lds + (bufoff) + ldsw + _i * 8192), 16, 0, 0); } while (0)
; #define PG8_LDA(dst, b, h) do { _Pragma("unroll") for (int m = 0; m < 4; ++m) _Pragma("unroll") for (int k = 0; k < 2; ++k) dst[m][k] = *(const PG8_LAS bf16x8*)(lds + PG8_SA(b, h) + aoff + m * 2048 + k * 1024); } while (0)
; #define PG8_MMA(ai, bj, At, Bt) do { __builtin_amdgcn_s_setprio(1); _Pragma("unroll") for (int m = 0; m < 4; ++m) _Pragma("unroll") for (int n = 0; n < 2; ++n) _Pragma("unroll") for (int k = 0; k < 2; ++k) \
;         acc[ai][bj][m][n] = __builtin_amdgcn_mfma_f32_16x16x32_bf16(Bt[n][k], At[m][k], acc[ai][bj][m][n], 0, 0, 0); __builtin_amdgcn_s_setprio(0); } while (0)
; #define PG8_WAIT_V(n) asm volatile("s_waitcnt vmcnt(" #n ")" ::: "memory")
; #define PG8_WAIT_L(n) asm volatile("s_waitcnt lgkmcnt(" #n ")" ::: "memory")
; #define PG8_BAR __builtin_amdgcn_s_barrier()
; #define PG8_SCHED __builtin_amdgcn_sched_barrier(0)
; template <class Epi, class Sched, bool ALIGN_EPI = false, bool SP2 = false>
; __device__ __forceinline__ void gemm_phase(PG8_LAS unsigned char* lds, const Gemm g, const Sched& S, const Epi& E) {
;     ...
;             PG8_WAIT_V(8); PG8_WAIT_L(0); PG8_BAR; PG8_MMA(0, 0, At, B0); PG8_MMA(0, 1, At, B1); PG8_BAR; PG8_SCHED;
;             PG8_LDA(At, 1, 1); PG8_STAGE(PG8_SB(1, 0), b3, voffB); PG8_STAGE(PG8_SB(1, 1), b3 + hstep, voffB); PG8_STAGE(PG8_SA(1, 0), a3, voffA);
;             PG8_WAIT_V(8); PG8_WAIT_L(0); PG8_BAR; PG8_MMA(1, 0, At, B0); PG8_MMA(1, 1, At, B1); PG8_BAR; PG8_SCHED;
;     ...
;         if constexpr (ALIGN_EPI) { if (wr == 0) PG8_BAR; }
	v_mfma_f32_16x16x32_bf16 v[68:71], v[172:175], v[212:215], v[68:71]
	v_mfma_f32_16x16x32_bf16 v[64:67], v[180:183], v[212:215], v[64:67]
	s_setprio 0
	s_add_i32 s24, s50, s26
	v_lshl_add_u64 v[216:217], v[216:217], 0, s[4:5]
	s_mov_b32 m0, s24
	ds_read_b128 v[184:187], v151 offset:49152
	ds_read_b128 v[188:191], v151 offset:50176
	ds_read_b128 v[192:195], v151 offset:51200
	ds_read_b128 v[196:199], v151 offset:52224
	ds_read_b128 v[200:203], v151 offset:53248
	ds_read_b128 v[204:207], v151 offset:54272
	ds_read_b128 v[208:211], v151 offset:55296
	ds_read_b128 v[212:215], v151 offset:56320
	global_load_lds_dwordx4 v[216:217], off
	s_add_i32 m0, s24, 0x2000
	s_add_u32 s22, s22, 0x80080
	v_lshl_add_u64 v[216:217], v[218:219], 0, s[4:5]
	s_addc_u32 s23, s23, 0
	s_add_i32 s24, s51, s26
	global_load_lds_dwordx4 v[216:217], off
	v_lshl_add_u64 v[216:217], s[22:23], 0, v[134:135]
	s_mov_b32 m0, s24
	s_nop 0
	global_load_lds_dwordx4 v[216:217], off
	v_lshl_add_u64 v[216:217], s[22:23], 0, v[130:131]
	s_add_i32 m0, s24, 0x2000
	s_nop 0
	global_load_lds_dwordx4 v[216:217], off
	v_lshl_add_u64 v[216:217], v[220:221], 0, s[4:5]
	s_mov_b32 m0, s35
	s_nop 0
	global_load_lds_dwordx4 v[216:217], off
	v_lshl_add_u64 v[216:217], v[222:223], 0, s[4:5]
	s_mov_b32 m0, s36
	s_nop 0
	global_load_lds_dwordx4 v[216:217], off
	s_waitcnt vmcnt(8)
	s_waitcnt lgkmcnt(0)
	s_barrier
	s_setprio 1
	s_waitcnt lgkmcnt(0)
	v_mfma_f32_16x16x32_bf16 v[60:63], v[152:155], v[184:187], v[60:63]
	v_mfma_f32_16x16x32_bf16 v[56:59], v[160:163], v[184:187], v[56:59]
	v_mfma_f32_16x16x32_bf16 v[52:55], v[152:155], v[192:195], v[52:55]
	v_mfma_f32_16x16x32_bf16 v[48:51], v[160:163], v[192:195], v[48:51]
	v_mfma_f32_16x16x32_bf16 v[36:39], v[152:155], v[200:203], v[36:39]
	v_mfma_f32_16x16x32_bf16 v[32:35], v[160:163], v[200:203], v[32:35]
	v_mfma_f32_16x16x32_bf16 v[20:23], v[152:155], v[208:211], v[20:23]
	v_mfma_f32_16x16x32_bf16 v[16:19], v[160:163], v[208:211], v[16:19]
	v_mfma_f32_16x16x32_bf16 v[60:63], v[156:159], v[188:191], v[60:63]
	v_mfma_f32_16x16x32_bf16 v[56:59], v[164:167], v[188:191], v[56:59]
	v_mfma_f32_16x16x32_bf16 v[52:55], v[156:159], v[196:199], v[52:55]
	v_mfma_f32_16x16x32_bf16 v[48:51], v[164:167], v[196:199], v[48:51]
	v_mfma_f32_16x16x32_bf16 v[36:39], v[156:159], v[204:207], v[36:39]
	v_mfma_f32_16x16x32_bf16 v[32:35], v[164:167], v[204:207], v[32:35]
	v_mfma_f32_16x16x32_bf16 v[20:23], v[156:159], v[212:215], v[20:23]
	v_mfma_f32_16x16x32_bf16 v[16:19], v[164:167], v[212:215], v[16:19]
	s_setprio 0
	s_setprio 1
	v_mfma_f32_16x16x32_bf16 v[44:47], v[168:171], v[184:187], v[44:47]
	v_mfma_f32_16x16x32_bf16 v[40:43], v[176:179], v[184:187], v[40:43]
	v_mfma_f32_16x16x32_bf16 v[28:31], v[168:171], v[192:195], v[28:31]
	v_mfma_f32_16x16x32_bf16 v[24:27], v[176:179], v[192:195], v[24:27]
	v_mfma_f32_16x16x32_bf16 v[12:15], v[168:171], v[200:203], v[12:15]
	v_mfma_f32_16x16x32_bf16 v[8:11], v[176:179], v[200:203], v[8:11]
	v_mfma_f32_16x16x32_bf16 v[4:7], v[168:171], v[208:211], v[4:7]
	v_mfma_f32_16x16x32_bf16 v[0:3], v[176:179], v[208:211], v[0:3]
	v_mfma_f32_16x16x32_bf16 v[44:47], v[172:175], v[188:191], v[44:47]
	v_mfma_f32_16x16x32_bf16 v[40:43], v[180:183], v[188:191], v[40:43]
	v_mfma_f32_16x16x32_bf16 v[28:31], v[172:175], v[196:199], v[28:31]
	v_mfma_f32_16x16x32_bf16 v[24:27], v[180:183], v[196:199], v[24:27]
	v_mfma_f32_16x16x32_bf16 v[12:15], v[172:175], v[204:207], v[12:15]
	v_mfma_f32_16x16x32_bf16 v[8:11], v[180:183], v[204:207], v[8:11]
	s_setprio 2
	s_barrier
	v_mfma_f32_16x16x32_bf16 v[4:7], v[172:175], v[212:215], v[4:7]
	v_mfma_f32_16x16x32_bf16 v[0:3], v[180:183], v[212:215], v[0:3]
	s_setprio 0
	s_add_i32 s49, s49, 2
	s_add_u32 s20, s20, 0x100
	s_addc_u32 s21, s21, 0
	s_add_u32 s45, s45, 0x100
	s_addc_u32 s48, s48, 0
	s_cmp_gt_u32 s49, 29
	s_cbranch_scc0 .LBB0_356
	s_and_b64 vcc, exec, s[8:9]
	s_cbranch_vccz .LBB0_359
	s_barrier

; #define PG8_STAGE(bufoff, gbase, voff) do { _Pragma("unroll") for (int _i = 0; _i < 2; ++_i) \
;         __builtin_amdgcn_global_load_lds((const unsigned*)((const char*)(gbase) + (voff)[_i]), (PG8_LAS unsigned*)(lds + (bufoff) + ldsw + _i * 8192), 16, 0, 0); } while (0)
; #define PG8_LDA(dst, b, h) do { _Pragma("unroll") for (int m = 0; m < 4; ++m) _Pragma("unroll") for (int k = 0; k < 2; ++k) dst[m][k] = *(const PG8_LAS bf16x8*)(lds + PG8_SA(b, h) + aoff + m * 2048 + k * 1024); } while (0)
; #define PG8_LDB(dst, b, h) do { _Pragma("unroll") for (int n = 0; n < 2; ++n) _Pragma("unroll") for (int k = 0; k < 2; ++k) dst[n][k] = *(const PG8_LAS bf16x8*)(lds + PG8_SB(b, h) + boff + n * 2048 + k * 1024); } while (0)
; #define PG8_MMA(ai, bj, At, Bt) do { __builtin_amdgcn_s_setprio(1); _Pragma("unroll") for (int m = 0; m < 4; ++m) _Pragma("unroll") for (int n = 0; n < 2; ++n) _Pragma("unroll") for (int k = 0; k < 2; ++k) \
;         acc[ai][bj][m][n] = __builtin_amdgcn_mfma_f32_16x16x32_bf16(Bt[n][k], At[m][k], acc[ai][bj][m][n], 0, 0, 0); __builtin_amdgcn_s_setprio(0); } while (0)
; #define PG8_WAIT_V(n) asm volatile("s_waitcnt vmcnt(" #n ")" ::: "memory")
; #define PG8_BAR __builtin_amdgcn_s_barrier()
; template <class Epi, class Sched, bool ALIGN_EPI = false, bool SP2 = false>
; __device__ __forceinline__ void gemm_phase(PG8_LAS unsigned char* lds, const Gemm g, const Sched& S, const Epi& E) {
;     ...
;         for (int t = 0; t < nt; t += 2) {
;             const bool last = (t == nt - 2);
;             const char* a1 = cA + (size_t)(t + 1) * kstep;
;             const char* a2 = last ? nA : cA + (size_t)(t + 2) * kstep; const char* b2 = last ? nB : cB + (size_t)(t + 2) * kstep;
;             const char* a3 = a2 + kstep; const char* b3 = b2 + kstep;
;             if (last && has_next) S.a_ready(nxt);
;             if constexpr (SP2) {
;             PG8_LDB(B0, 0, 0); PG8_LDB(B1, 0, 1); PG8_SCHED; PG8_LDA(At, 0, 0); PG8_STAGE(PG8_SA(1, 1), a1 + hstep, voffA);
;             PG8_WAIT_V(8); PG8_WAIT_L(0); PG8_BAR; PG8_MMA(0, 0, At, B0); PG8_MMA(0, 1, At, B1); PG8_BAR; PG8_SCHED;
;             PG8_LDA(At, 0, 1); PG8_STAGE(PG8_SB(0, 0), b2, voffB); PG8_STAGE(PG8_SB(0, 1), b2 + hstep, voffB); PG8_STAGE(PG8_SA(0, 0), a2, voffA);
;             PG8_WAIT_V(8); PG8_WAIT_L(0); PG8_BAR; PG8_MMA(1, 0, At, B0); PG8_MMA(1, 1, At, B1); PG8_BAR; PG8_SCHED;
.LBB0_818:
	ds_read_b128 v[162:165], v158
	ds_read_b128 v[166:169], v158 offset:1024
	ds_read_b128 v[170:173], v158 offset:2048
	ds_read_b128 v[174:177], v158 offset:3072
	ds_read_b128 v[178:181], v159
	ds_read_b128 v[182:185], v159 offset:1024
	ds_read_b128 v[186:189], v159 offset:2048
	ds_read_b128 v[190:193], v159 offset:3072
	s_add_u32 s34, s30, 0xfff80080
	s_addc_u32 s35, s31, -1
	s_cmp_eq_u32 s59, 28
	s_cselect_b32 s37, s23, s35
	s_cselect_b32 s36, s55, s34
	s_cselect_b32 s35, s21, s58
	s_cselect_b32 s34, s56, s57
	v_lshl_add_u64 v[226:227], s[30:31], 0, v[138:139]
	s_add_i32 m0, s25, 0xc000
	ds_read_b128 v[194:197], v160
	ds_read_b128 v[198:201], v160 offset:1024
	ds_read_b128 v[202:205], v160 offset:2048
	ds_read_b128 v[206:209], v160 offset:3072
	ds_read_b128 v[210:213], v160 offset:4096
	ds_read_b128 v[214:217], v160 offset:5120
	ds_read_b128 v[218:221], v160 offset:6144
	ds_read_b128 v[222:225], v160 offset:7168
	global_load_lds_dwordx4 v[226:227], off
	v_lshl_add_u64 v[226:227], s[30:31], 0, v[140:141]
	s_add_i32 m0, s25, 0xe000
	s_nop 0
	global_load_lds_dwordx4 v[226:227], off
	s_waitcnt vmcnt(8)
	s_waitcnt lgkmcnt(0)
	s_barrier
	s_setprio 1
	s_waitcnt lgkmcnt(0)
	v_mfma_f32_16x16x32_bf16 v[124:127], v[162:165], v[194:197], v[124:127]
	v_mfma_f32_16x16x32_bf16 v[120:123], v[170:173], v[194:197], v[120:123]
	v_mfma_f32_16x16x32_bf16 v[116:119], v[162:165], v[202:205], v[116:119]
	v_mfma_f32_16x16x32_bf16 v[112:115], v[170:173], v[202:205], v[112:115]
	v_mfma_f32_16x16x32_bf16 v[100:103], v[162:165], v[210:213], v[100:103]
	v_mfma_f32_16x16x32_bf16 v[96:99], v[170:173], v[210:213], v[96:99]
	v_mfma_f32_16x16x32_bf16 v[84:87], v[162:165], v[218:221], v[84:87]
	v_mfma_f32_16x16x32_bf16 v[80:83], v[170:173], v[218:221], v[80:83]
	v_mfma_f32_16x16x32_bf16 v[124:127], v[166:169], v[198:201], v[124:127]
	v_mfma_f32_16x16x32_bf16 v[120:123], v[174:177], v[198:201], v[120:123]
	v_mfma_f32_16x16x32_bf16 v[116:119], v[166:169], v[206:209], v[116:119]
	v_mfma_f32_16x16x32_bf16 v[112:115], v[174:177], v[206:209], v[112:115]
	v_mfma_f32_16x16x32_bf16 v[100:103], v[166:169], v[214:217], v[100:103]
	v_mfma_f32_16x16x32_bf16 v[96:99], v[174:177], v[214:217], v[96:99]
	v_mfma_f32_16x16x32_bf16 v[84:87], v[166:169], v[222:225], v[84:87]
	v_mfma_f32_16x16x32_bf16 v[80:83], v[174:177], v[222:225], v[80:83]
	s_setprio 0
	s_setprio 1
	v_mfma_f32_16x16x32_bf16 v[108:111], v[178:181], v[194:197], v[108:111]
	v_mfma_f32_16x16x32_bf16 v[104:107], v[186:189], v[194:197], v[104:107]
	v_mfma_f32_16x16x32_bf16 v[92:95], v[178:181], v[202:205], v[92:95]
	v_mfma_f32_16x16x32_bf16 v[88:91], v[186:189], v[202:205], v[88:91]
	v_mfma_f32_16x16x32_bf16 v[76:79], v[178:181], v[210:213], v[76:79]
	v_mfma_f32_16x16x32_bf16 v[72:75], v[186:189], v[210:213], v[72:75]
	v_mfma_f32_16x16x32_bf16 v[68:71], v[178:181], v[218:221], v[68:71]
	v_mfma_f32_16x16x32_bf16 v[64:67], v[186:189], v[218:221], v[64:67]
	v_mfma_f32_16x16x32_bf16 v[108:111], v[182:185], v[198:201], v[108:111]
	v_mfma_f32_16x16x32_bf16 v[104:107], v[190:193], v[198:201], v[104:107]
	v_mfma_f32_16x16x32_bf16 v[92:95], v[182:185], v[206:209], v[92:95]
	v_mfma_f32_16x16x32_bf16 v[88:91], v[190:193], v[206:209], v[88:91]
	v_mfma_f32_16x16x32_bf16 v[76:79], v[182:185], v[214:217], v[76:79]
	v_mfma_f32_16x16x32_bf16 v[72:75], v[190:193], v[214:217], v[72:75]
	s_setprio 2
	s_barrier
	v_mfma_f32_16x16x32_bf16 v[68:71], v[182:185], v[222:225], v[68:71]
	v_mfma_f32_16x16x32_bf16 v[64:67], v[190:193], v[222:225], v[64:67]
	s_setprio 0
	s_add_i32 s60, s48, s33
	v_lshl_add_u64 v[226:227], s[34:35], 0, v[134:135]
	s_mov_b32 m0, s60
	ds_read_b128 v[194:197], v160 offset:16384
	ds_read_b128 v[198:201], v160 offset:17408
	ds_read_b128 v[202:205], v160 offset:18432
	ds_read_b128 v[206:209], v160 offset:19456
	ds_read_b128 v[210:213], v160 offset:20480
	ds_read_b128 v[214:217], v160 offset:21504
	ds_read_b128 v[218:221], v160 offset:22528
	ds_read_b128 v[222:225], v160 offset:23552
	global_load_lds_dwordx4 v[226:227], off
	s_add_i32 m0, s60, 0x2000
	s_add_u32 s60, s34, 0x80000
	v_lshl_add_u64 v[228:229], s[34:35], 0, v[130:131]
	s_addc_u32 s61, s35, 0
	s_add_i32 s62, s49, s33
	global_load_lds_dwordx4 v[228:229], off
	v_lshl_add_u64 v[230:231], s[60:61], 0, v[134:135]
	s_mov_b32 m0, s62
	v_lshl_add_u64 v[232:233], s[36:37], 0, v[132:133]
	global_load_lds_dwordx4 v[230:231], off
	v_lshl_add_u64 v[230:231], s[60:61], 0, v[130:131]
	s_add_i32 m0, s62, 0x2000
	s_nop 0
	global_load_lds_dwordx4 v[230:231], off
	v_lshl_add_u64 v[230:231], s[36:37], 0, v[136:137]
	s_mov_b32 m0, s25
	s_nop 0
	global_load_lds_dwordx4 v[230:231], off
	s_mov_b32 m0, s40
	s_nop 0
	global_load_lds_dwordx4 v[232:233], off
	s_waitcnt vmcnt(8)
	s_waitcnt lgkmcnt(0)
	s_barrier
; #define PG8_STAGE(bufoff, gbase, voff) do { _Pragma("unroll") for (int _i = 0; _i < 2; ++_i) \
;         __builtin_amdgcn_global_load_lds((const unsigned*)((const char*)(gbase) + (voff)[_i]), (PG8_LAS unsigned*)(lds + (bufoff) + ldsw + _i * 8192), 16, 0, 0); } while (0)
; #define PG8_LDA(dst, b, h) do { _Pragma("unroll") for (int m = 0; m < 4; ++m) _Pragma("unroll") for (int k = 0; k < 2; ++k) dst[m][k] = *(const PG8_LAS bf16x8*)(lds + PG8_SA(b, h) + aoff + m * 2048 + k * 1024); } while (0)
; #define PG8_LDB(dst, b, h) do { _Pragma("unroll") for (int n = 0; n < 2; ++n) _Pragma("unroll") for (int k = 0; k < 2; ++k) dst[n][k] = *(const PG8_LAS bf16x8*)(lds + PG8_SB(b, h) + boff + n * 2048 + k * 1024); } while (0)
; #define PG8_MMA(ai, bj, At, Bt) do { __builtin_amdgcn_s_setprio(1); _Pragma("unroll") for (int m = 0; m < 4; ++m) _Pragma("unroll") for (int n = 0; n < 2; ++n) _Pragma("unroll") for (int k = 0; k < 2; ++k) \
;         acc[ai][bj][m][n] = __builtin_amdgcn_mfma_f32_16x16x32_bf16(Bt[n][k], At[m][k], acc[ai][bj][m][n], 0, 0, 0); __builtin_amdgcn_s_setprio(0); } while (0)
; #define PG8_WAIT_V(n) asm volatile("s_waitcnt vmcnt(" #n ")" ::: "memory")
; #define PG8_WAIT_L(n) asm volatile("s_waitcnt lgkmcnt(" #n ")" ::: "memory")
; #define PG8_BAR __builtin_amdgcn_s_barrier()
; #define PG8_SCHED __builtin_amdgcn_sched_barrier(0)
; template <class Epi, class Sched, bool ALIGN_EPI = false, bool SP2 = false>
; __device__ __forceinline__ void gemm_phase(PG8_LAS unsigned char* lds, const Gemm g, const Sched& S, const Epi& E) {
;     ...
;             PG8_WAIT_V(8); PG8_WAIT_L(0); PG8_BAR; PG8_MMA(1, 0, At, B0); PG8_MMA(1, 1, At, B1); PG8_BAR; PG8_SCHED;
;             PG8_LDB(B0, 1, 0); PG8_LDB(B1, 1, 1); PG8_SCHED; PG8_LDA(At, 1, 0); PG8_STAGE(PG8_SA(0, 1), a2 + hstep, voffA);
;             PG8_WAIT_V(8); PG8_WAIT_L(0); PG8_BAR; PG8_MMA(0, 0, At, B0); PG8_MMA(0, 1, At, B1); PG8_BAR; PG8_SCHED;
	s_setprio 1
	s_waitcnt lgkmcnt(0)
	v_mfma_f32_16x16x32_bf16 v[60:63], v[162:165], v[194:197], v[60:63]
	v_mfma_f32_16x16x32_bf16 v[56:59], v[170:173], v[194:197], v[56:59]
	v_mfma_f32_16x16x32_bf16 v[52:55], v[162:165], v[202:205], v[52:55]
	v_mfma_f32_16x16x32_bf16 v[48:51], v[170:173], v[202:205], v[48:51]
	v_mfma_f32_16x16x32_bf16 v[36:39], v[162:165], v[210:213], v[36:39]
	v_mfma_f32_16x16x32_bf16 v[32:35], v[170:173], v[210:213], v[32:35]
	v_mfma_f32_16x16x32_bf16 v[20:23], v[162:165], v[218:221], v[20:23]
	v_mfma_f32_16x16x32_bf16 v[16:19], v[170:173], v[218:221], v[16:19]
	v_mfma_f32_16x16x32_bf16 v[60:63], v[166:169], v[198:201], v[60:63]
	v_mfma_f32_16x16x32_bf16 v[56:59], v[174:177], v[198:201], v[56:59]
	v_mfma_f32_16x16x32_bf16 v[52:55], v[166:169], v[206:209], v[52:55]
	v_mfma_f32_16x16x32_bf16 v[48:51], v[174:177], v[206:209], v[48:51]
	v_mfma_f32_16x16x32_bf16 v[36:39], v[166:169], v[214:217], v[36:39]
	v_mfma_f32_16x16x32_bf16 v[32:35], v[174:177], v[214:217], v[32:35]
	v_mfma_f32_16x16x32_bf16 v[20:23], v[166:169], v[222:225], v[20:23]
	v_mfma_f32_16x16x32_bf16 v[16:19], v[174:177], v[222:225], v[16:19]
	s_setprio 0
	s_setprio 1
	v_mfma_f32_16x16x32_bf16 v[44:47], v[178:181], v[194:197], v[44:47]
	v_mfma_f32_16x16x32_bf16 v[40:43], v[186:189], v[194:197], v[40:43]
	v_mfma_f32_16x16x32_bf16 v[28:31], v[178:181], v[202:205], v[28:31]
	v_mfma_f32_16x16x32_bf16 v[24:27], v[186:189], v[202:205], v[24:27]
	v_mfma_f32_16x16x32_bf16 v[12:15], v[178:181], v[210:213], v[12:15]
	v_mfma_f32_16x16x32_bf16 v[8:11], v[186:189], v[210:213], v[8:11]
	v_mfma_f32_16x16x32_bf16 v[4:7], v[178:181], v[218:221], v[4:7]
	v_mfma_f32_16x16x32_bf16 v[0:3], v[186:189], v[218:221], v[0:3]
	v_mfma_f32_16x16x32_bf16 v[44:47], v[182:185], v[198:201], v[44:47]
	v_mfma_f32_16x16x32_bf16 v[40:43], v[190:193], v[198:201], v[40:43]
	v_mfma_f32_16x16x32_bf16 v[28:31], v[182:185], v[206:209], v[28:31]
	v_mfma_f32_16x16x32_bf16 v[24:27], v[190:193], v[206:209], v[24:27]
	v_mfma_f32_16x16x32_bf16 v[12:15], v[182:185], v[214:217], v[12:15]
	v_mfma_f32_16x16x32_bf16 v[8:11], v[190:193], v[214:217], v[8:11]
	s_setprio 2
	s_barrier
	v_mfma_f32_16x16x32_bf16 v[4:7], v[182:185], v[222:225], v[4:7]
	v_mfma_f32_16x16x32_bf16 v[0:3], v[190:193], v[222:225], v[0:3]
	s_setprio 0
	s_add_i32 s60, 0, 0x18000
	v_add_u32_e32 v161, s60, v156
	s_add_i32 s61, 0, 0x1c000
	ds_read_b128 v[162:165], v161
	ds_read_b128 v[166:169], v161 offset:1024
	ds_read_b128 v[170:173], v161 offset:2048
	ds_read_b128 v[174:177], v161 offset:3072
	v_add_u32_e32 v161, s61, v156
	ds_read_b128 v[178:181], v161
	ds_read_b128 v[182:185], v161 offset:1024
	ds_read_b128 v[186:189], v161 offset:2048
	ds_read_b128 v[190:193], v161 offset:3072
	s_add_u32 s36, s36, 0x80000
	s_addc_u32 s37, s37, 0
	s_mov_b32 m0, s41
	v_lshl_add_u64 v[234:235], s[36:37], 0, v[136:137]
	ds_read_b128 v[194:197], v160 offset:32768
	ds_read_b128 v[198:201], v160 offset:33792
	ds_read_b128 v[202:205], v160 offset:34816
	ds_read_b128 v[206:209], v160 offset:35840
	ds_read_b128 v[210:213], v160 offset:36864
	ds_read_b128 v[214:217], v160 offset:37888
	ds_read_b128 v[218:221], v160 offset:38912
	ds_read_b128 v[222:225], v160 offset:39936
	global_load_lds_dwordx4 v[234:235], off
	v_lshl_add_u64 v[234:235], s[36:37], 0, v[132:133]
	s_mov_b32 m0, s42
	s_nop 0
	global_load_lds_dwordx4 v[234:235], off
	s_waitcnt vmcnt(8)
	s_waitcnt lgkmcnt(0)
	s_barrier
	s_setprio 1
	s_waitcnt lgkmcnt(0)
	v_mfma_f32_16x16x32_bf16 v[124:127], v[162:165], v[194:197], v[124:127]
	v_mfma_f32_16x16x32_bf16 v[120:123], v[170:173], v[194:197], v[120:123]
	v_mfma_f32_16x16x32_bf16 v[116:119], v[162:165], v[202:205], v[116:119]
	v_mfma_f32_16x16x32_bf16 v[112:115], v[170:173], v[202:205], v[112:115]
	v_mfma_f32_16x16x32_bf16 v[100:103], v[162:165], v[210:213], v[100:103]
	v_mfma_f32_16x16x32_bf16 v[96:99], v[170:173], v[210:213], v[96:99]
	v_mfma_f32_16x16x32_bf16 v[84:87], v[162:165], v[218:221], v[84:87]
	v_mfma_f32_16x16x32_bf16 v[80:83], v[170:173], v[218:221], v[80:83]
	v_mfma_f32_16x16x32_bf16 v[124:127], v[166:169], v[198:201], v[124:127]
	v_mfma_f32_16x16x32_bf16 v[120:123], v[174:177], v[198:201], v[120:123]
	v_mfma_f32_16x16x32_bf16 v[116:119], v[166:169], v[206:209], v[116:119]
	v_mfma_f32_16x16x32_bf16 v[112:115], v[174:177], v[206:209], v[112:115]
	v_mfma_f32_16x16x32_bf16 v[100:103], v[166:169], v[214:217], v[100:103]
	v_mfma_f32_16x16x32_bf16 v[96:99], v[174:177], v[214:217], v[96:99]
	v_mfma_f32_16x16x32_bf16 v[84:87], v[166:169], v[222:225], v[84:87]
	v_mfma_f32_16x16x32_bf16 v[80:83], v[174:177], v[222:225], v[80:83]
	s_setprio 0
	s_setprio 1
	v_mfma_f32_16x16x32_bf16 v[108:111], v[178:181], v[194:197], v[108:111]
	v_mfma_f32_16x16x32_bf16 v[104:107], v[186:189], v[194:197], v[104:107]
	v_mfma_f32_16x16x32_bf16 v[92:95], v[178:181], v[202:205], v[92:95]
	v_mfma_f32_16x16x32_bf16 v[88:91], v[186:189], v[202:205], v[88:91]
	v_mfma_f32_16x16x32_bf16 v[76:79], v[178:181], v[210:213], v[76:79]
	v_mfma_f32_16x16x32_bf16 v[72:75], v[186:189], v[210:213], v[72:75]
	v_mfma_f32_16x16x32_bf16 v[68:71], v[178:181], v[218:221], v[68:71]
	v_mfma_f32_16x16x32_bf16 v[64:67], v[186:189], v[218:221], v[64:67]
	v_mfma_f32_16x16x32_bf16 v[108:111], v[182:185], v[198:201], v[108:111]
	v_mfma_f32_16x16x32_bf16 v[104:107], v[190:193], v[198:201], v[104:107]
	v_mfma_f32_16x16x32_bf16 v[92:95], v[182:185], v[206:209], v[92:95]
	v_mfma_f32_16x16x32_bf16 v[88:91], v[190:193], v[206:209], v[88:91]
	v_mfma_f32_16x16x32_bf16 v[76:79], v[182:185], v[214:217], v[76:79]
	v_mfma_f32_16x16x32_bf16 v[72:75], v[190:193], v[214:217], v[72:75]
	s_setprio 2
	s_barrier
; #define PG8_STAGE(bufoff, gbase, voff) do { _Pragma("unroll") for (int _i = 0; _i < 2; ++_i) \
;         __builtin_amdgcn_global_load_lds((const unsigned*)((const char*)(gbase) + (voff)[_i]), (PG8_LAS unsigned*)(lds + (bufoff) + ldsw + _i * 8192), 16, 0, 0); } while (0)
; #define PG8_LDA(dst, b, h) do { _Pragma("unroll") for (int m = 0; m < 4; ++m) _Pragma("unroll") for (int k = 0; k < 2; ++k) dst[m][k] = *(const PG8_LAS bf16x8*)(lds + PG8_SA(b, h) + aoff + m * 2048 + k * 1024); } while (0)
; #define PG8_MMA(ai, bj, At, Bt) do { __builtin_amdgcn_s_setprio(1); _Pragma("unroll") for (int m = 0; m < 4; ++m) _Pragma("unroll") for (int n = 0; n < 2; ++n) _Pragma("unroll") for (int k = 0; k < 2; ++k) \
;         acc[ai][bj][m][n] = __builtin_amdgcn_mfma_f32_16x16x32_bf16(Bt[n][k], At[m][k], acc[ai][bj][m][n], 0, 0, 0); __builtin_amdgcn_s_setprio(0); } while (0)
; #define PG8_WAIT_V(n) asm volatile("s_waitcnt vmcnt(" #n ")" ::: "memory")
; #define PG8_WAIT_L(n) asm volatile("s_waitcnt lgkmcnt(" #n ")" ::: "memory")
; #define PG8_BAR __builtin_amdgcn_s_barrier()
; #define PG8_SCHED __builtin_amdgcn_sched_barrier(0)
; template <class Epi, class Sched, bool ALIGN_EPI = false, bool SP2 = false>
; __device__ __forceinline__ void gemm_phase(PG8_LAS unsigned char* lds, const Gemm g, const Sched& S, const Epi& E) {
;     ...
;             PG8_WAIT_V(8); PG8_WAIT_L(0); PG8_BAR; PG8_MMA(0, 0, At, B0); PG8_MMA(0, 1, At, B1); PG8_BAR; PG8_SCHED;
;             PG8_LDA(At, 1, 1); PG8_STAGE(PG8_SB(1, 0), b3, voffB); PG8_STAGE(PG8_SB(1, 1), b3 + hstep, voffB); PG8_STAGE(PG8_SA(1, 0), a3, voffA);
;             PG8_WAIT_V(8); PG8_WAIT_L(0); PG8_BAR; PG8_MMA(1, 0, At, B0); PG8_MMA(1, 1, At, B1); PG8_BAR; PG8_SCHED;
;     ...
;         if constexpr (ALIGN_EPI) { if (wr == 0) PG8_BAR; }
	v_mfma_f32_16x16x32_bf16 v[68:71], v[182:185], v[222:225], v[68:71]
	v_mfma_f32_16x16x32_bf16 v[64:67], v[190:193], v[222:225], v[64:67]
	s_setprio 0
	s_add_i32 s36, s60, s33
	v_lshl_add_u64 v[226:227], v[226:227], 0, s[10:11]
	s_mov_b32 m0, s36
	ds_read_b128 v[194:197], v160 offset:49152
	ds_read_b128 v[198:201], v160 offset:50176
	ds_read_b128 v[202:205], v160 offset:51200
	ds_read_b128 v[206:209], v160 offset:52224
	ds_read_b128 v[210:213], v160 offset:53248
	ds_read_b128 v[214:217], v160 offset:54272
	ds_read_b128 v[218:221], v160 offset:55296
	ds_read_b128 v[222:225], v160 offset:56320
	global_load_lds_dwordx4 v[226:227], off
	s_add_i32 m0, s36, 0x2000
	s_add_u32 s34, s34, 0x80080
	v_lshl_add_u64 v[226:227], v[228:229], 0, s[10:11]
	s_addc_u32 s35, s35, 0
	s_add_i32 s36, s61, s33
	global_load_lds_dwordx4 v[226:227], off
	v_lshl_add_u64 v[226:227], s[34:35], 0, v[134:135]
	s_mov_b32 m0, s36
	s_nop 0
	global_load_lds_dwordx4 v[226:227], off
	v_lshl_add_u64 v[226:227], s[34:35], 0, v[130:131]
	s_add_i32 m0, s36, 0x2000
	s_nop 0
	global_load_lds_dwordx4 v[226:227], off
	v_lshl_add_u64 v[226:227], v[230:231], 0, s[10:11]
	s_mov_b32 m0, s44
	s_nop 0
	global_load_lds_dwordx4 v[226:227], off
	v_lshl_add_u64 v[226:227], v[232:233], 0, s[10:11]
	s_mov_b32 m0, s45
	s_nop 0
	global_load_lds_dwordx4 v[226:227], off
	s_waitcnt vmcnt(8)
	s_waitcnt lgkmcnt(0)
	s_barrier
	s_setprio 1
	s_waitcnt lgkmcnt(0)
	v_mfma_f32_16x16x32_bf16 v[60:63], v[162:165], v[194:197], v[60:63]
	v_mfma_f32_16x16x32_bf16 v[56:59], v[170:173], v[194:197], v[56:59]
	v_mfma_f32_16x16x32_bf16 v[52:55], v[162:165], v[202:205], v[52:55]
	v_mfma_f32_16x16x32_bf16 v[48:51], v[170:173], v[202:205], v[48:51]
	v_mfma_f32_16x16x32_bf16 v[36:39], v[162:165], v[210:213], v[36:39]
	v_mfma_f32_16x16x32_bf16 v[32:35], v[170:173], v[210:213], v[32:35]
	v_mfma_f32_16x16x32_bf16 v[20:23], v[162:165], v[218:221], v[20:23]
	v_mfma_f32_16x16x32_bf16 v[16:19], v[170:173], v[218:221], v[16:19]
	v_mfma_f32_16x16x32_bf16 v[60:63], v[166:169], v[198:201], v[60:63]
	v_mfma_f32_16x16x32_bf16 v[56:59], v[174:177], v[198:201], v[56:59]
	v_mfma_f32_16x16x32_bf16 v[52:55], v[166:169], v[206:209], v[52:55]
	v_mfma_f32_16x16x32_bf16 v[48:51], v[174:177], v[206:209], v[48:51]
	v_mfma_f32_16x16x32_bf16 v[36:39], v[166:169], v[214:217], v[36:39]
	v_mfma_f32_16x16x32_bf16 v[32:35], v[174:177], v[214:217], v[32:35]
	v_mfma_f32_16x16x32_bf16 v[20:23], v[166:169], v[222:225], v[20:23]
	v_mfma_f32_16x16x32_bf16 v[16:19], v[174:177], v[222:225], v[16:19]
	s_setprio 0
	s_setprio 1
	v_mfma_f32_16x16x32_bf16 v[44:47], v[178:181], v[194:197], v[44:47]
	v_mfma_f32_16x16x32_bf16 v[40:43], v[186:189], v[194:197], v[40:43]
	v_mfma_f32_16x16x32_bf16 v[28:31], v[178:181], v[202:205], v[28:31]
	v_mfma_f32_16x16x32_bf16 v[24:27], v[186:189], v[202:205], v[24:27]
	v_mfma_f32_16x16x32_bf16 v[12:15], v[178:181], v[210:213], v[12:15]
	v_mfma_f32_16x16x32_bf16 v[8:11], v[186:189], v[210:213], v[8:11]
	v_mfma_f32_16x16x32_bf16 v[4:7], v[178:181], v[218:221], v[4:7]
	v_mfma_f32_16x16x32_bf16 v[0:3], v[186:189], v[218:221], v[0:3]
	v_mfma_f32_16x16x32_bf16 v[44:47], v[182:185], v[198:201], v[44:47]
	v_mfma_f32_16x16x32_bf16 v[40:43], v[190:193], v[198:201], v[40:43]
	v_mfma_f32_16x16x32_bf16 v[28:31], v[182:185], v[206:209], v[28:31]
	v_mfma_f32_16x16x32_bf16 v[24:27], v[190:193], v[206:209], v[24:27]
	v_mfma_f32_16x16x32_bf16 v[12:15], v[182:185], v[214:217], v[12:15]
	v_mfma_f32_16x16x32_bf16 v[8:11], v[190:193], v[214:217], v[8:11]
	s_setprio 2
	s_barrier
	v_mfma_f32_16x16x32_bf16 v[4:7], v[182:185], v[222:225], v[4:7]
	v_mfma_f32_16x16x32_bf16 v[0:3], v[190:193], v[222:225], v[0:3]
	s_setprio 0
	s_add_i32 s59, s59, 2
	s_add_u32 s30, s30, 0x100
	s_addc_u32 s31, s31, 0
	s_add_u32 s57, s57, 0x100
	s_addc_u32 s58, s58, 0
	s_cmp_gt_u32 s59, 29
	s_cbranch_scc0 .LBB0_818
	s_and_b64 vcc, exec, s[12:13]
	s_cbranch_vccz .LBB0_821
	s_barrier

; #define PG8_STAGE(bufoff, gbase, voff) do { _Pragma("unroll") for (int _i = 0; _i < 2; ++_i) \
;         __builtin_amdgcn_global_load_lds((const unsigned*)((const char*)(gbase) + (voff)[_i]), (PG8_LAS unsigned*)(lds + (bufoff) + ldsw + _i * 8192), 16, 0, 0); } while (0)
; #define PG8_LDA(dst, b, h) do { _Pragma("unroll") for (int m = 0; m < 4; ++m) _Pragma("unroll") for (int k = 0; k < 2; ++k) dst[m][k] = *(const PG8_LAS bf16x8*)(lds + PG8_SA(b, h) + aoff + m * 2048 + k * 1024); } while (0)
; #define PG8_LDB(dst, b, h) do { _Pragma("unroll") for (int n = 0; n < 2; ++n) _Pragma("unroll") for (int k = 0; k < 2; ++k) dst[n][k] = *(const PG8_LAS bf16x8*)(lds + PG8_SB(b, h) + boff + n * 2048 + k * 1024); } while (0)
; #define PG8_MMA(ai, bj, At, Bt) do { __builtin_amdgcn_s_setprio(1); _Pragma("unroll") for (int m = 0; m < 4; ++m) _Pragma("unroll") for (int n = 0; n < 2; ++n) _Pragma("unroll") for (int k = 0; k < 2; ++k) \
;         acc[ai][bj][m][n] = __builtin_amdgcn_mfma_f32_16x16x32_bf16(Bt[n][k], At[m][k], acc[ai][bj][m][n], 0, 0, 0); __builtin_amdgcn_s_setprio(0); } while (0)
; #define PG8_WAIT_V(n) asm volatile("s_waitcnt vmcnt(" #n ")" ::: "memory")
; #define PG8_BAR __builtin_amdgcn_s_barrier()
; template <class Epi, class Sched, bool ALIGN_EPI = false, bool SP2 = false>
; __device__ __forceinline__ void gemm_phase(PG8_LAS unsigned char* lds, const Gemm g, const Sched& S, const Epi& E) {
;     ...
;         for (int t = 0; t < nt; t += 2) {
;             const bool last = (t == nt - 2);
;             const char* a1 = cA + (size_t)(t + 1) * kstep;
;             const char* a2 = last ? nA : cA + (size_t)(t + 2) * kstep; const char* b2 = last ? nB : cB + (size_t)(t + 2) * kstep;
;             const char* a3 = a2 + kstep; const char* b3 = b2 + kstep;
;             if (last && has_next) S.a_ready(nxt);
;             if constexpr (SP2) {
;             PG8_LDB(B0, 0, 0); PG8_LDB(B1, 0, 1); PG8_SCHED; PG8_LDA(At, 0, 0); PG8_STAGE(PG8_SA(1, 1), a1 + hstep, voffA);
;             PG8_WAIT_V(8); PG8_WAIT_L(0); PG8_BAR; PG8_MMA(0, 0, At, B0); PG8_MMA(0, 1, At, B1); PG8_BAR; PG8_SCHED;
;             PG8_LDA(At, 0, 1); PG8_STAGE(PG8_SB(0, 0), b2, voffB); PG8_STAGE(PG8_SB(0, 1), b2 + hstep, voffB); PG8_STAGE(PG8_SA(0, 0), a2, voffA);
;             PG8_WAIT_V(8); PG8_WAIT_L(0); PG8_BAR; PG8_MMA(1, 0, At, B0); PG8_MMA(1, 1, At, B1); PG8_BAR; PG8_SCHED;
.LBB0_835:
	s_add_u32 s31, s24, s30
	s_addc_u32 s38, s25, 0
	s_add_u32 s36, s31, 0x100
	s_addc_u32 s37, s38, 0
	s_and_b64 s[34:35], s[28:29], exec
	s_cselect_b32 s35, s15, s37
	s_cselect_b32 s34, s58, s36
	s_add_u32 s30, s18, s30
	s_addc_u32 s36, s19, 0
	s_add_u32 s30, s30, 0x100
	s_addc_u32 s36, s36, 0
	s_and_b64 s[28:29], s[28:29], exec
	s_cselect_b32 s37, s13, s36
	s_cselect_b32 s36, s59, s30
	s_add_u32 s40, s31, 0x10080
	ds_read_b128 v[148:151], v145
	ds_read_b128 v[152:155], v145 offset:1024
	ds_read_b128 v[156:159], v145 offset:2048
	ds_read_b128 v[160:163], v145 offset:3072
	ds_read_b128 v[164:167], v146
	ds_read_b128 v[168:171], v146 offset:1024
	ds_read_b128 v[172:175], v146 offset:2048
	ds_read_b128 v[176:179], v146 offset:3072
	s_addc_u32 s41, s38, 0
	s_add_i32 s69, s55, s42
	s_add_i32 m0, s17, 0xc000
	s_add_i32 s70, s17, 0xe000
	s_add_i32 s66, s69, 0x2000
	s_add_u32 s38, s36, 0x10000
	s_addc_u32 s39, s37, 0
	s_add_i32 s68, s56, s42
	s_add_i32 s67, s68, 0x2000
	s_add_i32 s65, 0, 0x18000
	s_add_i32 s64, 0, 0x1c000
	s_add_u32 s30, s34, 0x10000
	s_addc_u32 s31, s35, 0
	s_add_i32 s63, s65, s42
	s_add_i32 s61, s63, 0x2000
	s_add_u32 s28, s36, 0x10080
	s_addc_u32 s29, s37, 0
	s_add_i32 s62, s64, s42
	s_add_i32 s60, s62, 0x2000
	v_lshl_add_u64 v[212:213], s[40:41], 0, v[136:137]
	ds_read_b128 v[180:183], v147
	ds_read_b128 v[184:187], v147 offset:1024
	ds_read_b128 v[188:191], v147 offset:2048
	ds_read_b128 v[192:195], v147 offset:3072
	ds_read_b128 v[196:199], v147 offset:4096
	ds_read_b128 v[200:203], v147 offset:5120
	ds_read_b128 v[204:207], v147 offset:6144
	ds_read_b128 v[208:211], v147 offset:7168
	global_load_lds_dwordx4 v[212:213], off
	v_lshl_add_u64 v[212:213], s[40:41], 0, v[132:133]
	s_mov_b32 m0, s70
	s_nop 0
	global_load_lds_dwordx4 v[212:213], off
	s_waitcnt vmcnt(8)
	s_waitcnt lgkmcnt(0)
	s_barrier
	s_setprio 1
	s_waitcnt lgkmcnt(0)
	v_mfma_f32_16x16x32_bf16 v[124:127], v[148:151], v[180:183], v[124:127]
	v_mfma_f32_16x16x32_bf16 v[120:123], v[156:159], v[180:183], v[120:123]
	v_mfma_f32_16x16x32_bf16 v[116:119], v[148:151], v[188:191], v[116:119]
	v_mfma_f32_16x16x32_bf16 v[112:115], v[156:159], v[188:191], v[112:115]
	v_mfma_f32_16x16x32_bf16 v[100:103], v[148:151], v[196:199], v[100:103]
	v_mfma_f32_16x16x32_bf16 v[96:99], v[156:159], v[196:199], v[96:99]
	v_mfma_f32_16x16x32_bf16 v[84:87], v[148:151], v[204:207], v[84:87]
	v_mfma_f32_16x16x32_bf16 v[80:83], v[156:159], v[204:207], v[80:83]
	v_mfma_f32_16x16x32_bf16 v[124:127], v[152:155], v[184:187], v[124:127]
	v_mfma_f32_16x16x32_bf16 v[120:123], v[160:163], v[184:187], v[120:123]
	v_mfma_f32_16x16x32_bf16 v[116:119], v[152:155], v[192:195], v[116:119]
	v_mfma_f32_16x16x32_bf16 v[112:115], v[160:163], v[192:195], v[112:115]
	v_mfma_f32_16x16x32_bf16 v[100:103], v[152:155], v[200:203], v[100:103]
	v_mfma_f32_16x16x32_bf16 v[96:99], v[160:163], v[200:203], v[96:99]
	v_mfma_f32_16x16x32_bf16 v[84:87], v[152:155], v[208:211], v[84:87]
	v_mfma_f32_16x16x32_bf16 v[80:83], v[160:163], v[208:211], v[80:83]
	s_setprio 0
	s_setprio 1
	v_mfma_f32_16x16x32_bf16 v[108:111], v[164:167], v[180:183], v[108:111]
	v_mfma_f32_16x16x32_bf16 v[104:107], v[172:175], v[180:183], v[104:107]
	v_mfma_f32_16x16x32_bf16 v[92:95], v[164:167], v[188:191], v[92:95]
	v_mfma_f32_16x16x32_bf16 v[88:91], v[172:175], v[188:191], v[88:91]
	v_mfma_f32_16x16x32_bf16 v[76:79], v[164:167], v[196:199], v[76:79]
	v_mfma_f32_16x16x32_bf16 v[72:75], v[172:175], v[196:199], v[72:75]
	v_mfma_f32_16x16x32_bf16 v[68:71], v[164:167], v[204:207], v[68:71]
	v_mfma_f32_16x16x32_bf16 v[64:67], v[172:175], v[204:207], v[64:67]
	v_mfma_f32_16x16x32_bf16 v[108:111], v[168:171], v[184:187], v[108:111]
	v_mfma_f32_16x16x32_bf16 v[104:107], v[176:179], v[184:187], v[104:107]
	v_mfma_f32_16x16x32_bf16 v[92:95], v[168:171], v[192:195], v[92:95]
	v_mfma_f32_16x16x32_bf16 v[88:91], v[176:179], v[192:195], v[88:91]
	v_mfma_f32_16x16x32_bf16 v[76:79], v[168:171], v[200:203], v[76:79]
	v_mfma_f32_16x16x32_bf16 v[72:75], v[176:179], v[200:203], v[72:75]
	s_setprio 2
	s_barrier
	v_mfma_f32_16x16x32_bf16 v[68:71], v[168:171], v[208:211], v[68:71]
	v_mfma_f32_16x16x32_bf16 v[64:67], v[176:179], v[208:211], v[64:67]
	s_setprio 0
	s_mov_b32 m0, s69
	v_lshl_add_u64 v[212:213], s[36:37], 0, v[134:135]
	ds_read_b128 v[180:183], v147 offset:16384
	ds_read_b128 v[184:187], v147 offset:17408
	ds_read_b128 v[188:191], v147 offset:18432
	ds_read_b128 v[192:195], v147 offset:19456
	ds_read_b128 v[196:199], v147 offset:20480
	ds_read_b128 v[200:203], v147 offset:21504
	ds_read_b128 v[204:207], v147 offset:22528
	ds_read_b128 v[208:211], v147 offset:23552
	global_load_lds_dwordx4 v[212:213], off
	v_lshl_add_u64 v[214:215], s[36:37], 0, v[130:131]
	s_mov_b32 m0, s66
	v_lshl_add_u64 v[216:217], s[38:39], 0, v[134:135]
	global_load_lds_dwordx4 v[214:215], off
	s_mov_b32 m0, s68
	v_lshl_add_u64 v[218:219], s[34:35], 0, v[132:133]
	global_load_lds_dwordx4 v[216:217], off
	v_lshl_add_u64 v[216:217], s[38:39], 0, v[130:131]
	s_mov_b32 m0, s67
	s_nop 0
	global_load_lds_dwordx4 v[216:217], off
	v_lshl_add_u64 v[216:217], s[34:35], 0, v[136:137]
	s_mov_b32 m0, s17
	s_nop 0
	global_load_lds_dwordx4 v[216:217], off
	s_mov_b32 m0, s47
	s_nop 0
	global_load_lds_dwordx4 v[218:219], off
	s_waitcnt vmcnt(8)
	s_waitcnt lgkmcnt(0)
	s_barrier
; #define PG8_STAGE(bufoff, gbase, voff) do { _Pragma("unroll") for (int _i = 0; _i < 2; ++_i) \
;         __builtin_amdgcn_global_load_lds((const unsigned*)((const char*)(gbase) + (voff)[_i]), (PG8_LAS unsigned*)(lds + (bufoff) + ldsw + _i * 8192), 16, 0, 0); } while (0)
; #define PG8_LDA(dst, b, h) do { _Pragma("unroll") for (int m = 0; m < 4; ++m) _Pragma("unroll") for (int k = 0; k < 2; ++k) dst[m][k] = *(const PG8_LAS bf16x8*)(lds + PG8_SA(b, h) + aoff + m * 2048 + k * 1024); } while (0)
; #define PG8_LDB(dst, b, h) do { _Pragma("unroll") for (int n = 0; n < 2; ++n) _Pragma("unroll") for (int k = 0; k < 2; ++k) dst[n][k] = *(const PG8_LAS bf16x8*)(lds + PG8_SB(b, h) + boff + n * 2048 + k * 1024); } while (0)
; #define PG8_MMA(ai, bj, At, Bt) do { __builtin_amdgcn_s_setprio(1); _Pragma("unroll") for (int m = 0; m < 4; ++m) _Pragma("unroll") for (int n = 0; n < 2; ++n) _Pragma("unroll") for (int k = 0; k < 2; ++k) \
;         acc[ai][bj][m][n] = __builtin_amdgcn_mfma_f32_16x16x32_bf16(Bt[n][k], At[m][k], acc[ai][bj][m][n], 0, 0, 0); __builtin_amdgcn_s_setprio(0); } while (0)
; #define PG8_WAIT_V(n) asm volatile("s_waitcnt vmcnt(" #n ")" ::: "memory")
; #define PG8_WAIT_L(n) asm volatile("s_waitcnt lgkmcnt(" #n ")" ::: "memory")
; #define PG8_BAR __builtin_amdgcn_s_barrier()
; #define PG8_SCHED __builtin_amdgcn_sched_barrier(0)
; template <class Epi, class Sched, bool ALIGN_EPI = false, bool SP2 = false>
; __device__ __forceinline__ void gemm_phase(PG8_LAS unsigned char* lds, const Gemm g, const Sched& S, const Epi& E) {
;     ...
;             PG8_WAIT_V(8); PG8_WAIT_L(0); PG8_BAR; PG8_MMA(1, 0, At, B0); PG8_MMA(1, 1, At, B1); PG8_BAR; PG8_SCHED;
;             PG8_LDB(B0, 1, 0); PG8_LDB(B1, 1, 1); PG8_SCHED; PG8_LDA(At, 1, 0); PG8_STAGE(PG8_SA(0, 1), a2 + hstep, voffA);
;             PG8_WAIT_V(8); PG8_WAIT_L(0); PG8_BAR; PG8_MMA(0, 0, At, B0); PG8_MMA(0, 1, At, B1); PG8_BAR; PG8_SCHED;
	s_setprio 1
	s_waitcnt lgkmcnt(0)
	v_mfma_f32_16x16x32_bf16 v[60:63], v[148:151], v[180:183], v[60:63]
	v_mfma_f32_16x16x32_bf16 v[56:59], v[156:159], v[180:183], v[56:59]
	v_mfma_f32_16x16x32_bf16 v[52:55], v[148:151], v[188:191], v[52:55]
	v_mfma_f32_16x16x32_bf16 v[48:51], v[156:159], v[188:191], v[48:51]
	v_mfma_f32_16x16x32_bf16 v[36:39], v[148:151], v[196:199], v[36:39]
	v_mfma_f32_16x16x32_bf16 v[32:35], v[156:159], v[196:199], v[32:35]
	v_mfma_f32_16x16x32_bf16 v[20:23], v[148:151], v[204:207], v[20:23]
	v_mfma_f32_16x16x32_bf16 v[16:19], v[156:159], v[204:207], v[16:19]
	v_mfma_f32_16x16x32_bf16 v[60:63], v[152:155], v[184:187], v[60:63]
	v_mfma_f32_16x16x32_bf16 v[56:59], v[160:163], v[184:187], v[56:59]
	v_mfma_f32_16x16x32_bf16 v[52:55], v[152:155], v[192:195], v[52:55]
	v_mfma_f32_16x16x32_bf16 v[48:51], v[160:163], v[192:195], v[48:51]
	v_mfma_f32_16x16x32_bf16 v[36:39], v[152:155], v[200:203], v[36:39]
	v_mfma_f32_16x16x32_bf16 v[32:35], v[160:163], v[200:203], v[32:35]
	v_mfma_f32_16x16x32_bf16 v[20:23], v[152:155], v[208:211], v[20:23]
	v_mfma_f32_16x16x32_bf16 v[16:19], v[160:163], v[208:211], v[16:19]
	s_setprio 0
	s_setprio 1
	v_mfma_f32_16x16x32_bf16 v[44:47], v[164:167], v[180:183], v[44:47]
	v_mfma_f32_16x16x32_bf16 v[40:43], v[172:175], v[180:183], v[40:43]
	v_mfma_f32_16x16x32_bf16 v[28:31], v[164:167], v[188:191], v[28:31]
	v_mfma_f32_16x16x32_bf16 v[24:27], v[172:175], v[188:191], v[24:27]
	v_mfma_f32_16x16x32_bf16 v[12:15], v[164:167], v[196:199], v[12:15]
	v_mfma_f32_16x16x32_bf16 v[8:11], v[172:175], v[196:199], v[8:11]
	v_mfma_f32_16x16x32_bf16 v[4:7], v[164:167], v[204:207], v[4:7]
	v_mfma_f32_16x16x32_bf16 v[0:3], v[172:175], v[204:207], v[0:3]
	v_mfma_f32_16x16x32_bf16 v[44:47], v[168:171], v[184:187], v[44:47]
	v_mfma_f32_16x16x32_bf16 v[40:43], v[176:179], v[184:187], v[40:43]
	v_mfma_f32_16x16x32_bf16 v[28:31], v[168:171], v[192:195], v[28:31]
	v_mfma_f32_16x16x32_bf16 v[24:27], v[176:179], v[192:195], v[24:27]
	v_mfma_f32_16x16x32_bf16 v[12:15], v[168:171], v[200:203], v[12:15]
	v_mfma_f32_16x16x32_bf16 v[8:11], v[176:179], v[200:203], v[8:11]
	s_setprio 2
	s_barrier
	v_mfma_f32_16x16x32_bf16 v[4:7], v[168:171], v[208:211], v[4:7]
	v_mfma_f32_16x16x32_bf16 v[0:3], v[176:179], v[208:211], v[0:3]
	s_setprio 0
	v_add_u32_e32 v160, s65, v143
	v_add_u32_e32 v176, s64, v143
	ds_read_b128 v[148:151], v160
	ds_read_b128 v[152:155], v160 offset:1024
	ds_read_b128 v[156:159], v160 offset:2048
	ds_read_b128 v[160:163], v160 offset:3072
	ds_read_b128 v[164:167], v176
	ds_read_b128 v[168:171], v176 offset:1024
	ds_read_b128 v[172:175], v176 offset:2048
	ds_read_b128 v[176:179], v176 offset:3072
	s_mov_b32 m0, s48
	v_lshl_add_u64 v[220:221], s[30:31], 0, v[136:137]
	ds_read_b128 v[180:183], v147 offset:32768
	ds_read_b128 v[184:187], v147 offset:33792
	ds_read_b128 v[188:191], v147 offset:34816
	ds_read_b128 v[192:195], v147 offset:35840
	ds_read_b128 v[196:199], v147 offset:36864
	ds_read_b128 v[200:203], v147 offset:37888
	ds_read_b128 v[204:207], v147 offset:38912
	ds_read_b128 v[208:211], v147 offset:39936
	global_load_lds_dwordx4 v[220:221], off
	v_lshl_add_u64 v[220:221], s[30:31], 0, v[132:133]
	s_mov_b32 m0, s49
	s_nop 0
	global_load_lds_dwordx4 v[220:221], off
	s_waitcnt vmcnt(8)
	s_waitcnt lgkmcnt(0)
	s_barrier
	s_setprio 1
	s_waitcnt lgkmcnt(0)
	v_mfma_f32_16x16x32_bf16 v[124:127], v[148:151], v[180:183], v[124:127]
	v_mfma_f32_16x16x32_bf16 v[120:123], v[156:159], v[180:183], v[120:123]
	v_mfma_f32_16x16x32_bf16 v[116:119], v[148:151], v[188:191], v[116:119]
	v_mfma_f32_16x16x32_bf16 v[112:115], v[156:159], v[188:191], v[112:115]
	v_mfma_f32_16x16x32_bf16 v[100:103], v[148:151], v[196:199], v[100:103]
	v_mfma_f32_16x16x32_bf16 v[96:99], v[156:159], v[196:199], v[96:99]
	v_mfma_f32_16x16x32_bf16 v[84:87], v[148:151], v[204:207], v[84:87]
	v_mfma_f32_16x16x32_bf16 v[80:83], v[156:159], v[204:207], v[80:83]
	v_mfma_f32_16x16x32_bf16 v[124:127], v[152:155], v[184:187], v[124:127]
	v_mfma_f32_16x16x32_bf16 v[120:123], v[160:163], v[184:187], v[120:123]
	v_mfma_f32_16x16x32_bf16 v[116:119], v[152:155], v[192:195], v[116:119]
	v_mfma_f32_16x16x32_bf16 v[112:115], v[160:163], v[192:195], v[112:115]
	v_mfma_f32_16x16x32_bf16 v[100:103], v[152:155], v[200:203], v[100:103]
	v_mfma_f32_16x16x32_bf16 v[96:99], v[160:163], v[200:203], v[96:99]
	v_mfma_f32_16x16x32_bf16 v[84:87], v[152:155], v[208:211], v[84:87]
	v_mfma_f32_16x16x32_bf16 v[80:83], v[160:163], v[208:211], v[80:83]
	s_setprio 0
	s_setprio 1
	v_mfma_f32_16x16x32_bf16 v[108:111], v[164:167], v[180:183], v[108:111]
	v_mfma_f32_16x16x32_bf16 v[104:107], v[172:175], v[180:183], v[104:107]
	v_mfma_f32_16x16x32_bf16 v[92:95], v[164:167], v[188:191], v[92:95]
	v_mfma_f32_16x16x32_bf16 v[88:91], v[172:175], v[188:191], v[88:91]
	v_mfma_f32_16x16x32_bf16 v[76:79], v[164:167], v[196:199], v[76:79]
	v_mfma_f32_16x16x32_bf16 v[72:75], v[172:175], v[196:199], v[72:75]
	v_mfma_f32_16x16x32_bf16 v[68:71], v[164:167], v[204:207], v[68:71]
	v_mfma_f32_16x16x32_bf16 v[64:67], v[172:175], v[204:207], v[64:67]
	v_mfma_f32_16x16x32_bf16 v[108:111], v[168:171], v[184:187], v[108:111]
	v_mfma_f32_16x16x32_bf16 v[104:107], v[176:179], v[184:187], v[104:107]
	v_mfma_f32_16x16x32_bf16 v[92:95], v[168:171], v[192:195], v[92:95]
	v_mfma_f32_16x16x32_bf16 v[88:91], v[176:179], v[192:195], v[88:91]
	v_mfma_f32_16x16x32_bf16 v[76:79], v[168:171], v[200:203], v[76:79]
	v_mfma_f32_16x16x32_bf16 v[72:75], v[176:179], v[200:203], v[72:75]
	s_setprio 2
	s_barrier
; #define PG8_STAGE(bufoff, gbase, voff) do { _Pragma("unroll") for (int _i = 0; _i < 2; ++_i) \
;         __builtin_amdgcn_global_load_lds((const unsigned*)((const char*)(gbase) + (voff)[_i]), (PG8_LAS unsigned*)(lds + (bufoff) + ldsw + _i * 8192), 16, 0, 0); } while (0)
; #define PG8_LDA(dst, b, h) do { _Pragma("unroll") for (int m = 0; m < 4; ++m) _Pragma("unroll") for (int k = 0; k < 2; ++k) dst[m][k] = *(const PG8_LAS bf16x8*)(lds + PG8_SA(b, h) + aoff + m * 2048 + k * 1024); } while (0)
; #define PG8_MMA(ai, bj, At, Bt) do { __builtin_amdgcn_s_setprio(1); _Pragma("unroll") for (int m = 0; m < 4; ++m) _Pragma("unroll") for (int n = 0; n < 2; ++n) _Pragma("unroll") for (int k = 0; k < 2; ++k) \
;         acc[ai][bj][m][n] = __builtin_amdgcn_mfma_f32_16x16x32_bf16(Bt[n][k], At[m][k], acc[ai][bj][m][n], 0, 0, 0); __builtin_amdgcn_s_setprio(0); } while (0)
; #define PG8_WAIT_V(n) asm volatile("s_waitcnt vmcnt(" #n ")" ::: "memory")
; #define PG8_WAIT_L(n) asm volatile("s_waitcnt lgkmcnt(" #n ")" ::: "memory")
; #define PG8_BAR __builtin_amdgcn_s_barrier()
; #define PG8_SCHED __builtin_amdgcn_sched_barrier(0)
; template <class Epi, class Sched, bool ALIGN_EPI = false, bool SP2 = false>
; __device__ __forceinline__ void gemm_phase(PG8_LAS unsigned char* lds, const Gemm g, const Sched& S, const Epi& E) {
;     ...
;             PG8_WAIT_V(8); PG8_WAIT_L(0); PG8_BAR; PG8_MMA(0, 0, At, B0); PG8_MMA(0, 1, At, B1); PG8_BAR; PG8_SCHED;
;             PG8_LDA(At, 1, 1); PG8_STAGE(PG8_SB(1, 0), b3, voffB); PG8_STAGE(PG8_SB(1, 1), b3 + hstep, voffB); PG8_STAGE(PG8_SA(1, 0), a3, voffA);
;             PG8_WAIT_V(8); PG8_WAIT_L(0); PG8_BAR; PG8_MMA(1, 0, At, B0); PG8_MMA(1, 1, At, B1); PG8_BAR; PG8_SCHED;
;     ...
;         if constexpr (ALIGN_EPI) { if (wr == 0) PG8_BAR; }
	v_mfma_f32_16x16x32_bf16 v[68:71], v[168:171], v[208:211], v[68:71]
	v_mfma_f32_16x16x32_bf16 v[64:67], v[176:179], v[208:211], v[64:67]
	s_setprio 0
	s_mov_b32 m0, s63
	v_lshl_add_u64 v[212:213], v[212:213], 0, s[4:5]
	ds_read_b128 v[180:183], v147 offset:49152
	ds_read_b128 v[184:187], v147 offset:50176
	ds_read_b128 v[188:191], v147 offset:51200
	ds_read_b128 v[192:195], v147 offset:52224
	ds_read_b128 v[196:199], v147 offset:53248
	ds_read_b128 v[200:203], v147 offset:54272
	ds_read_b128 v[204:207], v147 offset:55296
	ds_read_b128 v[208:211], v147 offset:56320
	global_load_lds_dwordx4 v[212:213], off
	v_lshl_add_u64 v[212:213], v[214:215], 0, s[4:5]
	s_mov_b32 m0, s61
	s_nop 0
	global_load_lds_dwordx4 v[212:213], off
	v_lshl_add_u64 v[212:213], s[28:29], 0, v[134:135]
	s_mov_b32 m0, s62
	s_nop 0
	global_load_lds_dwordx4 v[212:213], off
	v_lshl_add_u64 v[212:213], s[28:29], 0, v[130:131]
	s_mov_b32 m0, s60
	s_nop 0
	global_load_lds_dwordx4 v[212:213], off
	v_lshl_add_u64 v[212:213], v[216:217], 0, s[4:5]
	s_mov_b32 m0, s52
	s_nop 0
	global_load_lds_dwordx4 v[212:213], off
	v_lshl_add_u64 v[212:213], v[218:219], 0, s[4:5]
	s_mov_b32 m0, s53
	s_nop 0
	global_load_lds_dwordx4 v[212:213], off
	s_waitcnt vmcnt(8)
	s_waitcnt lgkmcnt(0)
	s_barrier
	s_setprio 1
	s_waitcnt lgkmcnt(0)
	v_mfma_f32_16x16x32_bf16 v[60:63], v[148:151], v[180:183], v[60:63]
	v_mfma_f32_16x16x32_bf16 v[56:59], v[156:159], v[180:183], v[56:59]
	v_mfma_f32_16x16x32_bf16 v[52:55], v[148:151], v[188:191], v[52:55]
	v_mfma_f32_16x16x32_bf16 v[48:51], v[156:159], v[188:191], v[48:51]
	v_mfma_f32_16x16x32_bf16 v[36:39], v[148:151], v[196:199], v[36:39]
	v_mfma_f32_16x16x32_bf16 v[32:35], v[156:159], v[196:199], v[32:35]
	v_mfma_f32_16x16x32_bf16 v[20:23], v[148:151], v[204:207], v[20:23]
	v_mfma_f32_16x16x32_bf16 v[16:19], v[156:159], v[204:207], v[16:19]
	v_mfma_f32_16x16x32_bf16 v[60:63], v[152:155], v[184:187], v[60:63]
	v_mfma_f32_16x16x32_bf16 v[56:59], v[160:163], v[184:187], v[56:59]
	v_mfma_f32_16x16x32_bf16 v[52:55], v[152:155], v[192:195], v[52:55]
	v_mfma_f32_16x16x32_bf16 v[48:51], v[160:163], v[192:195], v[48:51]
	v_mfma_f32_16x16x32_bf16 v[36:39], v[152:155], v[200:203], v[36:39]
	v_mfma_f32_16x16x32_bf16 v[32:35], v[160:163], v[200:203], v[32:35]
	v_mfma_f32_16x16x32_bf16 v[20:23], v[152:155], v[208:211], v[20:23]
	v_mfma_f32_16x16x32_bf16 v[16:19], v[160:163], v[208:211], v[16:19]
	s_setprio 0
	s_setprio 1
	v_mfma_f32_16x16x32_bf16 v[44:47], v[164:167], v[180:183], v[44:47]
	v_mfma_f32_16x16x32_bf16 v[40:43], v[172:175], v[180:183], v[40:43]
	v_mfma_f32_16x16x32_bf16 v[28:31], v[164:167], v[188:191], v[28:31]
	v_mfma_f32_16x16x32_bf16 v[24:27], v[172:175], v[188:191], v[24:27]
	v_mfma_f32_16x16x32_bf16 v[12:15], v[164:167], v[196:199], v[12:15]
	v_mfma_f32_16x16x32_bf16 v[8:11], v[172:175], v[196:199], v[8:11]
	v_mfma_f32_16x16x32_bf16 v[4:7], v[164:167], v[204:207], v[4:7]
	v_mfma_f32_16x16x32_bf16 v[0:3], v[172:175], v[204:207], v[0:3]
	v_mfma_f32_16x16x32_bf16 v[44:47], v[168:171], v[184:187], v[44:47]
	v_mfma_f32_16x16x32_bf16 v[40:43], v[176:179], v[184:187], v[40:43]
	v_mfma_f32_16x16x32_bf16 v[28:31], v[168:171], v[192:195], v[28:31]
	v_mfma_f32_16x16x32_bf16 v[24:27], v[176:179], v[192:195], v[24:27]
	v_mfma_f32_16x16x32_bf16 v[12:15], v[168:171], v[200:203], v[12:15]
	v_mfma_f32_16x16x32_bf16 v[8:11], v[176:179], v[200:203], v[8:11]
	s_setprio 2
	s_barrier
	v_mfma_f32_16x16x32_bf16 v[4:7], v[168:171], v[208:211], v[4:7]
	v_mfma_f32_16x16x32_bf16 v[0:3], v[176:179], v[208:211], v[0:3]
	s_setprio 0
	s_movk_i32 s30, 0x100
	s_andn2_b64 vcc, exec, s[26:27]
	s_mov_b64 s[28:29], -1
	s_mov_b64 s[26:27], 0
	s_cbranch_vccz .LBB0_835
	s_and_b64 vcc, exec, s[10:11]
	s_cbranch_vccz .LBB0_838
	s_barrier

; #define PG8_STAGE(bufoff, gbase, voff) do { _Pragma("unroll") for (int _i = 0; _i < 2; ++_i) \
;         __builtin_amdgcn_global_load_lds((const unsigned*)((const char*)(gbase) + (voff)[_i]), (PG8_LAS unsigned*)(lds + (bufoff) + ldsw + _i * 8192), 16, 0, 0); } while (0)
; #define PG8_LDA(dst, b, h) do { _Pragma("unroll") for (int m = 0; m < 4; ++m) _Pragma("unroll") for (int k = 0; k < 2; ++k) dst[m][k] = *(const PG8_LAS bf16x8*)(lds + PG8_SA(b, h) + aoff + m * 2048 + k * 1024); } while (0)
; #define PG8_LDB(dst, b, h) do { _Pragma("unroll") for (int n = 0; n < 2; ++n) _Pragma("unroll") for (int k = 0; k < 2; ++k) dst[n][k] = *(const PG8_LAS bf16x8*)(lds + PG8_SB(b, h) + boff + n * 2048 + k * 1024); } while (0)
; #define PG8_MMA(ai, bj, At, Bt) do { __builtin_amdgcn_s_setprio(1); _Pragma("unroll") for (int m = 0; m < 4; ++m) _Pragma("unroll") for (int n = 0; n < 2; ++n) _Pragma("unroll") for (int k = 0; k < 2; ++k) \
;         acc[ai][bj][m][n] = __builtin_amdgcn_mfma_f32_16x16x32_bf16(Bt[n][k], At[m][k], acc[ai][bj][m][n], 0, 0, 0); __builtin_amdgcn_s_setprio(0); } while (0)
; #define PG8_WAIT_V(n) asm volatile("s_waitcnt vmcnt(" #n ")" ::: "memory")
; #define PG8_BAR __builtin_amdgcn_s_barrier()
; template <class Epi, class Sched, bool ALIGN_EPI = false, bool SP2 = false>
; __device__ __forceinline__ void gemm_phase(PG8_LAS unsigned char* lds, const Gemm g, const Sched& S, const Epi& E) {
;     ...
;         for (int t = 0; t < nt; t += 2) {
;             const bool last = (t == nt - 2);
;             const char* a1 = cA + (size_t)(t + 1) * kstep;
;             const char* a2 = last ? nA : cA + (size_t)(t + 2) * kstep; const char* b2 = last ? nB : cB + (size_t)(t + 2) * kstep;
;             const char* a3 = a2 + kstep; const char* b3 = b2 + kstep;
;             if (last && has_next) S.a_ready(nxt);
;             if constexpr (SP2) {
;             PG8_LDB(B0, 0, 0); PG8_LDB(B1, 0, 1); PG8_SCHED; PG8_LDA(At, 0, 0); PG8_STAGE(PG8_SA(1, 1), a1 + hstep, voffA);
;             PG8_WAIT_V(8); PG8_WAIT_L(0); PG8_BAR; PG8_MMA(0, 0, At, B0); PG8_MMA(0, 1, At, B1); PG8_BAR; PG8_SCHED;
;             PG8_LDA(At, 0, 1); PG8_STAGE(PG8_SB(0, 0), b2, voffB); PG8_STAGE(PG8_SB(0, 1), b2 + hstep, voffB); PG8_STAGE(PG8_SA(0, 0), a2, voffA);
;             PG8_WAIT_V(8); PG8_WAIT_L(0); PG8_BAR; PG8_MMA(1, 0, At, B0); PG8_MMA(1, 1, At, B1); PG8_BAR; PG8_SCHED;
.LBB0_966:
	ds_read_b128 v[146:149], v153
	ds_read_b128 v[156:159], v153 offset:1024
	ds_read_b128 v[160:163], v153 offset:2048
	ds_read_b128 v[164:167], v153 offset:3072
	ds_read_b128 v[168:171], v154
	ds_read_b128 v[172:175], v154 offset:1024
	ds_read_b128 v[176:179], v154 offset:2048
	ds_read_b128 v[180:183], v154 offset:3072
	s_add_u32 s24, s22, 0xfff80080
	s_addc_u32 s25, s23, -1
	s_cmp_eq_u32 s52, 28
	s_cselect_b32 s27, s15, s25
	s_cselect_b32 s26, s45, s24
	s_cselect_b32 s25, s13, s51
	s_cselect_b32 s24, s46, s47
	v_lshl_add_u64 v[216:217], s[22:23], 0, v[138:139]
	s_add_i32 m0, s21, 0xc000
	ds_read_b128 v[184:187], v155
	ds_read_b128 v[188:191], v155 offset:1024
	ds_read_b128 v[192:195], v155 offset:2048
	ds_read_b128 v[196:199], v155 offset:3072
	ds_read_b128 v[200:203], v155 offset:4096
	ds_read_b128 v[204:207], v155 offset:5120
	ds_read_b128 v[208:211], v155 offset:6144
	ds_read_b128 v[212:215], v155 offset:7168
	global_load_lds_dwordx4 v[216:217], off
	v_lshl_add_u64 v[216:217], s[22:23], 0, v[140:141]
	s_add_i32 m0, s21, 0xe000
	s_nop 0
	global_load_lds_dwordx4 v[216:217], off
	s_waitcnt vmcnt(8)
	s_waitcnt lgkmcnt(0)
	s_barrier
	s_setprio 1
	s_waitcnt lgkmcnt(0)
	v_mfma_f32_16x16x32_bf16 v[124:127], v[146:149], v[184:187], v[124:127]
	v_mfma_f32_16x16x32_bf16 v[116:119], v[160:163], v[184:187], v[116:119]
	v_mfma_f32_16x16x32_bf16 v[108:111], v[146:149], v[192:195], v[108:111]
	v_mfma_f32_16x16x32_bf16 v[100:103], v[160:163], v[192:195], v[100:103]
	v_mfma_f32_16x16x32_bf16 v[92:95], v[146:149], v[200:203], v[92:95]
	v_mfma_f32_16x16x32_bf16 v[84:87], v[160:163], v[200:203], v[84:87]
	v_mfma_f32_16x16x32_bf16 v[76:79], v[146:149], v[208:211], v[76:79]
	v_mfma_f32_16x16x32_bf16 v[68:71], v[160:163], v[208:211], v[68:71]
	v_mfma_f32_16x16x32_bf16 v[124:127], v[156:159], v[188:191], v[124:127]
	v_mfma_f32_16x16x32_bf16 v[116:119], v[164:167], v[188:191], v[116:119]
	v_mfma_f32_16x16x32_bf16 v[108:111], v[156:159], v[196:199], v[108:111]
	v_mfma_f32_16x16x32_bf16 v[100:103], v[164:167], v[196:199], v[100:103]
	v_mfma_f32_16x16x32_bf16 v[92:95], v[156:159], v[204:207], v[92:95]
	v_mfma_f32_16x16x32_bf16 v[84:87], v[164:167], v[204:207], v[84:87]
	v_mfma_f32_16x16x32_bf16 v[76:79], v[156:159], v[212:215], v[76:79]
	v_mfma_f32_16x16x32_bf16 v[68:71], v[164:167], v[212:215], v[68:71]
	s_setprio 0
	s_setprio 1
	v_mfma_f32_16x16x32_bf16 v[120:123], v[168:171], v[184:187], v[120:123]
	v_mfma_f32_16x16x32_bf16 v[112:115], v[176:179], v[184:187], v[112:115]
	v_mfma_f32_16x16x32_bf16 v[104:107], v[168:171], v[192:195], v[104:107]
	v_mfma_f32_16x16x32_bf16 v[96:99], v[176:179], v[192:195], v[96:99]
	v_mfma_f32_16x16x32_bf16 v[88:91], v[168:171], v[200:203], v[88:91]
	v_mfma_f32_16x16x32_bf16 v[80:83], v[176:179], v[200:203], v[80:83]
	v_mfma_f32_16x16x32_bf16 v[72:75], v[168:171], v[208:211], v[72:75]
	v_mfma_f32_16x16x32_bf16 v[64:67], v[176:179], v[208:211], v[64:67]
	v_mfma_f32_16x16x32_bf16 v[120:123], v[172:175], v[188:191], v[120:123]
	v_mfma_f32_16x16x32_bf16 v[112:115], v[180:183], v[188:191], v[112:115]
	v_mfma_f32_16x16x32_bf16 v[104:107], v[172:175], v[196:199], v[104:107]
	v_mfma_f32_16x16x32_bf16 v[96:99], v[180:183], v[196:199], v[96:99]
	v_mfma_f32_16x16x32_bf16 v[88:91], v[172:175], v[204:207], v[88:91]
	v_mfma_f32_16x16x32_bf16 v[80:83], v[180:183], v[204:207], v[80:83]
	s_setprio 2
	s_barrier
	v_mfma_f32_16x16x32_bf16 v[72:75], v[172:175], v[212:215], v[72:75]
	v_mfma_f32_16x16x32_bf16 v[64:67], v[180:183], v[212:215], v[64:67]
	s_setprio 0
	s_add_i32 s53, s41, s28
	v_lshl_add_u64 v[216:217], s[24:25], 0, v[134:135]
	s_mov_b32 m0, s53
	ds_read_b128 v[184:187], v155 offset:16384
	ds_read_b128 v[188:191], v155 offset:17408
	ds_read_b128 v[192:195], v155 offset:18432
	ds_read_b128 v[196:199], v155 offset:19456
	ds_read_b128 v[200:203], v155 offset:20480
	ds_read_b128 v[204:207], v155 offset:21504
	ds_read_b128 v[208:211], v155 offset:22528
	ds_read_b128 v[212:215], v155 offset:23552
	global_load_lds_dwordx4 v[216:217], off
	s_add_i32 m0, s53, 0x2000
	s_add_u32 s54, s24, 0x80000
	v_lshl_add_u64 v[218:219], s[24:25], 0, v[130:131]
	s_addc_u32 s55, s25, 0
	s_add_i32 s53, s42, s28
	global_load_lds_dwordx4 v[218:219], off
	v_lshl_add_u64 v[220:221], s[54:55], 0, v[134:135]
	s_mov_b32 m0, s53
	v_lshl_add_u64 v[222:223], s[26:27], 0, v[132:133]
	global_load_lds_dwordx4 v[220:221], off
	v_lshl_add_u64 v[220:221], s[54:55], 0, v[130:131]
	s_add_i32 m0, s53, 0x2000
	s_nop 0
	global_load_lds_dwordx4 v[220:221], off
	v_lshl_add_u64 v[220:221], s[26:27], 0, v[136:137]
	s_mov_b32 m0, s21
	s_nop 0
	global_load_lds_dwordx4 v[220:221], off
	s_mov_b32 m0, s31
	s_nop 0
	global_load_lds_dwordx4 v[222:223], off
	s_waitcnt vmcnt(8)
	s_waitcnt lgkmcnt(0)
	s_barrier
; #define PG8_STAGE(bufoff, gbase, voff) do { _Pragma("unroll") for (int _i = 0; _i < 2; ++_i) \
;         __builtin_amdgcn_global_load_lds((const unsigned*)((const char*)(gbase) + (voff)[_i]), (PG8_LAS unsigned*)(lds + (bufoff) + ldsw + _i * 8192), 16, 0, 0); } while (0)
; #define PG8_LDA(dst, b, h) do { _Pragma("unroll") for (int m = 0; m < 4; ++m) _Pragma("unroll") for (int k = 0; k < 2; ++k) dst[m][k] = *(const PG8_LAS bf16x8*)(lds + PG8_SA(b, h) + aoff + m * 2048 + k * 1024); } while (0)
; #define PG8_LDB(dst, b, h) do { _Pragma("unroll") for (int n = 0; n < 2; ++n) _Pragma("unroll") for (int k = 0; k < 2; ++k) dst[n][k] = *(const PG8_LAS bf16x8*)(lds + PG8_SB(b, h) + boff + n * 2048 + k * 1024); } while (0)
; #define PG8_MMA(ai, bj, At, Bt) do { __builtin_amdgcn_s_setprio(1); _Pragma("unroll") for (int m = 0; m < 4; ++m) _Pragma("unroll") for (int n = 0; n < 2; ++n) _Pragma("unroll") for (int k = 0; k < 2; ++k) \
;         acc[ai][bj][m][n] = __builtin_amdgcn_mfma_f32_16x16x32_bf16(Bt[n][k], At[m][k], acc[ai][bj][m][n], 0, 0, 0); __builtin_amdgcn_s_setprio(0); } while (0)
; #define PG8_WAIT_V(n) asm volatile("s_waitcnt vmcnt(" #n ")" ::: "memory")
; #define PG8_WAIT_L(n) asm volatile("s_waitcnt lgkmcnt(" #n ")" ::: "memory")
; #define PG8_BAR __builtin_amdgcn_s_barrier()
; #define PG8_SCHED __builtin_amdgcn_sched_barrier(0)
; template <class Epi, class Sched, bool ALIGN_EPI = false, bool SP2 = false>
; __device__ __forceinline__ void gemm_phase(PG8_LAS unsigned char* lds, const Gemm g, const Sched& S, const Epi& E) {
;     ...
;             PG8_WAIT_V(8); PG8_WAIT_L(0); PG8_BAR; PG8_MMA(1, 0, At, B0); PG8_MMA(1, 1, At, B1); PG8_BAR; PG8_SCHED;
;             PG8_LDB(B0, 1, 0); PG8_LDB(B1, 1, 1); PG8_SCHED; PG8_LDA(At, 1, 0); PG8_STAGE(PG8_SA(0, 1), a2 + hstep, voffA);
;             PG8_WAIT_V(8); PG8_WAIT_L(0); PG8_BAR; PG8_MMA(0, 0, At, B0); PG8_MMA(0, 1, At, B1); PG8_BAR; PG8_SCHED;
	s_setprio 1
	s_waitcnt lgkmcnt(0)
	v_mfma_f32_16x16x32_bf16 v[60:63], v[146:149], v[184:187], v[60:63]
	v_mfma_f32_16x16x32_bf16 v[52:55], v[160:163], v[184:187], v[52:55]
	v_mfma_f32_16x16x32_bf16 v[44:47], v[146:149], v[192:195], v[44:47]
	v_mfma_f32_16x16x32_bf16 v[36:39], v[160:163], v[192:195], v[36:39]
	v_mfma_f32_16x16x32_bf16 v[28:31], v[146:149], v[200:203], v[28:31]
	v_mfma_f32_16x16x32_bf16 v[20:23], v[160:163], v[200:203], v[20:23]
	v_mfma_f32_16x16x32_bf16 v[12:15], v[146:149], v[208:211], v[12:15]
	v_mfma_f32_16x16x32_bf16 v[4:7], v[160:163], v[208:211], v[4:7]
	v_mfma_f32_16x16x32_bf16 v[60:63], v[156:159], v[188:191], v[60:63]
	v_mfma_f32_16x16x32_bf16 v[52:55], v[164:167], v[188:191], v[52:55]
	v_mfma_f32_16x16x32_bf16 v[44:47], v[156:159], v[196:199], v[44:47]
	v_mfma_f32_16x16x32_bf16 v[36:39], v[164:167], v[196:199], v[36:39]
	v_mfma_f32_16x16x32_bf16 v[28:31], v[156:159], v[204:207], v[28:31]
	v_mfma_f32_16x16x32_bf16 v[20:23], v[164:167], v[204:207], v[20:23]
	v_mfma_f32_16x16x32_bf16 v[12:15], v[156:159], v[212:215], v[12:15]
	v_mfma_f32_16x16x32_bf16 v[4:7], v[164:167], v[212:215], v[4:7]
	s_setprio 0
	s_setprio 1
	v_mfma_f32_16x16x32_bf16 v[56:59], v[168:171], v[184:187], v[56:59]
	v_mfma_f32_16x16x32_bf16 v[48:51], v[176:179], v[184:187], v[48:51]
	v_mfma_f32_16x16x32_bf16 v[40:43], v[168:171], v[192:195], v[40:43]
	v_mfma_f32_16x16x32_bf16 v[32:35], v[176:179], v[192:195], v[32:35]
	v_mfma_f32_16x16x32_bf16 v[24:27], v[168:171], v[200:203], v[24:27]
	v_mfma_f32_16x16x32_bf16 v[16:19], v[176:179], v[200:203], v[16:19]
	v_mfma_f32_16x16x32_bf16 v[8:11], v[168:171], v[208:211], v[8:11]
	v_mfma_f32_16x16x32_bf16 v[0:3], v[176:179], v[208:211], v[0:3]
	v_mfma_f32_16x16x32_bf16 v[56:59], v[172:175], v[188:191], v[56:59]
	v_mfma_f32_16x16x32_bf16 v[48:51], v[180:183], v[188:191], v[48:51]
	v_mfma_f32_16x16x32_bf16 v[40:43], v[172:175], v[196:199], v[40:43]
	v_mfma_f32_16x16x32_bf16 v[32:35], v[180:183], v[196:199], v[32:35]
	v_mfma_f32_16x16x32_bf16 v[24:27], v[172:175], v[204:207], v[24:27]
	v_mfma_f32_16x16x32_bf16 v[16:19], v[180:183], v[204:207], v[16:19]
	s_setprio 2
	s_barrier
	v_mfma_f32_16x16x32_bf16 v[8:11], v[172:175], v[212:215], v[8:11]
	v_mfma_f32_16x16x32_bf16 v[0:3], v[180:183], v[212:215], v[0:3]
	s_setprio 0
	s_add_i32 s53, 0, 0x18000
	s_add_i32 s54, 0, 0x1c000
	v_add_u32_e32 v164, s53, v151
	v_add_u32_e32 v180, s54, v151
	ds_read_b128 v[146:149], v164
	ds_read_b128 v[156:159], v164 offset:1024
	ds_read_b128 v[160:163], v164 offset:2048
	ds_read_b128 v[164:167], v164 offset:3072
	ds_read_b128 v[168:171], v180
	ds_read_b128 v[172:175], v180 offset:1024
	ds_read_b128 v[176:179], v180 offset:2048
	ds_read_b128 v[180:183], v180 offset:3072
	s_add_u32 s26, s26, 0x80000
	s_addc_u32 s27, s27, 0
	s_mov_b32 m0, s34
	v_lshl_add_u64 v[224:225], s[26:27], 0, v[136:137]
	ds_read_b128 v[184:187], v155 offset:32768
	ds_read_b128 v[188:191], v155 offset:33792
	ds_read_b128 v[192:195], v155 offset:34816
	ds_read_b128 v[196:199], v155 offset:35840
	ds_read_b128 v[200:203], v155 offset:36864
	ds_read_b128 v[204:207], v155 offset:37888
	ds_read_b128 v[208:211], v155 offset:38912
	ds_read_b128 v[212:215], v155 offset:39936
	global_load_lds_dwordx4 v[224:225], off
	v_lshl_add_u64 v[224:225], s[26:27], 0, v[132:133]
	s_mov_b32 m0, s35
	s_nop 0
	global_load_lds_dwordx4 v[224:225], off
	s_waitcnt vmcnt(8)
	s_waitcnt lgkmcnt(0)
	s_barrier
	s_setprio 1
	s_waitcnt lgkmcnt(0)
	v_mfma_f32_16x16x32_bf16 v[124:127], v[146:149], v[184:187], v[124:127]
	v_mfma_f32_16x16x32_bf16 v[116:119], v[160:163], v[184:187], v[116:119]
	v_mfma_f32_16x16x32_bf16 v[108:111], v[146:149], v[192:195], v[108:111]
	v_mfma_f32_16x16x32_bf16 v[100:103], v[160:163], v[192:195], v[100:103]
	v_mfma_f32_16x16x32_bf16 v[92:95], v[146:149], v[200:203], v[92:95]
	v_mfma_f32_16x16x32_bf16 v[84:87], v[160:163], v[200:203], v[84:87]
	v_mfma_f32_16x16x32_bf16 v[76:79], v[146:149], v[208:211], v[76:79]
	v_mfma_f32_16x16x32_bf16 v[68:71], v[160:163], v[208:211], v[68:71]
	v_mfma_f32_16x16x32_bf16 v[124:127], v[156:159], v[188:191], v[124:127]
	v_mfma_f32_16x16x32_bf16 v[116:119], v[164:167], v[188:191], v[116:119]
	v_mfma_f32_16x16x32_bf16 v[108:111], v[156:159], v[196:199], v[108:111]
	v_mfma_f32_16x16x32_bf16 v[100:103], v[164:167], v[196:199], v[100:103]
	v_mfma_f32_16x16x32_bf16 v[92:95], v[156:159], v[204:207], v[92:95]
	v_mfma_f32_16x16x32_bf16 v[84:87], v[164:167], v[204:207], v[84:87]
	v_mfma_f32_16x16x32_bf16 v[76:79], v[156:159], v[212:215], v[76:79]
	v_mfma_f32_16x16x32_bf16 v[68:71], v[164:167], v[212:215], v[68:71]
	s_setprio 0
	s_setprio 1
	v_mfma_f32_16x16x32_bf16 v[120:123], v[168:171], v[184:187], v[120:123]
	v_mfma_f32_16x16x32_bf16 v[112:115], v[176:179], v[184:187], v[112:115]
	v_mfma_f32_16x16x32_bf16 v[104:107], v[168:171], v[192:195], v[104:107]
	v_mfma_f32_16x16x32_bf16 v[96:99], v[176:179], v[192:195], v[96:99]
	v_mfma_f32_16x16x32_bf16 v[88:91], v[168:171], v[200:203], v[88:91]
	v_mfma_f32_16x16x32_bf16 v[80:83], v[176:179], v[200:203], v[80:83]
	v_mfma_f32_16x16x32_bf16 v[72:75], v[168:171], v[208:211], v[72:75]
	v_mfma_f32_16x16x32_bf16 v[64:67], v[176:179], v[208:211], v[64:67]
	v_mfma_f32_16x16x32_bf16 v[120:123], v[172:175], v[188:191], v[120:123]
	v_mfma_f32_16x16x32_bf16 v[112:115], v[180:183], v[188:191], v[112:115]
	v_mfma_f32_16x16x32_bf16 v[104:107], v[172:175], v[196:199], v[104:107]
	v_mfma_f32_16x16x32_bf16 v[96:99], v[180:183], v[196:199], v[96:99]
	v_mfma_f32_16x16x32_bf16 v[88:91], v[172:175], v[204:207], v[88:91]
	v_mfma_f32_16x16x32_bf16 v[80:83], v[180:183], v[204:207], v[80:83]
	s_setprio 2
	s_barrier
; #define PG8_STAGE(bufoff, gbase, voff) do { _Pragma("unroll") for (int _i = 0; _i < 2; ++_i) \
;         __builtin_amdgcn_global_load_lds((const unsigned*)((const char*)(gbase) + (voff)[_i]), (PG8_LAS unsigned*)(lds + (bufoff) + ldsw + _i * 8192), 16, 0, 0); } while (0)
; #define PG8_LDA(dst, b, h) do { _Pragma("unroll") for (int m = 0; m < 4; ++m) _Pragma("unroll") for (int k = 0; k < 2; ++k) dst[m][k] = *(const PG8_LAS bf16x8*)(lds + PG8_SA(b, h) + aoff + m * 2048 + k * 1024); } while (0)
; #define PG8_MMA(ai, bj, At, Bt) do { __builtin_amdgcn_s_setprio(1); _Pragma("unroll") for (int m = 0; m < 4; ++m) _Pragma("unroll") for (int n = 0; n < 2; ++n) _Pragma("unroll") for (int k = 0; k < 2; ++k) \
;         acc[ai][bj][m][n] = __builtin_amdgcn_mfma_f32_16x16x32_bf16(Bt[n][k], At[m][k], acc[ai][bj][m][n], 0, 0, 0); __builtin_amdgcn_s_setprio(0); } while (0)
; #define PG8_WAIT_V(n) asm volatile("s_waitcnt vmcnt(" #n ")" ::: "memory")
; #define PG8_WAIT_L(n) asm volatile("s_waitcnt lgkmcnt(" #n ")" ::: "memory")
; #define PG8_BAR __builtin_amdgcn_s_barrier()
; #define PG8_SCHED __builtin_amdgcn_sched_barrier(0)
; template <class Epi, class Sched, bool ALIGN_EPI = false, bool SP2 = false>
; __device__ __forceinline__ void gemm_phase(PG8_LAS unsigned char* lds, const Gemm g, const Sched& S, const Epi& E) {
;     ...
;             PG8_WAIT_V(8); PG8_WAIT_L(0); PG8_BAR; PG8_MMA(0, 0, At, B0); PG8_MMA(0, 1, At, B1); PG8_BAR; PG8_SCHED;
;             PG8_LDA(At, 1, 1); PG8_STAGE(PG8_SB(1, 0), b3, voffB); PG8_STAGE(PG8_SB(1, 1), b3 + hstep, voffB); PG8_STAGE(PG8_SA(1, 0), a3, voffA);
;             PG8_WAIT_V(8); PG8_WAIT_L(0); PG8_BAR; PG8_MMA(1, 0, At, B0); PG8_MMA(1, 1, At, B1); PG8_BAR; PG8_SCHED;
;     ...
;         if constexpr (ALIGN_EPI) { if (wr == 0) PG8_BAR; }
	v_mfma_f32_16x16x32_bf16 v[72:75], v[172:175], v[212:215], v[72:75]
	v_mfma_f32_16x16x32_bf16 v[64:67], v[180:183], v[212:215], v[64:67]
	s_setprio 0
	s_add_i32 s26, s53, s28
	v_lshl_add_u64 v[216:217], v[216:217], 0, s[4:5]
	s_mov_b32 m0, s26
	ds_read_b128 v[184:187], v155 offset:49152
	ds_read_b128 v[188:191], v155 offset:50176
	ds_read_b128 v[192:195], v155 offset:51200
	ds_read_b128 v[196:199], v155 offset:52224
	ds_read_b128 v[200:203], v155 offset:53248
	ds_read_b128 v[204:207], v155 offset:54272
	ds_read_b128 v[208:211], v155 offset:55296
	ds_read_b128 v[212:215], v155 offset:56320
	global_load_lds_dwordx4 v[216:217], off
	s_add_i32 m0, s26, 0x2000
	s_add_u32 s24, s24, 0x80080
	v_lshl_add_u64 v[216:217], v[218:219], 0, s[4:5]
	s_addc_u32 s25, s25, 0
	s_add_i32 s26, s54, s28
	global_load_lds_dwordx4 v[216:217], off
	v_lshl_add_u64 v[216:217], s[24:25], 0, v[134:135]
	s_mov_b32 m0, s26
	s_nop 0
	global_load_lds_dwordx4 v[216:217], off
	v_lshl_add_u64 v[216:217], s[24:25], 0, v[130:131]
	s_add_i32 m0, s26, 0x2000
	s_nop 0
	global_load_lds_dwordx4 v[216:217], off
	v_lshl_add_u64 v[216:217], v[220:221], 0, s[4:5]
	s_mov_b32 m0, s37
	s_nop 0
	global_load_lds_dwordx4 v[216:217], off
	v_lshl_add_u64 v[216:217], v[222:223], 0, s[4:5]
	s_mov_b32 m0, s38
	s_nop 0
	global_load_lds_dwordx4 v[216:217], off
	s_waitcnt vmcnt(8)
	s_waitcnt lgkmcnt(0)
	s_barrier
	s_setprio 1
	s_waitcnt lgkmcnt(0)
	v_mfma_f32_16x16x32_bf16 v[60:63], v[146:149], v[184:187], v[60:63]
	v_mfma_f32_16x16x32_bf16 v[52:55], v[160:163], v[184:187], v[52:55]
	v_mfma_f32_16x16x32_bf16 v[44:47], v[146:149], v[192:195], v[44:47]
	v_mfma_f32_16x16x32_bf16 v[36:39], v[160:163], v[192:195], v[36:39]
	v_mfma_f32_16x16x32_bf16 v[28:31], v[146:149], v[200:203], v[28:31]
	v_mfma_f32_16x16x32_bf16 v[20:23], v[160:163], v[200:203], v[20:23]
	v_mfma_f32_16x16x32_bf16 v[12:15], v[146:149], v[208:211], v[12:15]
	v_mfma_f32_16x16x32_bf16 v[4:7], v[160:163], v[208:211], v[4:7]
	v_mfma_f32_16x16x32_bf16 v[60:63], v[156:159], v[188:191], v[60:63]
	v_mfma_f32_16x16x32_bf16 v[52:55], v[164:167], v[188:191], v[52:55]
	v_mfma_f32_16x16x32_bf16 v[44:47], v[156:159], v[196:199], v[44:47]
	v_mfma_f32_16x16x32_bf16 v[36:39], v[164:167], v[196:199], v[36:39]
	v_mfma_f32_16x16x32_bf16 v[28:31], v[156:159], v[204:207], v[28:31]
	v_mfma_f32_16x16x32_bf16 v[20:23], v[164:167], v[204:207], v[20:23]
	v_mfma_f32_16x16x32_bf16 v[12:15], v[156:159], v[212:215], v[12:15]
	v_mfma_f32_16x16x32_bf16 v[4:7], v[164:167], v[212:215], v[4:7]
	s_setprio 0
	s_setprio 1
	v_mfma_f32_16x16x32_bf16 v[56:59], v[168:171], v[184:187], v[56:59]
	v_mfma_f32_16x16x32_bf16 v[48:51], v[176:179], v[184:187], v[48:51]
	v_mfma_f32_16x16x32_bf16 v[40:43], v[168:171], v[192:195], v[40:43]
	v_mfma_f32_16x16x32_bf16 v[32:35], v[176:179], v[192:195], v[32:35]
	v_mfma_f32_16x16x32_bf16 v[24:27], v[168:171], v[200:203], v[24:27]
	v_mfma_f32_16x16x32_bf16 v[16:19], v[176:179], v[200:203], v[16:19]
	v_mfma_f32_16x16x32_bf16 v[8:11], v[168:171], v[208:211], v[8:11]
	v_mfma_f32_16x16x32_bf16 v[0:3], v[176:179], v[208:211], v[0:3]
	v_mfma_f32_16x16x32_bf16 v[56:59], v[172:175], v[188:191], v[56:59]
	v_mfma_f32_16x16x32_bf16 v[48:51], v[180:183], v[188:191], v[48:51]
	v_mfma_f32_16x16x32_bf16 v[40:43], v[172:175], v[196:199], v[40:43]
	v_mfma_f32_16x16x32_bf16 v[32:35], v[180:183], v[196:199], v[32:35]
	v_mfma_f32_16x16x32_bf16 v[24:27], v[172:175], v[204:207], v[24:27]
	v_mfma_f32_16x16x32_bf16 v[16:19], v[180:183], v[204:207], v[16:19]
	s_setprio 2
	s_barrier
	v_mfma_f32_16x16x32_bf16 v[8:11], v[172:175], v[212:215], v[8:11]
	v_mfma_f32_16x16x32_bf16 v[0:3], v[180:183], v[212:215], v[0:3]
	s_setprio 0
	s_add_i32 s52, s52, 2
	s_add_u32 s22, s22, 0x100
	s_addc_u32 s23, s23, 0
	s_add_u32 s47, s47, 0x100
	s_addc_u32 s51, s51, 0
	s_cmp_gt_u32 s52, 29
	s_cbranch_scc0 .LBB0_966
	s_and_b64 vcc, exec, s[10:11]
	s_cbranch_vccz .LBB0_969
	s_barrier

; #define PG8_STAGE(bufoff, gbase, voff) do { _Pragma("unroll") for (int _i = 0; _i < 2; ++_i) \
;         __builtin_amdgcn_global_load_lds((const unsigned*)((const char*)(gbase) + (voff)[_i]), (PG8_LAS unsigned*)(lds + (bufoff) + ldsw + _i * 8192), 16, 0, 0); } while (0)
; #define PG8_LDA(dst, b, h) do { _Pragma("unroll") for (int m = 0; m < 4; ++m) _Pragma("unroll") for (int k = 0; k < 2; ++k) dst[m][k] = *(const PG8_LAS bf16x8*)(lds + PG8_SA(b, h) + aoff + m * 2048 + k * 1024); } while (0)
; #define PG8_LDB(dst, b, h) do { _Pragma("unroll") for (int n = 0; n < 2; ++n) _Pragma("unroll") for (int k = 0; k < 2; ++k) dst[n][k] = *(const PG8_LAS bf16x8*)(lds + PG8_SB(b, h) + boff + n * 2048 + k * 1024); } while (0)
; #define PG8_MMA(ai, bj, At, Bt) do { __builtin_amdgcn_s_setprio(1); _Pragma("unroll") for (int m = 0; m < 4; ++m) _Pragma("unroll") for (int n = 0; n < 2; ++n) _Pragma("unroll") for (int k = 0; k < 2; ++k) \
;         acc[ai][bj][m][n] = __builtin_amdgcn_mfma_f32_16x16x32_bf16(Bt[n][k], At[m][k], acc[ai][bj][m][n], 0, 0, 0); __builtin_amdgcn_s_setprio(0); } while (0)
; #define PG8_WAIT_V(n) asm volatile("s_waitcnt vmcnt(" #n ")" ::: "memory")
; #define PG8_BAR __builtin_amdgcn_s_barrier()
; template <class Epi, class Sched, bool ALIGN_EPI = false, bool SP2 = false>
; __device__ __forceinline__ void gemm_phase(PG8_LAS unsigned char* lds, const Gemm g, const Sched& S, const Epi& E) {
;     ...
;         for (int t = 0; t < nt; t += 2) {
;             const bool last = (t == nt - 2);
;             const char* a1 = cA + (size_t)(t + 1) * kstep;
;             const char* a2 = last ? nA : cA + (size_t)(t + 2) * kstep; const char* b2 = last ? nB : cB + (size_t)(t + 2) * kstep;
;             const char* a3 = a2 + kstep; const char* b3 = b2 + kstep;
;             if (last && has_next) S.a_ready(nxt);
;             if constexpr (SP2) {
;             PG8_LDB(B0, 0, 0); PG8_LDB(B1, 0, 1); PG8_SCHED; PG8_LDA(At, 0, 0); PG8_STAGE(PG8_SA(1, 1), a1 + hstep, voffA);
;             PG8_WAIT_V(8); PG8_WAIT_L(0); PG8_BAR; PG8_MMA(0, 0, At, B0); PG8_MMA(0, 1, At, B1); PG8_BAR; PG8_SCHED;
;             PG8_LDA(At, 0, 1); PG8_STAGE(PG8_SB(0, 0), b2, voffB); PG8_STAGE(PG8_SB(0, 1), b2 + hstep, voffB); PG8_STAGE(PG8_SA(0, 0), a2, voffA);
;             PG8_WAIT_V(8); PG8_WAIT_L(0); PG8_BAR; PG8_MMA(1, 0, At, B0); PG8_MMA(1, 1, At, B1); PG8_BAR; PG8_SCHED;
.LBB0_1056:
	ds_read_b128 v[158:161], v155
	ds_read_b128 v[162:165], v155 offset:1024
	ds_read_b128 v[166:169], v155 offset:2048
	ds_read_b128 v[170:173], v155 offset:3072
	ds_read_b128 v[174:177], v156
	ds_read_b128 v[178:181], v156 offset:1024
	ds_read_b128 v[182:185], v156 offset:2048
	ds_read_b128 v[186:189], v156 offset:3072
	s_add_u32 s26, s24, 0xffea0080
	s_addc_u32 s27, s25, -1
	s_cmpk_eq_i32 s59, 0x54
	s_cselect_b32 s29, s21, s27
	s_cselect_b32 s28, s20, s26
	s_cselect_b32 s27, s23, s58
	s_cselect_b32 s26, s22, s57
	v_lshl_add_u64 v[222:223], s[24:25], 0, v[138:139]
	s_add_i32 m0, s35, 0xc000
	ds_read_b128 v[190:193], v157
	ds_read_b128 v[194:197], v157 offset:1024
	ds_read_b128 v[198:201], v157 offset:2048
	ds_read_b128 v[202:205], v157 offset:3072
	ds_read_b128 v[206:209], v157 offset:4096
	ds_read_b128 v[210:213], v157 offset:5120
	ds_read_b128 v[214:217], v157 offset:6144
	ds_read_b128 v[218:221], v157 offset:7168
	global_load_lds_dwordx4 v[222:223], off
	v_lshl_add_u64 v[222:223], s[24:25], 0, v[140:141]
	s_add_i32 m0, s35, 0xe000
	s_nop 0
	global_load_lds_dwordx4 v[222:223], off
	s_waitcnt vmcnt(8)
	s_waitcnt lgkmcnt(0)
	s_barrier
	s_setprio 1
	s_waitcnt lgkmcnt(0)
	v_mfma_f32_16x16x32_bf16 v[124:127], v[158:161], v[190:193], v[124:127]
	v_mfma_f32_16x16x32_bf16 v[120:123], v[166:169], v[190:193], v[120:123]
	v_mfma_f32_16x16x32_bf16 v[116:119], v[158:161], v[198:201], v[116:119]
	v_mfma_f32_16x16x32_bf16 v[112:115], v[166:169], v[198:201], v[112:115]
	v_mfma_f32_16x16x32_bf16 v[100:103], v[158:161], v[206:209], v[100:103]
	v_mfma_f32_16x16x32_bf16 v[96:99], v[166:169], v[206:209], v[96:99]
	v_mfma_f32_16x16x32_bf16 v[84:87], v[158:161], v[214:217], v[84:87]
	v_mfma_f32_16x16x32_bf16 v[80:83], v[166:169], v[214:217], v[80:83]
	v_mfma_f32_16x16x32_bf16 v[124:127], v[162:165], v[194:197], v[124:127]
	v_mfma_f32_16x16x32_bf16 v[120:123], v[170:173], v[194:197], v[120:123]
	v_mfma_f32_16x16x32_bf16 v[116:119], v[162:165], v[202:205], v[116:119]
	v_mfma_f32_16x16x32_bf16 v[112:115], v[170:173], v[202:205], v[112:115]
	v_mfma_f32_16x16x32_bf16 v[100:103], v[162:165], v[210:213], v[100:103]
	v_mfma_f32_16x16x32_bf16 v[96:99], v[170:173], v[210:213], v[96:99]
	v_mfma_f32_16x16x32_bf16 v[84:87], v[162:165], v[218:221], v[84:87]
	v_mfma_f32_16x16x32_bf16 v[80:83], v[170:173], v[218:221], v[80:83]
	s_setprio 0
	s_setprio 1
	v_mfma_f32_16x16x32_bf16 v[108:111], v[174:177], v[190:193], v[108:111]
	v_mfma_f32_16x16x32_bf16 v[104:107], v[182:185], v[190:193], v[104:107]
	v_mfma_f32_16x16x32_bf16 v[92:95], v[174:177], v[198:201], v[92:95]
	v_mfma_f32_16x16x32_bf16 v[88:91], v[182:185], v[198:201], v[88:91]
	v_mfma_f32_16x16x32_bf16 v[76:79], v[174:177], v[206:209], v[76:79]
	v_mfma_f32_16x16x32_bf16 v[72:75], v[182:185], v[206:209], v[72:75]
	v_mfma_f32_16x16x32_bf16 v[68:71], v[174:177], v[214:217], v[68:71]
	v_mfma_f32_16x16x32_bf16 v[64:67], v[182:185], v[214:217], v[64:67]
	v_mfma_f32_16x16x32_bf16 v[108:111], v[178:181], v[194:197], v[108:111]
	v_mfma_f32_16x16x32_bf16 v[104:107], v[186:189], v[194:197], v[104:107]
	v_mfma_f32_16x16x32_bf16 v[92:95], v[178:181], v[202:205], v[92:95]
	v_mfma_f32_16x16x32_bf16 v[88:91], v[186:189], v[202:205], v[88:91]
	v_mfma_f32_16x16x32_bf16 v[76:79], v[178:181], v[210:213], v[76:79]
	v_mfma_f32_16x16x32_bf16 v[72:75], v[186:189], v[210:213], v[72:75]
	s_setprio 2
	s_barrier
	v_mfma_f32_16x16x32_bf16 v[68:71], v[178:181], v[218:221], v[68:71]
	v_mfma_f32_16x16x32_bf16 v[64:67], v[186:189], v[218:221], v[64:67]
	s_setprio 0
	s_add_i32 s60, s44, s30
	v_lshl_add_u64 v[222:223], s[26:27], 0, v[132:133]
	s_mov_b32 m0, s60
	ds_read_b128 v[190:193], v157 offset:16384
	ds_read_b128 v[194:197], v157 offset:17408
	ds_read_b128 v[198:201], v157 offset:18432
	ds_read_b128 v[202:205], v157 offset:19456
	ds_read_b128 v[206:209], v157 offset:20480
	ds_read_b128 v[210:213], v157 offset:21504
	ds_read_b128 v[214:217], v157 offset:22528
	ds_read_b128 v[218:221], v157 offset:23552
	global_load_lds_dwordx4 v[222:223], off
	s_add_i32 m0, s60, 0x2000
	s_add_u32 s60, s26, 0x160000
	v_lshl_add_u64 v[224:225], s[26:27], 0, v[136:137]
	s_addc_u32 s61, s27, 0
	s_add_i32 s62, s45, s30
	global_load_lds_dwordx4 v[224:225], off
	v_lshl_add_u64 v[226:227], s[60:61], 0, v[132:133]
	s_mov_b32 m0, s62
	v_lshl_add_u64 v[228:229], s[28:29], 0, v[134:135]
	global_load_lds_dwordx4 v[226:227], off
	v_lshl_add_u64 v[226:227], s[60:61], 0, v[136:137]
	s_add_i32 m0, s62, 0x2000
	s_nop 0
	global_load_lds_dwordx4 v[226:227], off
	v_lshl_add_u64 v[226:227], s[28:29], 0, v[130:131]
	s_mov_b32 m0, s35
	s_nop 0
	global_load_lds_dwordx4 v[226:227], off
	s_mov_b32 m0, s36
	s_nop 0
	global_load_lds_dwordx4 v[228:229], off
	s_waitcnt vmcnt(8)
	s_waitcnt lgkmcnt(0)
	s_barrier
; #define PG8_STAGE(bufoff, gbase, voff) do { _Pragma("unroll") for (int _i = 0; _i < 2; ++_i) \
;         __builtin_amdgcn_global_load_lds((const unsigned*)((const char*)(gbase) + (voff)[_i]), (PG8_LAS unsigned*)(lds + (bufoff) + ldsw + _i * 8192), 16, 0, 0); } while (0)
; #define PG8_LDA(dst, b, h) do { _Pragma("unroll") for (int m = 0; m < 4; ++m) _Pragma("unroll") for (int k = 0; k < 2; ++k) dst[m][k] = *(const PG8_LAS bf16x8*)(lds + PG8_SA(b, h) + aoff + m * 2048 + k * 1024); } while (0)
; #define PG8_LDB(dst, b, h) do { _Pragma("unroll") for (int n = 0; n < 2; ++n) _Pragma("unroll") for (int k = 0; k < 2; ++k) dst[n][k] = *(const PG8_LAS bf16x8*)(lds + PG8_SB(b, h) + boff + n * 2048 + k * 1024); } while (0)
; #define PG8_MMA(ai, bj, At, Bt) do { __builtin_amdgcn_s_setprio(1); _Pragma("unroll") for (int m = 0; m < 4; ++m) _Pragma("unroll") for (int n = 0; n < 2; ++n) _Pragma("unroll") for (int k = 0; k < 2; ++k) \
;         acc[ai][bj][m][n] = __builtin_amdgcn_mfma_f32_16x16x32_bf16(Bt[n][k], At[m][k], acc[ai][bj][m][n], 0, 0, 0); __builtin_amdgcn_s_setprio(0); } while (0)
; #define PG8_WAIT_V(n) asm volatile("s_waitcnt vmcnt(" #n ")" ::: "memory")
; #define PG8_WAIT_L(n) asm volatile("s_waitcnt lgkmcnt(" #n ")" ::: "memory")
; #define PG8_BAR __builtin_amdgcn_s_barrier()
; #define PG8_SCHED __builtin_amdgcn_sched_barrier(0)
; template <class Epi, class Sched, bool ALIGN_EPI = false, bool SP2 = false>
; __device__ __forceinline__ void gemm_phase(PG8_LAS unsigned char* lds, const Gemm g, const Sched& S, const Epi& E) {
;     ...
;             PG8_WAIT_V(8); PG8_WAIT_L(0); PG8_BAR; PG8_MMA(1, 0, At, B0); PG8_MMA(1, 1, At, B1); PG8_BAR; PG8_SCHED;
;             PG8_LDB(B0, 1, 0); PG8_LDB(B1, 1, 1); PG8_SCHED; PG8_LDA(At, 1, 0); PG8_STAGE(PG8_SA(0, 1), a2 + hstep, voffA);
;             PG8_WAIT_V(8); PG8_WAIT_L(0); PG8_BAR; PG8_MMA(0, 0, At, B0); PG8_MMA(0, 1, At, B1); PG8_BAR; PG8_SCHED;
	s_setprio 1
	s_waitcnt lgkmcnt(0)
	v_mfma_f32_16x16x32_bf16 v[60:63], v[158:161], v[190:193], v[60:63]
	v_mfma_f32_16x16x32_bf16 v[56:59], v[166:169], v[190:193], v[56:59]
	v_mfma_f32_16x16x32_bf16 v[52:55], v[158:161], v[198:201], v[52:55]
	v_mfma_f32_16x16x32_bf16 v[48:51], v[166:169], v[198:201], v[48:51]
	v_mfma_f32_16x16x32_bf16 v[36:39], v[158:161], v[206:209], v[36:39]
	v_mfma_f32_16x16x32_bf16 v[32:35], v[166:169], v[206:209], v[32:35]
	v_mfma_f32_16x16x32_bf16 v[20:23], v[158:161], v[214:217], v[20:23]
	v_mfma_f32_16x16x32_bf16 v[16:19], v[166:169], v[214:217], v[16:19]
	v_mfma_f32_16x16x32_bf16 v[60:63], v[162:165], v[194:197], v[60:63]
	v_mfma_f32_16x16x32_bf16 v[56:59], v[170:173], v[194:197], v[56:59]
	v_mfma_f32_16x16x32_bf16 v[52:55], v[162:165], v[202:205], v[52:55]
	v_mfma_f32_16x16x32_bf16 v[48:51], v[170:173], v[202:205], v[48:51]
	v_mfma_f32_16x16x32_bf16 v[36:39], v[162:165], v[210:213], v[36:39]
	v_mfma_f32_16x16x32_bf16 v[32:35], v[170:173], v[210:213], v[32:35]
	v_mfma_f32_16x16x32_bf16 v[20:23], v[162:165], v[218:221], v[20:23]
	v_mfma_f32_16x16x32_bf16 v[16:19], v[170:173], v[218:221], v[16:19]
	s_setprio 0
	s_setprio 1
	v_mfma_f32_16x16x32_bf16 v[44:47], v[174:177], v[190:193], v[44:47]
	v_mfma_f32_16x16x32_bf16 v[40:43], v[182:185], v[190:193], v[40:43]
	v_mfma_f32_16x16x32_bf16 v[28:31], v[174:177], v[198:201], v[28:31]
	v_mfma_f32_16x16x32_bf16 v[24:27], v[182:185], v[198:201], v[24:27]
	v_mfma_f32_16x16x32_bf16 v[12:15], v[174:177], v[206:209], v[12:15]
	v_mfma_f32_16x16x32_bf16 v[8:11], v[182:185], v[206:209], v[8:11]
	v_mfma_f32_16x16x32_bf16 v[4:7], v[174:177], v[214:217], v[4:7]
	v_mfma_f32_16x16x32_bf16 v[0:3], v[182:185], v[214:217], v[0:3]
	v_mfma_f32_16x16x32_bf16 v[44:47], v[178:181], v[194:197], v[44:47]
	v_mfma_f32_16x16x32_bf16 v[40:43], v[186:189], v[194:197], v[40:43]
	v_mfma_f32_16x16x32_bf16 v[28:31], v[178:181], v[202:205], v[28:31]
	v_mfma_f32_16x16x32_bf16 v[24:27], v[186:189], v[202:205], v[24:27]
	v_mfma_f32_16x16x32_bf16 v[12:15], v[178:181], v[210:213], v[12:15]
	v_mfma_f32_16x16x32_bf16 v[8:11], v[186:189], v[210:213], v[8:11]
	s_setprio 2
	s_barrier
	v_mfma_f32_16x16x32_bf16 v[4:7], v[178:181], v[218:221], v[4:7]
	v_mfma_f32_16x16x32_bf16 v[0:3], v[186:189], v[218:221], v[0:3]
	s_setprio 0
	s_add_i32 s60, 0, 0x18000
	s_add_i32 s61, 0, 0x1c000
	v_add_u32_e32 v170, s60, v153
	v_add_u32_e32 v186, s61, v153
	ds_read_b128 v[158:161], v170
	ds_read_b128 v[162:165], v170 offset:1024
	ds_read_b128 v[166:169], v170 offset:2048
	ds_read_b128 v[170:173], v170 offset:3072
	ds_read_b128 v[174:177], v186
	ds_read_b128 v[178:181], v186 offset:1024
	ds_read_b128 v[182:185], v186 offset:2048
	ds_read_b128 v[186:189], v186 offset:3072
	s_add_u32 s28, s28, 0x160000
	s_addc_u32 s29, s29, 0
	s_mov_b32 m0, s37
	v_lshl_add_u64 v[230:231], s[28:29], 0, v[130:131]
	ds_read_b128 v[190:193], v157 offset:32768
	ds_read_b128 v[194:197], v157 offset:33792
	ds_read_b128 v[198:201], v157 offset:34816
	ds_read_b128 v[202:205], v157 offset:35840
	ds_read_b128 v[206:209], v157 offset:36864
	ds_read_b128 v[210:213], v157 offset:37888
	ds_read_b128 v[214:217], v157 offset:38912
	ds_read_b128 v[218:221], v157 offset:39936
	global_load_lds_dwordx4 v[230:231], off
	v_lshl_add_u64 v[230:231], s[28:29], 0, v[134:135]
	s_mov_b32 m0, s38
	s_nop 0
	global_load_lds_dwordx4 v[230:231], off
	s_waitcnt vmcnt(8)
	s_waitcnt lgkmcnt(0)
	s_barrier
	s_setprio 1
	s_waitcnt lgkmcnt(0)
	v_mfma_f32_16x16x32_bf16 v[124:127], v[158:161], v[190:193], v[124:127]
	v_mfma_f32_16x16x32_bf16 v[120:123], v[166:169], v[190:193], v[120:123]
	v_mfma_f32_16x16x32_bf16 v[116:119], v[158:161], v[198:201], v[116:119]
	v_mfma_f32_16x16x32_bf16 v[112:115], v[166:169], v[198:201], v[112:115]
	v_mfma_f32_16x16x32_bf16 v[100:103], v[158:161], v[206:209], v[100:103]
	v_mfma_f32_16x16x32_bf16 v[96:99], v[166:169], v[206:209], v[96:99]
	v_mfma_f32_16x16x32_bf16 v[84:87], v[158:161], v[214:217], v[84:87]
	v_mfma_f32_16x16x32_bf16 v[80:83], v[166:169], v[214:217], v[80:83]
	v_mfma_f32_16x16x32_bf16 v[124:127], v[162:165], v[194:197], v[124:127]
	v_mfma_f32_16x16x32_bf16 v[120:123], v[170:173], v[194:197], v[120:123]
	v_mfma_f32_16x16x32_bf16 v[116:119], v[162:165], v[202:205], v[116:119]
	v_mfma_f32_16x16x32_bf16 v[112:115], v[170:173], v[202:205], v[112:115]
	v_mfma_f32_16x16x32_bf16 v[100:103], v[162:165], v[210:213], v[100:103]
	v_mfma_f32_16x16x32_bf16 v[96:99], v[170:173], v[210:213], v[96:99]
	v_mfma_f32_16x16x32_bf16 v[84:87], v[162:165], v[218:221], v[84:87]
	v_mfma_f32_16x16x32_bf16 v[80:83], v[170:173], v[218:221], v[80:83]
	s_setprio 0
	s_setprio 1
	v_mfma_f32_16x16x32_bf16 v[108:111], v[174:177], v[190:193], v[108:111]
	v_mfma_f32_16x16x32_bf16 v[104:107], v[182:185], v[190:193], v[104:107]
	v_mfma_f32_16x16x32_bf16 v[92:95], v[174:177], v[198:201], v[92:95]
	v_mfma_f32_16x16x32_bf16 v[88:91], v[182:185], v[198:201], v[88:91]
	v_mfma_f32_16x16x32_bf16 v[76:79], v[174:177], v[206:209], v[76:79]
	v_mfma_f32_16x16x32_bf16 v[72:75], v[182:185], v[206:209], v[72:75]
	v_mfma_f32_16x16x32_bf16 v[68:71], v[174:177], v[214:217], v[68:71]
	v_mfma_f32_16x16x32_bf16 v[64:67], v[182:185], v[214:217], v[64:67]
	v_mfma_f32_16x16x32_bf16 v[108:111], v[178:181], v[194:197], v[108:111]
	v_mfma_f32_16x16x32_bf16 v[104:107], v[186:189], v[194:197], v[104:107]
	v_mfma_f32_16x16x32_bf16 v[92:95], v[178:181], v[202:205], v[92:95]
	v_mfma_f32_16x16x32_bf16 v[88:91], v[186:189], v[202:205], v[88:91]
	v_mfma_f32_16x16x32_bf16 v[76:79], v[178:181], v[210:213], v[76:79]
	v_mfma_f32_16x16x32_bf16 v[72:75], v[186:189], v[210:213], v[72:75]
	s_setprio 2
	s_barrier
; #define PG8_STAGE(bufoff, gbase, voff) do { _Pragma("unroll") for (int _i = 0; _i < 2; ++_i) \
;         __builtin_amdgcn_global_load_lds((const unsigned*)((const char*)(gbase) + (voff)[_i]), (PG8_LAS unsigned*)(lds + (bufoff) + ldsw + _i * 8192), 16, 0, 0); } while (0)
; #define PG8_LDA(dst, b, h) do { _Pragma("unroll") for (int m = 0; m < 4; ++m) _Pragma("unroll") for (int k = 0; k < 2; ++k) dst[m][k] = *(const PG8_LAS bf16x8*)(lds + PG8_SA(b, h) + aoff + m * 2048 + k * 1024); } while (0)
; #define PG8_MMA(ai, bj, At, Bt) do { __builtin_amdgcn_s_setprio(1); _Pragma("unroll") for (int m = 0; m < 4; ++m) _Pragma("unroll") for (int n = 0; n < 2; ++n) _Pragma("unroll") for (int k = 0; k < 2; ++k) \
;         acc[ai][bj][m][n] = __builtin_amdgcn_mfma_f32_16x16x32_bf16(Bt[n][k], At[m][k], acc[ai][bj][m][n], 0, 0, 0); __builtin_amdgcn_s_setprio(0); } while (0)
; #define PG8_WAIT_V(n) asm volatile("s_waitcnt vmcnt(" #n ")" ::: "memory")
; #define PG8_WAIT_L(n) asm volatile("s_waitcnt lgkmcnt(" #n ")" ::: "memory")
; #define PG8_BAR __builtin_amdgcn_s_barrier()
; #define PG8_SCHED __builtin_amdgcn_sched_barrier(0)
; template <class Epi, class Sched, bool ALIGN_EPI = false, bool SP2 = false>
; __device__ __forceinline__ void gemm_phase(PG8_LAS unsigned char* lds, const Gemm g, const Sched& S, const Epi& E) {
;     ...
;             PG8_WAIT_V(8); PG8_WAIT_L(0); PG8_BAR; PG8_MMA(0, 0, At, B0); PG8_MMA(0, 1, At, B1); PG8_BAR; PG8_SCHED;
;             PG8_LDA(At, 1, 1); PG8_STAGE(PG8_SB(1, 0), b3, voffB); PG8_STAGE(PG8_SB(1, 1), b3 + hstep, voffB); PG8_STAGE(PG8_SA(1, 0), a3, voffA);
;             PG8_WAIT_V(8); PG8_WAIT_L(0); PG8_BAR; PG8_MMA(1, 0, At, B0); PG8_MMA(1, 1, At, B1); PG8_BAR; PG8_SCHED;
;     ...
;         if constexpr (ALIGN_EPI) { if (wr == 0) PG8_BAR; }
	v_mfma_f32_16x16x32_bf16 v[68:71], v[178:181], v[218:221], v[68:71]
	v_mfma_f32_16x16x32_bf16 v[64:67], v[186:189], v[218:221], v[64:67]
	s_setprio 0
	s_add_i32 s28, s60, s30
	v_lshl_add_u64 v[222:223], v[222:223], 0, s[4:5]
	s_mov_b32 m0, s28
	ds_read_b128 v[190:193], v157 offset:49152
	ds_read_b128 v[194:197], v157 offset:50176
	ds_read_b128 v[198:201], v157 offset:51200
	ds_read_b128 v[202:205], v157 offset:52224
	ds_read_b128 v[206:209], v157 offset:53248
	ds_read_b128 v[210:213], v157 offset:54272
	ds_read_b128 v[214:217], v157 offset:55296
	ds_read_b128 v[218:221], v157 offset:56320
	global_load_lds_dwordx4 v[222:223], off
	s_add_i32 m0, s28, 0x2000
	s_add_u32 s26, s26, 0x160080
	v_lshl_add_u64 v[222:223], v[224:225], 0, s[4:5]
	s_addc_u32 s27, s27, 0
	s_add_i32 s28, s61, s30
	global_load_lds_dwordx4 v[222:223], off
	v_lshl_add_u64 v[222:223], s[26:27], 0, v[132:133]
	s_mov_b32 m0, s28
	s_nop 0
	global_load_lds_dwordx4 v[222:223], off
	v_lshl_add_u64 v[222:223], s[26:27], 0, v[136:137]
	s_add_i32 m0, s28, 0x2000
	s_nop 0
	global_load_lds_dwordx4 v[222:223], off
	v_lshl_add_u64 v[222:223], v[226:227], 0, s[4:5]
	s_mov_b32 m0, s40
	s_nop 0
	global_load_lds_dwordx4 v[222:223], off
	v_lshl_add_u64 v[222:223], v[228:229], 0, s[4:5]
	s_mov_b32 m0, s41
	s_nop 0
	global_load_lds_dwordx4 v[222:223], off
	s_waitcnt vmcnt(8)
	s_waitcnt lgkmcnt(0)
	s_barrier
	s_setprio 1
	s_waitcnt lgkmcnt(0)
	v_mfma_f32_16x16x32_bf16 v[60:63], v[158:161], v[190:193], v[60:63]
	v_mfma_f32_16x16x32_bf16 v[56:59], v[166:169], v[190:193], v[56:59]
	v_mfma_f32_16x16x32_bf16 v[52:55], v[158:161], v[198:201], v[52:55]
	v_mfma_f32_16x16x32_bf16 v[48:51], v[166:169], v[198:201], v[48:51]
	v_mfma_f32_16x16x32_bf16 v[36:39], v[158:161], v[206:209], v[36:39]
	v_mfma_f32_16x16x32_bf16 v[32:35], v[166:169], v[206:209], v[32:35]
	v_mfma_f32_16x16x32_bf16 v[20:23], v[158:161], v[214:217], v[20:23]
	v_mfma_f32_16x16x32_bf16 v[16:19], v[166:169], v[214:217], v[16:19]
	v_mfma_f32_16x16x32_bf16 v[60:63], v[162:165], v[194:197], v[60:63]
	v_mfma_f32_16x16x32_bf16 v[56:59], v[170:173], v[194:197], v[56:59]
	v_mfma_f32_16x16x32_bf16 v[52:55], v[162:165], v[202:205], v[52:55]
	v_mfma_f32_16x16x32_bf16 v[48:51], v[170:173], v[202:205], v[48:51]
	v_mfma_f32_16x16x32_bf16 v[36:39], v[162:165], v[210:213], v[36:39]
	v_mfma_f32_16x16x32_bf16 v[32:35], v[170:173], v[210:213], v[32:35]
	v_mfma_f32_16x16x32_bf16 v[20:23], v[162:165], v[218:221], v[20:23]
	v_mfma_f32_16x16x32_bf16 v[16:19], v[170:173], v[218:221], v[16:19]
	s_setprio 0
	s_setprio 1
	v_mfma_f32_16x16x32_bf16 v[44:47], v[174:177], v[190:193], v[44:47]
	v_mfma_f32_16x16x32_bf16 v[40:43], v[182:185], v[190:193], v[40:43]
	v_mfma_f32_16x16x32_bf16 v[28:31], v[174:177], v[198:201], v[28:31]
	v_mfma_f32_16x16x32_bf16 v[24:27], v[182:185], v[198:201], v[24:27]
	v_mfma_f32_16x16x32_bf16 v[12:15], v[174:177], v[206:209], v[12:15]
	v_mfma_f32_16x16x32_bf16 v[8:11], v[182:185], v[206:209], v[8:11]
	v_mfma_f32_16x16x32_bf16 v[4:7], v[174:177], v[214:217], v[4:7]
	v_mfma_f32_16x16x32_bf16 v[0:3], v[182:185], v[214:217], v[0:3]
	v_mfma_f32_16x16x32_bf16 v[44:47], v[178:181], v[194:197], v[44:47]
	v_mfma_f32_16x16x32_bf16 v[40:43], v[186:189], v[194:197], v[40:43]
	v_mfma_f32_16x16x32_bf16 v[28:31], v[178:181], v[202:205], v[28:31]
	v_mfma_f32_16x16x32_bf16 v[24:27], v[186:189], v[202:205], v[24:27]
	v_mfma_f32_16x16x32_bf16 v[12:15], v[178:181], v[210:213], v[12:15]
	v_mfma_f32_16x16x32_bf16 v[8:11], v[186:189], v[210:213], v[8:11]
	s_setprio 2
	s_barrier
	v_mfma_f32_16x16x32_bf16 v[4:7], v[178:181], v[218:221], v[4:7]
	v_mfma_f32_16x16x32_bf16 v[0:3], v[186:189], v[218:221], v[0:3]
	s_setprio 0
	s_add_i32 s59, s59, 2
	s_add_u32 s24, s24, 0x100
	s_addc_u32 s25, s25, 0
	s_add_u32 s57, s57, 0x100
	s_addc_u32 s58, s58, 0
	s_cmpk_gt_u32 s59, 0x55
	s_cbranch_scc0 .LBB0_1056
	s_and_b64 vcc, exec, s[10:11]
	s_cbranch_vccz .LBB0_1059
	s_barrier

; #define PG8_STAGE(bufoff, gbase, voff) do { _Pragma("unroll") for (int _i = 0; _i < 2; ++_i) \
;         __builtin_amdgcn_global_load_lds((const unsigned*)((const char*)(gbase) + (voff)[_i]), (PG8_LAS unsigned*)(lds + (bufoff) + ldsw + _i * 8192), 16, 0, 0); } while (0)
; #define PG8_LDA(dst, b, h) do { _Pragma("unroll") for (int m = 0; m < 4; ++m) _Pragma("unroll") for (int k = 0; k < 2; ++k) dst[m][k] = *(const PG8_LAS bf16x8*)(lds + PG8_SA(b, h) + aoff + m * 2048 + k * 1024); } while (0)
; #define PG8_LDB(dst, b, h) do { _Pragma("unroll") for (int n = 0; n < 2; ++n) _Pragma("unroll") for (int k = 0; k < 2; ++k) dst[n][k] = *(const PG8_LAS bf16x8*)(lds + PG8_SB(b, h) + boff + n * 2048 + k * 1024); } while (0)
; #define PG8_MMA(ai, bj, At, Bt) do { __builtin_amdgcn_s_setprio(1); _Pragma("unroll") for (int m = 0; m < 4; ++m) _Pragma("unroll") for (int n = 0; n < 2; ++n) _Pragma("unroll") for (int k = 0; k < 2; ++k) \
;         acc[ai][bj][m][n] = __builtin_amdgcn_mfma_f32_16x16x32_bf16(Bt[n][k], At[m][k], acc[ai][bj][m][n], 0, 0, 0); __builtin_amdgcn_s_setprio(0); } while (0)
; #define PG8_WAIT_V(n) asm volatile("s_waitcnt vmcnt(" #n ")" ::: "memory")
; #define PG8_BAR __builtin_amdgcn_s_barrier()
; template <class Epi, class Sched, bool ALIGN_EPI = false, bool SP2 = false>
; __device__ __forceinline__ void gemm_phase(PG8_LAS unsigned char* lds, const Gemm g, const Sched& S, const Epi& E) {
;     ...
;         for (int t = 0; t < nt; t += 2) {
;             const bool last = (t == nt - 2);
;             const char* a1 = cA + (size_t)(t + 1) * kstep;
;             const char* a2 = last ? nA : cA + (size_t)(t + 2) * kstep; const char* b2 = last ? nB : cB + (size_t)(t + 2) * kstep;
;             const char* a3 = a2 + kstep; const char* b3 = b2 + kstep;
;             if (last && has_next) S.a_ready(nxt);
;             if constexpr (SP2) {
;             PG8_LDB(B0, 0, 0); PG8_LDB(B1, 0, 1); PG8_SCHED; PG8_LDA(At, 0, 0); PG8_STAGE(PG8_SA(1, 1), a1 + hstep, voffA);
;             PG8_WAIT_V(8); PG8_WAIT_L(0); PG8_BAR; PG8_MMA(0, 0, At, B0); PG8_MMA(0, 1, At, B1); PG8_BAR; PG8_SCHED;
;             PG8_LDA(At, 0, 1); PG8_STAGE(PG8_SB(0, 0), b2, voffB); PG8_STAGE(PG8_SB(0, 1), b2 + hstep, voffB); PG8_STAGE(PG8_SA(0, 0), a2, voffA);
;             PG8_WAIT_V(8); PG8_WAIT_L(0); PG8_BAR; PG8_MMA(1, 0, At, B0); PG8_MMA(1, 1, At, B1); PG8_BAR; PG8_SCHED;
.LBB0_1068:
	ds_read_b128 v[150:153], v139
	ds_read_b128 v[154:157], v139 offset:1024
	ds_read_b128 v[158:161], v139 offset:2048
	ds_read_b128 v[162:165], v139 offset:3072
	ds_read_b128 v[166:169], v145
	ds_read_b128 v[170:173], v145 offset:1024
	ds_read_b128 v[174:177], v145 offset:2048
	ds_read_b128 v[178:181], v145 offset:3072
	s_add_u32 s14, s10, s12
	s_addc_u32 s15, s11, s13
	s_add_u32 s14, s14, 0x13500100
	s_addc_u32 s15, s15, 0
	s_add_u32 s40, s26, s12
	s_addc_u32 s41, s27, s13
	s_cmpk_eq_i32 s12, 0x1500
	s_cselect_b32 s17, s5, s15
	s_cselect_b32 s16, s4, s14
	s_cselect_b32 s15, s3, s41
	s_cselect_b32 s14, s2, s40
	s_mov_b32 m0, s29
	v_lshl_add_u64 v[214:215], v[140:141], 0, s[12:13]
	ds_read_b128 v[182:185], v146
	ds_read_b128 v[186:189], v146 offset:1024
	ds_read_b128 v[190:193], v146 offset:2048
	ds_read_b128 v[194:197], v146 offset:3072
	ds_read_b128 v[198:201], v146 offset:4096
	ds_read_b128 v[202:205], v146 offset:5120
	ds_read_b128 v[206:209], v146 offset:6144
	ds_read_b128 v[210:213], v146 offset:7168
	global_load_lds_dwordx4 v[214:215], off
	v_lshl_add_u64 v[214:215], v[142:143], 0, s[12:13]
	s_mov_b32 m0, s30
	s_nop 0
	global_load_lds_dwordx4 v[214:215], off
	s_waitcnt vmcnt(8)
	s_waitcnt lgkmcnt(0)
	s_barrier
	s_setprio 1
	s_waitcnt lgkmcnt(0)
	v_mfma_f32_16x16x32_bf16 v[124:127], v[150:153], v[182:185], v[124:127]
	v_mfma_f32_16x16x32_bf16 v[120:123], v[158:161], v[182:185], v[120:123]
	v_mfma_f32_16x16x32_bf16 v[116:119], v[150:153], v[190:193], v[116:119]
	v_mfma_f32_16x16x32_bf16 v[112:115], v[158:161], v[190:193], v[112:115]
	v_mfma_f32_16x16x32_bf16 v[108:111], v[150:153], v[198:201], v[108:111]
	v_mfma_f32_16x16x32_bf16 v[104:107], v[158:161], v[198:201], v[104:107]
	v_mfma_f32_16x16x32_bf16 v[96:99], v[150:153], v[206:209], v[96:99]
	v_mfma_f32_16x16x32_bf16 v[88:91], v[158:161], v[206:209], v[88:91]
	v_mfma_f32_16x16x32_bf16 v[124:127], v[154:157], v[186:189], v[124:127]
	v_mfma_f32_16x16x32_bf16 v[120:123], v[162:165], v[186:189], v[120:123]
	v_mfma_f32_16x16x32_bf16 v[116:119], v[154:157], v[194:197], v[116:119]
	v_mfma_f32_16x16x32_bf16 v[112:115], v[162:165], v[194:197], v[112:115]
	v_mfma_f32_16x16x32_bf16 v[108:111], v[154:157], v[202:205], v[108:111]
	v_mfma_f32_16x16x32_bf16 v[104:107], v[162:165], v[202:205], v[104:107]
	v_mfma_f32_16x16x32_bf16 v[96:99], v[154:157], v[210:213], v[96:99]
	v_mfma_f32_16x16x32_bf16 v[88:91], v[162:165], v[210:213], v[88:91]
	s_setprio 0
	s_setprio 1
	v_mfma_f32_16x16x32_bf16 v[100:103], v[166:169], v[182:185], v[100:103]
	v_mfma_f32_16x16x32_bf16 v[92:95], v[174:177], v[182:185], v[92:95]
	v_mfma_f32_16x16x32_bf16 v[84:87], v[166:169], v[190:193], v[84:87]
	v_mfma_f32_16x16x32_bf16 v[80:83], v[174:177], v[190:193], v[80:83]
	v_mfma_f32_16x16x32_bf16 v[76:79], v[166:169], v[198:201], v[76:79]
	v_mfma_f32_16x16x32_bf16 v[72:75], v[174:177], v[198:201], v[72:75]
	v_mfma_f32_16x16x32_bf16 v[68:71], v[166:169], v[206:209], v[68:71]
	v_mfma_f32_16x16x32_bf16 v[64:67], v[174:177], v[206:209], v[64:67]
	v_mfma_f32_16x16x32_bf16 v[100:103], v[170:173], v[186:189], v[100:103]
	v_mfma_f32_16x16x32_bf16 v[92:95], v[178:181], v[186:189], v[92:95]
	v_mfma_f32_16x16x32_bf16 v[84:87], v[170:173], v[194:197], v[84:87]
	v_mfma_f32_16x16x32_bf16 v[80:83], v[178:181], v[194:197], v[80:83]
	v_mfma_f32_16x16x32_bf16 v[76:79], v[170:173], v[202:205], v[76:79]
	v_mfma_f32_16x16x32_bf16 v[72:75], v[178:181], v[202:205], v[72:75]
	s_setprio 2
	s_barrier
	v_mfma_f32_16x16x32_bf16 v[68:71], v[170:173], v[210:213], v[68:71]
	v_mfma_f32_16x16x32_bf16 v[64:67], v[178:181], v[210:213], v[64:67]
	s_setprio 0
	s_mov_b32 m0, s31
	v_lshl_add_u64 v[214:215], s[14:15], 0, v[132:133]
	s_add_u32 s40, s14, 0x160000
	ds_read_b128 v[182:185], v146 offset:16384
	ds_read_b128 v[186:189], v146 offset:17408
	ds_read_b128 v[190:193], v146 offset:18432
	ds_read_b128 v[194:197], v146 offset:19456
	ds_read_b128 v[198:201], v146 offset:20480
	ds_read_b128 v[202:205], v146 offset:21504
	ds_read_b128 v[206:209], v146 offset:22528
	ds_read_b128 v[210:213], v146 offset:23552
	global_load_lds_dwordx4 v[214:215], off
	v_lshl_add_u64 v[216:217], s[14:15], 0, v[136:137]
	s_mov_b32 m0, s33
	s_addc_u32 s41, s15, 0
	global_load_lds_dwordx4 v[216:217], off
	v_lshl_add_u64 v[218:219], s[40:41], 0, v[132:133]
	s_mov_b32 m0, s34
	v_lshl_add_u64 v[220:221], s[16:17], 0, v[134:135]
	global_load_lds_dwordx4 v[218:219], off
	v_lshl_add_u64 v[218:219], s[40:41], 0, v[136:137]
	s_mov_b32 m0, s35
	s_nop 0
	global_load_lds_dwordx4 v[218:219], off
	v_lshl_add_u64 v[218:219], s[16:17], 0, v[130:131]
	s_mov_b32 m0, s19
	s_nop 0
	global_load_lds_dwordx4 v[218:219], off
	s_mov_b32 m0, s20
	s_nop 0
	global_load_lds_dwordx4 v[220:221], off
	s_waitcnt vmcnt(8)
	s_waitcnt lgkmcnt(0)
	s_barrier
; #define PG8_STAGE(bufoff, gbase, voff) do { _Pragma("unroll") for (int _i = 0; _i < 2; ++_i) \
;         __builtin_amdgcn_global_load_lds((const unsigned*)((const char*)(gbase) + (voff)[_i]), (PG8_LAS unsigned*)(lds + (bufoff) + ldsw + _i * 8192), 16, 0, 0); } while (0)
; #define PG8_LDA(dst, b, h) do { _Pragma("unroll") for (int m = 0; m < 4; ++m) _Pragma("unroll") for (int k = 0; k < 2; ++k) dst[m][k] = *(const PG8_LAS bf16x8*)(lds + PG8_SA(b, h) + aoff + m * 2048 + k * 1024); } while (0)
; #define PG8_LDB(dst, b, h) do { _Pragma("unroll") for (int n = 0; n < 2; ++n) _Pragma("unroll") for (int k = 0; k < 2; ++k) dst[n][k] = *(const PG8_LAS bf16x8*)(lds + PG8_SB(b, h) + boff + n * 2048 + k * 1024); } while (0)
; #define PG8_MMA(ai, bj, At, Bt) do { __builtin_amdgcn_s_setprio(1); _Pragma("unroll") for (int m = 0; m < 4; ++m) _Pragma("unroll") for (int n = 0; n < 2; ++n) _Pragma("unroll") for (int k = 0; k < 2; ++k) \
;         acc[ai][bj][m][n] = __builtin_amdgcn_mfma_f32_16x16x32_bf16(Bt[n][k], At[m][k], acc[ai][bj][m][n], 0, 0, 0); __builtin_amdgcn_s_setprio(0); } while (0)
; #define PG8_WAIT_V(n) asm volatile("s_waitcnt vmcnt(" #n ")" ::: "memory")
; #define PG8_WAIT_L(n) asm volatile("s_waitcnt lgkmcnt(" #n ")" ::: "memory")
; #define PG8_BAR __builtin_amdgcn_s_barrier()
; #define PG8_SCHED __builtin_amdgcn_sched_barrier(0)
; template <class Epi, class Sched, bool ALIGN_EPI = false, bool SP2 = false>
; __device__ __forceinline__ void gemm_phase(PG8_LAS unsigned char* lds, const Gemm g, const Sched& S, const Epi& E) {
;     ...
;             PG8_WAIT_V(8); PG8_WAIT_L(0); PG8_BAR; PG8_MMA(1, 0, At, B0); PG8_MMA(1, 1, At, B1); PG8_BAR; PG8_SCHED;
;             PG8_LDB(B0, 1, 0); PG8_LDB(B1, 1, 1); PG8_SCHED; PG8_LDA(At, 1, 0); PG8_STAGE(PG8_SA(0, 1), a2 + hstep, voffA);
;             PG8_WAIT_V(8); PG8_WAIT_L(0); PG8_BAR; PG8_MMA(0, 0, At, B0); PG8_MMA(0, 1, At, B1); PG8_BAR; PG8_SCHED;
	s_setprio 1
	s_waitcnt lgkmcnt(0)
	v_mfma_f32_16x16x32_bf16 v[60:63], v[150:153], v[182:185], v[60:63]
	v_mfma_f32_16x16x32_bf16 v[56:59], v[158:161], v[182:185], v[56:59]
	v_mfma_f32_16x16x32_bf16 v[52:55], v[150:153], v[190:193], v[52:55]
	v_mfma_f32_16x16x32_bf16 v[48:51], v[158:161], v[190:193], v[48:51]
	v_mfma_f32_16x16x32_bf16 v[44:47], v[150:153], v[198:201], v[44:47]
	v_mfma_f32_16x16x32_bf16 v[40:43], v[158:161], v[198:201], v[40:43]
	v_mfma_f32_16x16x32_bf16 v[32:35], v[150:153], v[206:209], v[32:35]
	v_mfma_f32_16x16x32_bf16 v[24:27], v[158:161], v[206:209], v[24:27]
	v_mfma_f32_16x16x32_bf16 v[60:63], v[154:157], v[186:189], v[60:63]
	v_mfma_f32_16x16x32_bf16 v[56:59], v[162:165], v[186:189], v[56:59]
	v_mfma_f32_16x16x32_bf16 v[52:55], v[154:157], v[194:197], v[52:55]
	v_mfma_f32_16x16x32_bf16 v[48:51], v[162:165], v[194:197], v[48:51]
	v_mfma_f32_16x16x32_bf16 v[44:47], v[154:157], v[202:205], v[44:47]
	v_mfma_f32_16x16x32_bf16 v[40:43], v[162:165], v[202:205], v[40:43]
	v_mfma_f32_16x16x32_bf16 v[32:35], v[154:157], v[210:213], v[32:35]
	v_mfma_f32_16x16x32_bf16 v[24:27], v[162:165], v[210:213], v[24:27]
	s_setprio 0
	s_setprio 1
	v_mfma_f32_16x16x32_bf16 v[36:39], v[166:169], v[182:185], v[36:39]
	v_mfma_f32_16x16x32_bf16 v[28:31], v[174:177], v[182:185], v[28:31]
	v_mfma_f32_16x16x32_bf16 v[20:23], v[166:169], v[190:193], v[20:23]
	v_mfma_f32_16x16x32_bf16 v[16:19], v[174:177], v[190:193], v[16:19]
	v_mfma_f32_16x16x32_bf16 v[12:15], v[166:169], v[198:201], v[12:15]
	v_mfma_f32_16x16x32_bf16 v[8:11], v[174:177], v[198:201], v[8:11]
	v_mfma_f32_16x16x32_bf16 v[4:7], v[166:169], v[206:209], v[4:7]
	v_mfma_f32_16x16x32_bf16 v[0:3], v[174:177], v[206:209], v[0:3]
	v_mfma_f32_16x16x32_bf16 v[36:39], v[170:173], v[186:189], v[36:39]
	v_mfma_f32_16x16x32_bf16 v[28:31], v[178:181], v[186:189], v[28:31]
	v_mfma_f32_16x16x32_bf16 v[20:23], v[170:173], v[194:197], v[20:23]
	v_mfma_f32_16x16x32_bf16 v[16:19], v[178:181], v[194:197], v[16:19]
	v_mfma_f32_16x16x32_bf16 v[12:15], v[170:173], v[202:205], v[12:15]
	v_mfma_f32_16x16x32_bf16 v[8:11], v[178:181], v[202:205], v[8:11]
	s_setprio 2
	s_barrier
	v_mfma_f32_16x16x32_bf16 v[4:7], v[170:173], v[210:213], v[4:7]
	v_mfma_f32_16x16x32_bf16 v[0:3], v[178:181], v[210:213], v[0:3]
	s_setprio 0
	ds_read_b128 v[150:153], v147
	ds_read_b128 v[154:157], v147 offset:1024
	ds_read_b128 v[158:161], v147 offset:2048
	ds_read_b128 v[162:165], v147 offset:3072
	ds_read_b128 v[166:169], v148
	ds_read_b128 v[170:173], v148 offset:1024
	ds_read_b128 v[174:177], v148 offset:2048
	ds_read_b128 v[178:181], v148 offset:3072
	s_add_u32 s16, s16, 0x160000
	s_addc_u32 s17, s17, 0
	s_mov_b32 m0, s21
	v_lshl_add_u64 v[222:223], s[16:17], 0, v[130:131]
	ds_read_b128 v[182:185], v146 offset:32768
	ds_read_b128 v[186:189], v146 offset:33792
	ds_read_b128 v[190:193], v146 offset:34816
	ds_read_b128 v[194:197], v146 offset:35840
	ds_read_b128 v[198:201], v146 offset:36864
	ds_read_b128 v[202:205], v146 offset:37888
	ds_read_b128 v[206:209], v146 offset:38912
	ds_read_b128 v[210:213], v146 offset:39936
	global_load_lds_dwordx4 v[222:223], off
	v_lshl_add_u64 v[222:223], s[16:17], 0, v[134:135]
	s_mov_b32 m0, s22
	s_nop 0
	global_load_lds_dwordx4 v[222:223], off
	s_waitcnt vmcnt(8)
	s_waitcnt lgkmcnt(0)
	s_barrier
	s_setprio 1
	s_waitcnt lgkmcnt(0)
	v_mfma_f32_16x16x32_bf16 v[124:127], v[150:153], v[182:185], v[124:127]
	v_mfma_f32_16x16x32_bf16 v[120:123], v[158:161], v[182:185], v[120:123]
	v_mfma_f32_16x16x32_bf16 v[116:119], v[150:153], v[190:193], v[116:119]
	v_mfma_f32_16x16x32_bf16 v[112:115], v[158:161], v[190:193], v[112:115]
	v_mfma_f32_16x16x32_bf16 v[108:111], v[150:153], v[198:201], v[108:111]
	v_mfma_f32_16x16x32_bf16 v[104:107], v[158:161], v[198:201], v[104:107]
	v_mfma_f32_16x16x32_bf16 v[96:99], v[150:153], v[206:209], v[96:99]
	v_mfma_f32_16x16x32_bf16 v[88:91], v[158:161], v[206:209], v[88:91]
	v_mfma_f32_16x16x32_bf16 v[124:127], v[154:157], v[186:189], v[124:127]
	v_mfma_f32_16x16x32_bf16 v[120:123], v[162:165], v[186:189], v[120:123]
	v_mfma_f32_16x16x32_bf16 v[116:119], v[154:157], v[194:197], v[116:119]
	v_mfma_f32_16x16x32_bf16 v[112:115], v[162:165], v[194:197], v[112:115]
	v_mfma_f32_16x16x32_bf16 v[108:111], v[154:157], v[202:205], v[108:111]
	v_mfma_f32_16x16x32_bf16 v[104:107], v[162:165], v[202:205], v[104:107]
	v_mfma_f32_16x16x32_bf16 v[96:99], v[154:157], v[210:213], v[96:99]
	v_mfma_f32_16x16x32_bf16 v[88:91], v[162:165], v[210:213], v[88:91]
	s_setprio 0
	s_setprio 1
	v_mfma_f32_16x16x32_bf16 v[100:103], v[166:169], v[182:185], v[100:103]
	v_mfma_f32_16x16x32_bf16 v[92:95], v[174:177], v[182:185], v[92:95]
	v_mfma_f32_16x16x32_bf16 v[84:87], v[166:169], v[190:193], v[84:87]
	v_mfma_f32_16x16x32_bf16 v[80:83], v[174:177], v[190:193], v[80:83]
	v_mfma_f32_16x16x32_bf16 v[76:79], v[166:169], v[198:201], v[76:79]
	v_mfma_f32_16x16x32_bf16 v[72:75], v[174:177], v[198:201], v[72:75]
	v_mfma_f32_16x16x32_bf16 v[68:71], v[166:169], v[206:209], v[68:71]
	v_mfma_f32_16x16x32_bf16 v[64:67], v[174:177], v[206:209], v[64:67]
	v_mfma_f32_16x16x32_bf16 v[100:103], v[170:173], v[186:189], v[100:103]
	v_mfma_f32_16x16x32_bf16 v[92:95], v[178:181], v[186:189], v[92:95]
	v_mfma_f32_16x16x32_bf16 v[84:87], v[170:173], v[194:197], v[84:87]
	v_mfma_f32_16x16x32_bf16 v[80:83], v[178:181], v[194:197], v[80:83]
	v_mfma_f32_16x16x32_bf16 v[76:79], v[170:173], v[202:205], v[76:79]
	v_mfma_f32_16x16x32_bf16 v[72:75], v[178:181], v[202:205], v[72:75]
	s_setprio 2
	s_barrier
; #define PG8_STAGE(bufoff, gbase, voff) do { _Pragma("unroll") for (int _i = 0; _i < 2; ++_i) \
;         __builtin_amdgcn_global_load_lds((const unsigned*)((const char*)(gbase) + (voff)[_i]), (PG8_LAS unsigned*)(lds + (bufoff) + ldsw + _i * 8192), 16, 0, 0); } while (0)
; #define PG8_LDA(dst, b, h) do { _Pragma("unroll") for (int m = 0; m < 4; ++m) _Pragma("unroll") for (int k = 0; k < 2; ++k) dst[m][k] = *(const PG8_LAS bf16x8*)(lds + PG8_SA(b, h) + aoff + m * 2048 + k * 1024); } while (0)
; #define PG8_LDB(dst, b, h) do { _Pragma("unroll") for (int n = 0; n < 2; ++n) _Pragma("unroll") for (int k = 0; k < 2; ++k) dst[n][k] = *(const PG8_LAS bf16x8*)(lds + PG8_SB(b, h) + boff + n * 2048 + k * 1024); } while (0)
; #define PG8_MMA(ai, bj, At, Bt) do { __builtin_amdgcn_s_setprio(1); _Pragma("unroll") for (int m = 0; m < 4; ++m) _Pragma("unroll") for (int n = 0; n < 2; ++n) _Pragma("unroll") for (int k = 0; k < 2; ++k) \
;         acc[ai][bj][m][n] = __builtin_amdgcn_mfma_f32_16x16x32_bf16(Bt[n][k], At[m][k], acc[ai][bj][m][n], 0, 0, 0); __builtin_amdgcn_s_setprio(0); } while (0)
; #define PG8_WAIT_V(n) asm volatile("s_waitcnt vmcnt(" #n ")" ::: "memory")
; #define PG8_WAIT_L(n) asm volatile("s_waitcnt lgkmcnt(" #n ")" ::: "memory")
; #define PG8_BAR __builtin_amdgcn_s_barrier()
; #define PG8_SCHED __builtin_amdgcn_sched_barrier(0)
; template <class Epi, class Sched, bool ALIGN_EPI = false, bool SP2 = false>
; __device__ __forceinline__ void gemm_phase(PG8_LAS unsigned char* lds, const Gemm g, const Sched& S, const Epi& E) {
;     ...
;             PG8_LDB(B0, 1, 0); PG8_LDB(B1, 1, 1); PG8_SCHED; PG8_LDA(At, 1, 0); PG8_STAGE(PG8_SA(0, 1), a2 + hstep, voffA);
;             PG8_WAIT_V(8); PG8_WAIT_L(0); PG8_BAR; PG8_MMA(0, 0, At, B0); PG8_MMA(0, 1, At, B1); PG8_BAR; PG8_SCHED;
;             PG8_LDA(At, 1, 1); PG8_STAGE(PG8_SB(1, 0), b3, voffB); PG8_STAGE(PG8_SB(1, 1), b3 + hstep, voffB); PG8_STAGE(PG8_SA(1, 0), a3, voffA);
;             PG8_WAIT_V(8); PG8_WAIT_L(0); PG8_BAR; PG8_MMA(1, 0, At, B0); PG8_MMA(1, 1, At, B1); PG8_BAR; PG8_SCHED;
;     ...
;         if constexpr (ALIGN_EPI) { if (wr == 0) PG8_BAR; }
	v_mfma_f32_16x16x32_bf16 v[68:71], v[170:173], v[210:213], v[68:71]
	v_mfma_f32_16x16x32_bf16 v[64:67], v[178:181], v[210:213], v[64:67]
	s_setprio 0
	s_mov_b32 m0, s36
	v_lshl_add_u64 v[214:215], v[214:215], 0, s[6:7]
	s_add_u32 s14, s14, 0x160080
	ds_read_b128 v[182:185], v146 offset:49152
	ds_read_b128 v[186:189], v146 offset:50176
	ds_read_b128 v[190:193], v146 offset:51200
	ds_read_b128 v[194:197], v146 offset:52224
	ds_read_b128 v[198:201], v146 offset:53248
	ds_read_b128 v[202:205], v146 offset:54272
	ds_read_b128 v[206:209], v146 offset:55296
	ds_read_b128 v[210:213], v146 offset:56320
	global_load_lds_dwordx4 v[214:215], off
	v_lshl_add_u64 v[214:215], v[216:217], 0, s[6:7]
	s_mov_b32 m0, s37
	s_addc_u32 s15, s15, 0
	global_load_lds_dwordx4 v[214:215], off
	v_lshl_add_u64 v[214:215], s[14:15], 0, v[132:133]
	s_mov_b32 m0, s38
	s_nop 0
	global_load_lds_dwordx4 v[214:215], off
	v_lshl_add_u64 v[214:215], s[14:15], 0, v[136:137]
	s_mov_b32 m0, s39
	s_nop 0
	global_load_lds_dwordx4 v[214:215], off
	v_lshl_add_u64 v[214:215], v[218:219], 0, s[6:7]
	s_mov_b32 m0, s24
	s_nop 0
	global_load_lds_dwordx4 v[214:215], off
	v_lshl_add_u64 v[214:215], v[220:221], 0, s[6:7]
	s_mov_b32 m0, s25
	s_nop 0
	global_load_lds_dwordx4 v[214:215], off
	s_waitcnt vmcnt(8)
	s_waitcnt lgkmcnt(0)
	s_barrier
	s_setprio 1
	s_waitcnt lgkmcnt(0)
	v_mfma_f32_16x16x32_bf16 v[60:63], v[150:153], v[182:185], v[60:63]
	v_mfma_f32_16x16x32_bf16 v[56:59], v[158:161], v[182:185], v[56:59]
	v_mfma_f32_16x16x32_bf16 v[52:55], v[150:153], v[190:193], v[52:55]
	v_mfma_f32_16x16x32_bf16 v[48:51], v[158:161], v[190:193], v[48:51]
	v_mfma_f32_16x16x32_bf16 v[44:47], v[150:153], v[198:201], v[44:47]
	v_mfma_f32_16x16x32_bf16 v[40:43], v[158:161], v[198:201], v[40:43]
	v_mfma_f32_16x16x32_bf16 v[32:35], v[150:153], v[206:209], v[32:35]
	v_mfma_f32_16x16x32_bf16 v[24:27], v[158:161], v[206:209], v[24:27]
	v_mfma_f32_16x16x32_bf16 v[60:63], v[154:157], v[186:189], v[60:63]
	v_mfma_f32_16x16x32_bf16 v[56:59], v[162:165], v[186:189], v[56:59]
	v_mfma_f32_16x16x32_bf16 v[52:55], v[154:157], v[194:197], v[52:55]
	v_mfma_f32_16x16x32_bf16 v[48:51], v[162:165], v[194:197], v[48:51]
	v_mfma_f32_16x16x32_bf16 v[44:47], v[154:157], v[202:205], v[44:47]
	v_mfma_f32_16x16x32_bf16 v[40:43], v[162:165], v[202:205], v[40:43]
	v_mfma_f32_16x16x32_bf16 v[32:35], v[154:157], v[210:213], v[32:35]
	v_mfma_f32_16x16x32_bf16 v[24:27], v[162:165], v[210:213], v[24:27]
	s_setprio 0
	s_setprio 1
	v_mfma_f32_16x16x32_bf16 v[36:39], v[166:169], v[182:185], v[36:39]
	v_mfma_f32_16x16x32_bf16 v[28:31], v[174:177], v[182:185], v[28:31]
	v_mfma_f32_16x16x32_bf16 v[20:23], v[166:169], v[190:193], v[20:23]
	v_mfma_f32_16x16x32_bf16 v[16:19], v[174:177], v[190:193], v[16:19]
	v_mfma_f32_16x16x32_bf16 v[12:15], v[166:169], v[198:201], v[12:15]
	v_mfma_f32_16x16x32_bf16 v[8:11], v[174:177], v[198:201], v[8:11]
	v_mfma_f32_16x16x32_bf16 v[4:7], v[166:169], v[206:209], v[4:7]
	v_mfma_f32_16x16x32_bf16 v[0:3], v[174:177], v[206:209], v[0:3]
	v_mfma_f32_16x16x32_bf16 v[36:39], v[170:173], v[186:189], v[36:39]
	v_mfma_f32_16x16x32_bf16 v[28:31], v[178:181], v[186:189], v[28:31]
	v_mfma_f32_16x16x32_bf16 v[20:23], v[170:173], v[194:197], v[20:23]
	v_mfma_f32_16x16x32_bf16 v[16:19], v[178:181], v[194:197], v[16:19]
	v_mfma_f32_16x16x32_bf16 v[12:15], v[170:173], v[202:205], v[12:15]
	v_mfma_f32_16x16x32_bf16 v[8:11], v[178:181], v[202:205], v[8:11]
	s_setprio 2
	s_barrier
	v_mfma_f32_16x16x32_bf16 v[4:7], v[170:173], v[210:213], v[4:7]
	v_mfma_f32_16x16x32_bf16 v[0:3], v[178:181], v[210:213], v[0:3]
	s_setprio 0
	s_add_i32 s28, s28, 2
	s_add_u32 s12, s12, 0x100
	s_addc_u32 s13, s13, 0
	s_cmp_gt_u32 s28, 41
	s_cbranch_scc0 .LBB0_1068
	s_cmpk_lt_u32 s18, 0x100
	s_cbranch_scc0 .LBB0_1071
	s_barrier

; #define PG8_STAGE(bufoff, gbase, voff) do { _Pragma("unroll") for (int _i = 0; _i < 2; ++_i) \
;         __builtin_amdgcn_global_load_lds((const unsigned*)((const char*)(gbase) + (voff)[_i]), (PG8_LAS unsigned*)(lds + (bufoff) + ldsw + _i * 8192), 16, 0, 0); } while (0)
; #define PG8_LDA(dst, b, h) do { _Pragma("unroll") for (int m = 0; m < 4; ++m) _Pragma("unroll") for (int k = 0; k < 2; ++k) dst[m][k] = *(const PG8_LAS bf16x8*)(lds + PG8_SA(b, h) + aoff + m * 2048 + k * 1024); } while (0)
; #define PG8_LDB(dst, b, h) do { _Pragma("unroll") for (int n = 0; n < 2; ++n) _Pragma("unroll") for (int k = 0; k < 2; ++k) dst[n][k] = *(const PG8_LAS bf16x8*)(lds + PG8_SB(b, h) + boff + n * 2048 + k * 1024); } while (0)
; #define PG8_MMA(ai, bj, At, Bt) do { __builtin_amdgcn_s_setprio(1); _Pragma("unroll") for (int m = 0; m < 4; ++m) _Pragma("unroll") for (int n = 0; n < 2; ++n) _Pragma("unroll") for (int k = 0; k < 2; ++k) \
;         acc[ai][bj][m][n] = __builtin_amdgcn_mfma_f32_16x16x32_bf16(Bt[n][k], At[m][k], acc[ai][bj][m][n], 0, 0, 0); __builtin_amdgcn_s_setprio(0); } while (0)
; #define PG8_WAIT_V(n) asm volatile("s_waitcnt vmcnt(" #n ")" ::: "memory")
; #define PG8_WAIT_L(n) asm volatile("s_waitcnt lgkmcnt(" #n ")" ::: "memory")
; #define PG8_BAR __builtin_amdgcn_s_barrier()
; #define PG8_SCHED __builtin_amdgcn_sched_barrier(0)
; template <class Epi, class Sched, bool ALIGN_EPI = false, bool SP2 = false>
; __device__ __forceinline__ void gemm_phase(PG8_LAS unsigned char* lds, const Gemm g, const Sched& S, const Epi& E) {
;     ...
;             PG8_LDB(B0, 0, 0); PG8_LDB(B1, 0, 1); PG8_SCHED; PG8_LDA(At, 0, 0); PG8_STAGE(PG8_SA(1, 1), a1 + hstep, voffA);
;             PG8_WAIT_V(8); PG8_WAIT_L(0); PG8_BAR; PG8_MMA(0, 0, At, B0); PG8_MMA(0, 1, At, B1); PG8_BAR; PG8_SCHED;
;             PG8_LDA(At, 0, 1); PG8_STAGE(PG8_SB(0, 0), b2, voffB); PG8_STAGE(PG8_SB(0, 1), b2 + hstep, voffB); PG8_STAGE(PG8_SA(0, 0), a2, voffA);
;             PG8_WAIT_V(8); PG8_WAIT_L(0); PG8_BAR; PG8_MMA(1, 0, At, B0); PG8_MMA(1, 1, At, B1); PG8_BAR; PG8_SCHED;
.LBB0_1260:
	ds_read_b128 v[146:149], v129
	ds_read_b128 v[158:161], v129 offset:1024
	ds_read_b128 v[162:165], v129 offset:2048
	ds_read_b128 v[166:169], v129 offset:3072
	ds_read_b128 v[170:173], v155
	ds_read_b128 v[174:177], v155 offset:1024
	ds_read_b128 v[178:181], v155 offset:2048
	ds_read_b128 v[182:185], v155 offset:3072
	s_add_u32 s34, s30, 0xfff80080
	s_addc_u32 s35, s31, -1
	s_cmp_eq_u32 s57, 28
	s_cselect_b32 s37, s23, s35
	s_cselect_b32 s36, s53, s34
	s_cselect_b32 s35, s21, s56
	s_cselect_b32 s34, s54, s55
	v_lshl_add_u64 v[150:151], s[30:31], 0, v[138:139]
	s_add_i32 m0, s29, 0xc000
	ds_read_b128 v[186:189], v156
	ds_read_b128 v[190:193], v156 offset:1024
	ds_read_b128 v[194:197], v156 offset:2048
	ds_read_b128 v[198:201], v156 offset:3072
	ds_read_b128 v[202:205], v156 offset:4096
	ds_read_b128 v[206:209], v156 offset:5120
	ds_read_b128 v[210:213], v156 offset:6144
	ds_read_b128 v[214:217], v156 offset:7168
	global_load_lds_dwordx4 v[150:151], off
	v_lshl_add_u64 v[150:151], s[30:31], 0, v[140:141]
	s_add_i32 m0, s29, 0xe000
	s_nop 0
	global_load_lds_dwordx4 v[150:151], off
	s_waitcnt vmcnt(8)
	s_waitcnt lgkmcnt(0)
	s_barrier
	s_setprio 1
	s_waitcnt lgkmcnt(0)
	v_mfma_f32_16x16x32_bf16 v[124:127], v[146:149], v[186:189], v[124:127]
	v_mfma_f32_16x16x32_bf16 v[120:123], v[162:165], v[186:189], v[120:123]
	v_mfma_f32_16x16x32_bf16 v[108:111], v[146:149], v[194:197], v[108:111]
	v_mfma_f32_16x16x32_bf16 v[104:107], v[162:165], v[194:197], v[104:107]
	v_mfma_f32_16x16x32_bf16 v[92:95], v[146:149], v[202:205], v[92:95]
	v_mfma_f32_16x16x32_bf16 v[88:91], v[162:165], v[202:205], v[88:91]
	v_mfma_f32_16x16x32_bf16 v[76:79], v[146:149], v[210:213], v[76:79]
	v_mfma_f32_16x16x32_bf16 v[72:75], v[162:165], v[210:213], v[72:75]
	v_mfma_f32_16x16x32_bf16 v[124:127], v[158:161], v[190:193], v[124:127]
	v_mfma_f32_16x16x32_bf16 v[120:123], v[166:169], v[190:193], v[120:123]
	v_mfma_f32_16x16x32_bf16 v[108:111], v[158:161], v[198:201], v[108:111]
	v_mfma_f32_16x16x32_bf16 v[104:107], v[166:169], v[198:201], v[104:107]
	v_mfma_f32_16x16x32_bf16 v[92:95], v[158:161], v[206:209], v[92:95]
	v_mfma_f32_16x16x32_bf16 v[88:91], v[166:169], v[206:209], v[88:91]
	v_mfma_f32_16x16x32_bf16 v[76:79], v[158:161], v[214:217], v[76:79]
	v_mfma_f32_16x16x32_bf16 v[72:75], v[166:169], v[214:217], v[72:75]
	s_setprio 0
	s_setprio 1
	v_mfma_f32_16x16x32_bf16 v[116:119], v[170:173], v[186:189], v[116:119]
	v_mfma_f32_16x16x32_bf16 v[112:115], v[178:181], v[186:189], v[112:115]
	v_mfma_f32_16x16x32_bf16 v[100:103], v[170:173], v[194:197], v[100:103]
	v_mfma_f32_16x16x32_bf16 v[96:99], v[178:181], v[194:197], v[96:99]
	v_mfma_f32_16x16x32_bf16 v[84:87], v[170:173], v[202:205], v[84:87]
	v_mfma_f32_16x16x32_bf16 v[80:83], v[178:181], v[202:205], v[80:83]
	v_mfma_f32_16x16x32_bf16 v[68:71], v[170:173], v[210:213], v[68:71]
	v_mfma_f32_16x16x32_bf16 v[64:67], v[178:181], v[210:213], v[64:67]
	v_mfma_f32_16x16x32_bf16 v[116:119], v[174:177], v[190:193], v[116:119]
	v_mfma_f32_16x16x32_bf16 v[112:115], v[182:185], v[190:193], v[112:115]
	v_mfma_f32_16x16x32_bf16 v[100:103], v[174:177], v[198:201], v[100:103]
	v_mfma_f32_16x16x32_bf16 v[96:99], v[182:185], v[198:201], v[96:99]
	v_mfma_f32_16x16x32_bf16 v[84:87], v[174:177], v[206:209], v[84:87]
	v_mfma_f32_16x16x32_bf16 v[80:83], v[182:185], v[206:209], v[80:83]
	s_setprio 2
	s_barrier
	v_mfma_f32_16x16x32_bf16 v[68:71], v[174:177], v[214:217], v[68:71]
	v_mfma_f32_16x16x32_bf16 v[64:67], v[182:185], v[214:217], v[64:67]
	s_setprio 0
	s_add_i32 s58, s50, s33
	v_lshl_add_u64 v[150:151], s[34:35], 0, v[134:135]
	s_mov_b32 m0, s58
	ds_read_b128 v[186:189], v156 offset:16384
	ds_read_b128 v[190:193], v156 offset:17408
	ds_read_b128 v[194:197], v156 offset:18432
	ds_read_b128 v[198:201], v156 offset:19456
	ds_read_b128 v[202:205], v156 offset:20480
	ds_read_b128 v[206:209], v156 offset:21504
	ds_read_b128 v[210:213], v156 offset:22528
	ds_read_b128 v[214:217], v156 offset:23552
	global_load_lds_dwordx4 v[150:151], off
	s_add_i32 m0, s58, 0x2000
	s_add_u32 s58, s34, 0x80000
	v_lshl_add_u64 v[218:219], s[34:35], 0, v[130:131]
	s_addc_u32 s59, s35, 0
	s_add_i32 s60, s51, s33
	global_load_lds_dwordx4 v[218:219], off
	v_lshl_add_u64 v[220:221], s[58:59], 0, v[134:135]
	s_mov_b32 m0, s60
	v_lshl_add_u64 v[222:223], s[36:37], 0, v[132:133]
	global_load_lds_dwordx4 v[220:221], off
	v_lshl_add_u64 v[220:221], s[58:59], 0, v[130:131]
	s_add_i32 m0, s60, 0x2000
	s_nop 0
	global_load_lds_dwordx4 v[220:221], off
	v_lshl_add_u64 v[220:221], s[36:37], 0, v[136:137]
	s_mov_b32 m0, s29
	s_nop 0
	global_load_lds_dwordx4 v[220:221], off
	s_mov_b32 m0, s40
	s_nop 0
	global_load_lds_dwordx4 v[222:223], off
	s_waitcnt vmcnt(8)
	s_waitcnt lgkmcnt(0)
	s_barrier
; #define PG8_STAGE(bufoff, gbase, voff) do { _Pragma("unroll") for (int _i = 0; _i < 2; ++_i) \
;         __builtin_amdgcn_global_load_lds((const unsigned*)((const char*)(gbase) + (voff)[_i]), (PG8_LAS unsigned*)(lds + (bufoff) + ldsw + _i * 8192), 16, 0, 0); } while (0)
; #define PG8_LDA(dst, b, h) do { _Pragma("unroll") for (int m = 0; m < 4; ++m) _Pragma("unroll") for (int k = 0; k < 2; ++k) dst[m][k] = *(const PG8_LAS bf16x8*)(lds + PG8_SA(b, h) + aoff + m * 2048 + k * 1024); } while (0)
; #define PG8_LDB(dst, b, h) do { _Pragma("unroll") for (int n = 0; n < 2; ++n) _Pragma("unroll") for (int k = 0; k < 2; ++k) dst[n][k] = *(const PG8_LAS bf16x8*)(lds + PG8_SB(b, h) + boff + n * 2048 + k * 1024); } while (0)
; #define PG8_MMA(ai, bj, At, Bt) do { __builtin_amdgcn_s_setprio(1); _Pragma("unroll") for (int m = 0; m < 4; ++m) _Pragma("unroll") for (int n = 0; n < 2; ++n) _Pragma("unroll") for (int k = 0; k < 2; ++k) \
;         acc[ai][bj][m][n] = __builtin_amdgcn_mfma_f32_16x16x32_bf16(Bt[n][k], At[m][k], acc[ai][bj][m][n], 0, 0, 0); __builtin_amdgcn_s_setprio(0); } while (0)
; #define PG8_WAIT_V(n) asm volatile("s_waitcnt vmcnt(" #n ")" ::: "memory")
; #define PG8_WAIT_L(n) asm volatile("s_waitcnt lgkmcnt(" #n ")" ::: "memory")
; #define PG8_BAR __builtin_amdgcn_s_barrier()
; #define PG8_SCHED __builtin_amdgcn_sched_barrier(0)
; template <class Epi, class Sched, bool ALIGN_EPI = false, bool SP2 = false>
; __device__ __forceinline__ void gemm_phase(PG8_LAS unsigned char* lds, const Gemm g, const Sched& S, const Epi& E) {
;     ...
;             PG8_WAIT_V(8); PG8_WAIT_L(0); PG8_BAR; PG8_MMA(1, 0, At, B0); PG8_MMA(1, 1, At, B1); PG8_BAR; PG8_SCHED;
;             PG8_LDB(B0, 1, 0); PG8_LDB(B1, 1, 1); PG8_SCHED; PG8_LDA(At, 1, 0); PG8_STAGE(PG8_SA(0, 1), a2 + hstep, voffA);
;             PG8_WAIT_V(8); PG8_WAIT_L(0); PG8_BAR; PG8_MMA(0, 0, At, B0); PG8_MMA(0, 1, At, B1); PG8_BAR; PG8_SCHED;
	s_setprio 1
	s_waitcnt lgkmcnt(0)
	v_mfma_f32_16x16x32_bf16 v[60:63], v[146:149], v[186:189], v[60:63]
	v_mfma_f32_16x16x32_bf16 v[56:59], v[162:165], v[186:189], v[56:59]
	v_mfma_f32_16x16x32_bf16 v[44:47], v[146:149], v[194:197], v[44:47]
	v_mfma_f32_16x16x32_bf16 v[40:43], v[162:165], v[194:197], v[40:43]
	v_mfma_f32_16x16x32_bf16 v[28:31], v[146:149], v[202:205], v[28:31]
	v_mfma_f32_16x16x32_bf16 v[24:27], v[162:165], v[202:205], v[24:27]
	v_mfma_f32_16x16x32_bf16 v[12:15], v[146:149], v[210:213], v[12:15]
	v_mfma_f32_16x16x32_bf16 v[8:11], v[162:165], v[210:213], v[8:11]
	v_mfma_f32_16x16x32_bf16 v[60:63], v[158:161], v[190:193], v[60:63]
	v_mfma_f32_16x16x32_bf16 v[56:59], v[166:169], v[190:193], v[56:59]
	v_mfma_f32_16x16x32_bf16 v[44:47], v[158:161], v[198:201], v[44:47]
	v_mfma_f32_16x16x32_bf16 v[40:43], v[166:169], v[198:201], v[40:43]
	v_mfma_f32_16x16x32_bf16 v[28:31], v[158:161], v[206:209], v[28:31]
	v_mfma_f32_16x16x32_bf16 v[24:27], v[166:169], v[206:209], v[24:27]
	v_mfma_f32_16x16x32_bf16 v[12:15], v[158:161], v[214:217], v[12:15]
	v_mfma_f32_16x16x32_bf16 v[8:11], v[166:169], v[214:217], v[8:11]
	s_setprio 0
	s_setprio 1
	v_mfma_f32_16x16x32_bf16 v[52:55], v[170:173], v[186:189], v[52:55]
	v_mfma_f32_16x16x32_bf16 v[48:51], v[178:181], v[186:189], v[48:51]
	v_mfma_f32_16x16x32_bf16 v[36:39], v[170:173], v[194:197], v[36:39]
	v_mfma_f32_16x16x32_bf16 v[32:35], v[178:181], v[194:197], v[32:35]
	v_mfma_f32_16x16x32_bf16 v[20:23], v[170:173], v[202:205], v[20:23]
	v_mfma_f32_16x16x32_bf16 v[16:19], v[178:181], v[202:205], v[16:19]
	v_mfma_f32_16x16x32_bf16 v[4:7], v[170:173], v[210:213], v[4:7]
	v_mfma_f32_16x16x32_bf16 v[0:3], v[178:181], v[210:213], v[0:3]
	v_mfma_f32_16x16x32_bf16 v[52:55], v[174:177], v[190:193], v[52:55]
	v_mfma_f32_16x16x32_bf16 v[48:51], v[182:185], v[190:193], v[48:51]
	v_mfma_f32_16x16x32_bf16 v[36:39], v[174:177], v[198:201], v[36:39]
	v_mfma_f32_16x16x32_bf16 v[32:35], v[182:185], v[198:201], v[32:35]
	v_mfma_f32_16x16x32_bf16 v[20:23], v[174:177], v[206:209], v[20:23]
	v_mfma_f32_16x16x32_bf16 v[16:19], v[182:185], v[206:209], v[16:19]
	s_setprio 2
	s_barrier
	v_mfma_f32_16x16x32_bf16 v[4:7], v[174:177], v[214:217], v[4:7]
	v_mfma_f32_16x16x32_bf16 v[0:3], v[182:185], v[214:217], v[0:3]
	s_setprio 0
	s_add_i32 s58, 0, 0x18000
	v_add_u32_e32 v157, s58, v153
	s_add_i32 s59, 0, 0x1c000
	ds_read_b128 v[146:149], v157
	ds_read_b128 v[158:161], v157 offset:1024
	ds_read_b128 v[162:165], v157 offset:2048
	ds_read_b128 v[166:169], v157 offset:3072
	v_add_u32_e32 v157, s59, v153
	ds_read_b128 v[170:173], v157
	ds_read_b128 v[174:177], v157 offset:1024
	ds_read_b128 v[178:181], v157 offset:2048
	ds_read_b128 v[182:185], v157 offset:3072
	s_add_u32 s36, s36, 0x80000
	s_addc_u32 s37, s37, 0
	s_mov_b32 m0, s41
	v_lshl_add_u64 v[224:225], s[36:37], 0, v[136:137]
	ds_read_b128 v[186:189], v156 offset:32768
	ds_read_b128 v[190:193], v156 offset:33792
	ds_read_b128 v[194:197], v156 offset:34816
	ds_read_b128 v[198:201], v156 offset:35840
	ds_read_b128 v[202:205], v156 offset:36864
	ds_read_b128 v[206:209], v156 offset:37888
	ds_read_b128 v[210:213], v156 offset:38912
	ds_read_b128 v[214:217], v156 offset:39936
	global_load_lds_dwordx4 v[224:225], off
	v_lshl_add_u64 v[224:225], s[36:37], 0, v[132:133]
	s_mov_b32 m0, s42
	s_nop 0
	global_load_lds_dwordx4 v[224:225], off
	s_waitcnt vmcnt(8)
	s_waitcnt lgkmcnt(0)
	s_barrier
	s_setprio 1
	s_waitcnt lgkmcnt(0)
	v_mfma_f32_16x16x32_bf16 v[124:127], v[146:149], v[186:189], v[124:127]
	v_mfma_f32_16x16x32_bf16 v[120:123], v[162:165], v[186:189], v[120:123]
	v_mfma_f32_16x16x32_bf16 v[108:111], v[146:149], v[194:197], v[108:111]
	v_mfma_f32_16x16x32_bf16 v[104:107], v[162:165], v[194:197], v[104:107]
	v_mfma_f32_16x16x32_bf16 v[92:95], v[146:149], v[202:205], v[92:95]
	v_mfma_f32_16x16x32_bf16 v[88:91], v[162:165], v[202:205], v[88:91]
	v_mfma_f32_16x16x32_bf16 v[76:79], v[146:149], v[210:213], v[76:79]
	v_mfma_f32_16x16x32_bf16 v[72:75], v[162:165], v[210:213], v[72:75]
	v_mfma_f32_16x16x32_bf16 v[124:127], v[158:161], v[190:193], v[124:127]
	v_mfma_f32_16x16x32_bf16 v[120:123], v[166:169], v[190:193], v[120:123]
	v_mfma_f32_16x16x32_bf16 v[108:111], v[158:161], v[198:201], v[108:111]
	v_mfma_f32_16x16x32_bf16 v[104:107], v[166:169], v[198:201], v[104:107]
	v_mfma_f32_16x16x32_bf16 v[92:95], v[158:161], v[206:209], v[92:95]
	v_mfma_f32_16x16x32_bf16 v[88:91], v[166:169], v[206:209], v[88:91]
	v_mfma_f32_16x16x32_bf16 v[76:79], v[158:161], v[214:217], v[76:79]
	v_mfma_f32_16x16x32_bf16 v[72:75], v[166:169], v[214:217], v[72:75]
	s_setprio 0
	s_setprio 1
	v_mfma_f32_16x16x32_bf16 v[116:119], v[170:173], v[186:189], v[116:119]
	v_mfma_f32_16x16x32_bf16 v[112:115], v[178:181], v[186:189], v[112:115]
	v_mfma_f32_16x16x32_bf16 v[100:103], v[170:173], v[194:197], v[100:103]
	v_mfma_f32_16x16x32_bf16 v[96:99], v[178:181], v[194:197], v[96:99]
	v_mfma_f32_16x16x32_bf16 v[84:87], v[170:173], v[202:205], v[84:87]
	v_mfma_f32_16x16x32_bf16 v[80:83], v[178:181], v[202:205], v[80:83]
	v_mfma_f32_16x16x32_bf16 v[68:71], v[170:173], v[210:213], v[68:71]
	v_mfma_f32_16x16x32_bf16 v[64:67], v[178:181], v[210:213], v[64:67]
	v_mfma_f32_16x16x32_bf16 v[116:119], v[174:177], v[190:193], v[116:119]
	v_mfma_f32_16x16x32_bf16 v[112:115], v[182:185], v[190:193], v[112:115]
	v_mfma_f32_16x16x32_bf16 v[100:103], v[174:177], v[198:201], v[100:103]
	v_mfma_f32_16x16x32_bf16 v[96:99], v[182:185], v[198:201], v[96:99]
	v_mfma_f32_16x16x32_bf16 v[84:87], v[174:177], v[206:209], v[84:87]
	v_mfma_f32_16x16x32_bf16 v[80:83], v[182:185], v[206:209], v[80:83]
	s_setprio 2
	s_barrier
; #define PG8_STAGE(bufoff, gbase, voff) do { _Pragma("unroll") for (int _i = 0; _i < 2; ++_i) \
;         __builtin_amdgcn_global_load_lds((const unsigned*)((const char*)(gbase) + (voff)[_i]), (PG8_LAS unsigned*)(lds + (bufoff) + ldsw + _i * 8192), 16, 0, 0); } while (0)
; #define PG8_LDA(dst, b, h) do { _Pragma("unroll") for (int m = 0; m < 4; ++m) _Pragma("unroll") for (int k = 0; k < 2; ++k) dst[m][k] = *(const PG8_LAS bf16x8*)(lds + PG8_SA(b, h) + aoff + m * 2048 + k * 1024); } while (0)
; #define PG8_MMA(ai, bj, At, Bt) do { __builtin_amdgcn_s_setprio(1); _Pragma("unroll") for (int m = 0; m < 4; ++m) _Pragma("unroll") for (int n = 0; n < 2; ++n) _Pragma("unroll") for (int k = 0; k < 2; ++k) \
;         acc[ai][bj][m][n] = __builtin_amdgcn_mfma_f32_16x16x32_bf16(Bt[n][k], At[m][k], acc[ai][bj][m][n], 0, 0, 0); __builtin_amdgcn_s_setprio(0); } while (0)
; #define PG8_WAIT_V(n) asm volatile("s_waitcnt vmcnt(" #n ")" ::: "memory")
; #define PG8_WAIT_L(n) asm volatile("s_waitcnt lgkmcnt(" #n ")" ::: "memory")
; #define PG8_BAR __builtin_amdgcn_s_barrier()
; #define PG8_SCHED __builtin_amdgcn_sched_barrier(0)
; template <class Epi, class Sched, bool ALIGN_EPI = false, bool SP2 = false>
; __device__ __forceinline__ void gemm_phase(PG8_LAS unsigned char* lds, const Gemm g, const Sched& S, const Epi& E) {
;     ...
;             PG8_LDA(At, 1, 1); PG8_STAGE(PG8_SB(1, 0), b3, voffB); PG8_STAGE(PG8_SB(1, 1), b3 + hstep, voffB); PG8_STAGE(PG8_SA(1, 0), a3, voffA);
;             PG8_WAIT_V(8); PG8_WAIT_L(0); PG8_BAR; PG8_MMA(1, 0, At, B0); PG8_MMA(1, 1, At, B1); PG8_BAR; PG8_SCHED;
;     ...
;         if constexpr (ALIGN_EPI) { if (wr == 0) PG8_BAR; }
	v_mfma_f32_16x16x32_bf16 v[68:71], v[174:177], v[214:217], v[68:71]
	v_mfma_f32_16x16x32_bf16 v[64:67], v[182:185], v[214:217], v[64:67]
	s_setprio 0
	s_add_i32 s36, s58, s33
	v_lshl_add_u64 v[150:151], v[150:151], 0, s[10:11]
	s_mov_b32 m0, s36
	ds_read_b128 v[186:189], v156 offset:49152
	ds_read_b128 v[190:193], v156 offset:50176
	ds_read_b128 v[194:197], v156 offset:51200
	ds_read_b128 v[198:201], v156 offset:52224
	ds_read_b128 v[202:205], v156 offset:53248
	ds_read_b128 v[206:209], v156 offset:54272
	ds_read_b128 v[210:213], v156 offset:55296
	ds_read_b128 v[214:217], v156 offset:56320
	global_load_lds_dwordx4 v[150:151], off
	s_add_i32 m0, s36, 0x2000
	s_add_u32 s34, s34, 0x80080
	v_lshl_add_u64 v[150:151], v[218:219], 0, s[10:11]
	s_addc_u32 s35, s35, 0
	s_add_i32 s36, s59, s33
	global_load_lds_dwordx4 v[150:151], off
	v_lshl_add_u64 v[150:151], s[34:35], 0, v[134:135]
	s_mov_b32 m0, s36
	s_nop 0
	global_load_lds_dwordx4 v[150:151], off
	v_lshl_add_u64 v[150:151], s[34:35], 0, v[130:131]
	s_add_i32 m0, s36, 0x2000
	s_nop 0
	global_load_lds_dwordx4 v[150:151], off
	v_lshl_add_u64 v[150:151], v[220:221], 0, s[10:11]
	s_mov_b32 m0, s44
	s_nop 0
	global_load_lds_dwordx4 v[150:151], off
	v_lshl_add_u64 v[150:151], v[222:223], 0, s[10:11]
	s_mov_b32 m0, s45
	s_nop 0
	global_load_lds_dwordx4 v[150:151], off
	s_waitcnt vmcnt(8)
	s_waitcnt lgkmcnt(0)
	s_barrier
	s_setprio 1
	s_waitcnt lgkmcnt(0)
	v_mfma_f32_16x16x32_bf16 v[60:63], v[146:149], v[186:189], v[60:63]
	v_mfma_f32_16x16x32_bf16 v[56:59], v[162:165], v[186:189], v[56:59]
	v_mfma_f32_16x16x32_bf16 v[44:47], v[146:149], v[194:197], v[44:47]
	v_mfma_f32_16x16x32_bf16 v[40:43], v[162:165], v[194:197], v[40:43]
	v_mfma_f32_16x16x32_bf16 v[28:31], v[146:149], v[202:205], v[28:31]
	v_mfma_f32_16x16x32_bf16 v[24:27], v[162:165], v[202:205], v[24:27]
	v_mfma_f32_16x16x32_bf16 v[12:15], v[146:149], v[210:213], v[12:15]
	v_mfma_f32_16x16x32_bf16 v[8:11], v[162:165], v[210:213], v[8:11]
	v_mfma_f32_16x16x32_bf16 v[60:63], v[158:161], v[190:193], v[60:63]
	v_mfma_f32_16x16x32_bf16 v[56:59], v[166:169], v[190:193], v[56:59]
	v_mfma_f32_16x16x32_bf16 v[44:47], v[158:161], v[198:201], v[44:47]
	v_mfma_f32_16x16x32_bf16 v[40:43], v[166:169], v[198:201], v[40:43]
	v_mfma_f32_16x16x32_bf16 v[28:31], v[158:161], v[206:209], v[28:31]
	v_mfma_f32_16x16x32_bf16 v[24:27], v[166:169], v[206:209], v[24:27]
	v_mfma_f32_16x16x32_bf16 v[12:15], v[158:161], v[214:217], v[12:15]
	v_mfma_f32_16x16x32_bf16 v[8:11], v[166:169], v[214:217], v[8:11]
	s_setprio 0
	s_setprio 1
	v_mfma_f32_16x16x32_bf16 v[52:55], v[170:173], v[186:189], v[52:55]
	v_mfma_f32_16x16x32_bf16 v[48:51], v[178:181], v[186:189], v[48:51]
	v_mfma_f32_16x16x32_bf16 v[36:39], v[170:173], v[194:197], v[36:39]
	v_mfma_f32_16x16x32_bf16 v[32:35], v[178:181], v[194:197], v[32:35]
	v_mfma_f32_16x16x32_bf16 v[20:23], v[170:173], v[202:205], v[20:23]
	v_mfma_f32_16x16x32_bf16 v[16:19], v[178:181], v[202:205], v[16:19]
	v_mfma_f32_16x16x32_bf16 v[4:7], v[170:173], v[210:213], v[4:7]
	v_mfma_f32_16x16x32_bf16 v[0:3], v[178:181], v[210:213], v[0:3]
	v_mfma_f32_16x16x32_bf16 v[52:55], v[174:177], v[190:193], v[52:55]
	v_mfma_f32_16x16x32_bf16 v[48:51], v[182:185], v[190:193], v[48:51]
	v_mfma_f32_16x16x32_bf16 v[36:39], v[174:177], v[198:201], v[36:39]
	v_mfma_f32_16x16x32_bf16 v[32:35], v[182:185], v[198:201], v[32:35]
	v_mfma_f32_16x16x32_bf16 v[20:23], v[174:177], v[206:209], v[20:23]
	v_mfma_f32_16x16x32_bf16 v[16:19], v[182:185], v[206:209], v[16:19]
	s_setprio 2
	s_barrier
	v_mfma_f32_16x16x32_bf16 v[4:7], v[174:177], v[214:217], v[4:7]
	v_mfma_f32_16x16x32_bf16 v[0:3], v[182:185], v[214:217], v[0:3]
	s_setprio 0
	s_add_i32 s57, s57, 2
	s_add_u32 s30, s30, 0x100
	s_addc_u32 s31, s31, 0
	s_add_u32 s55, s55, 0x100
	s_addc_u32 s56, s56, 0
	s_cmp_gt_u32 s57, 29
	s_cbranch_scc0 .LBB0_1260
	s_and_b64 vcc, exec, s[12:13]
	s_cbranch_vccz .LBB0_1263
	s_barrier
